# hyena: software-pipelined LDS reads (window 12) in inverse FFT passes i2 and i1x2 + nop removal
# baseline (speedup 1.0000x reference)
; #define LAS __attribute__((address_space(3)))
; #define SINCOSPI(x, s, c) do { const float hx_ = 0.5f * (x); *(s) = __builtin_amdgcn_sinf(hx_); *(c) = __builtin_amdgcn_cosf(hx_); } while (0)
; #define OPAQUE_I(x) asm volatile("" : "+v"(x))
; template <int R, bool INV> DEV void dft_regs(cf (&v)[R]) {
; #pragma unroll
;     for (int s = R; s >= 2; s >>= 1) {
;         const int h = s >> 1;
; #pragma unroll
;         for (int b = 0; b < R; b += s) {
; #pragma unroll
;             for (int k = 0; k < h; ++k) {
;                 const cf a = v[b + k], c = v[b + k + h];
;                 v[b + k] = a + c;
;                 const cf d = a - c;
;                 const int m = k * (32 / s);
;                 const float wr = tw_cos(m), wi = INV ? tw_sin(m) : -tw_sin(m);
;                 v[b + k + h] = cf{d.x * wr - d.y * wi, d.x * wi + d.y * wr};
;             }
;         }
;     }
; }
; DEV void fft_f1x2(LAS cf* buf0, LAS cf* buf1, const cf (&z0)[8], const cf (&z1)[8], int tid) {
;     OPAQUE_I(tid);
;     cf v[16], u[16];
; #pragma unroll
;     for (int q = 0; q < 8; ++q) { v[q] = z0[q]; v[q + 8] = cf{0.f, 0.f}; u[q] = z1[q]; u[q + 8] = cf{0.f, 0.f}; }
;     dft_regs<16, false>(v); dft_regs<16, false>(u);
;     float sn, cs; SINCOSPI(-(float)tid * (2.0f / 8192.0f), &sn, &cs);
;     const cf w = cf{cs, sn}; cf wp = cf{1.f, 0.f};
;     LAS cf* p0 = buf0 + PADI(tid); LAS cf* p1 = buf1 + PADI(tid);
; #pragma unroll
;     for (int p = 0; p < 16; ++p) { p0[544 * p] = cmul(v[BR16[p]], wp); p1[544 * p] = cmul(u[BR16[p]], wp); wp = cmul(wp, w); }
; }
.LBB0_519:
	v_pk_mul_f32 v[16:17], v[26:27], s[16:17] op_sel_hi:[1,0]
	v_pk_add_f32 v[0:1], v[24:25], 0 op_sel_hi:[1,0]
	v_pk_fma_f32 v[18:19], v[26:27], s[84:85], v[16:17] op_sel:[0,0,1] op_sel_hi:[1,0,0]
	v_pk_fma_f32 v[16:17], v[26:27], s[84:85], v[16:17] op_sel:[0,0,1] op_sel_hi:[1,0,0] neg_lo:[0,0,1] neg_hi:[0,0,1]
	v_pk_mul_f32 v[2:3], v[24:25], 0 op_sel_hi:[1,0]
	v_mov_b32_e32 v19, v17
	v_pk_add_f32 v[16:17], v[22:23], 0 op_sel_hi:[1,0]
	v_pk_add_f32 v[4:5], v[24:25], v[2:3] op_sel:[0,1] op_sel_hi:[1,0] neg_lo:[0,1] neg_hi:[0,1]
	v_pk_add_f32 v[80:81], v[0:1], v[16:17]
	v_pk_add_f32 v[0:1], v[0:1], v[16:17] neg_lo:[0,1] neg_hi:[0,1]
	v_pk_add_f32 v[2:3], v[24:25], v[2:3] op_sel:[0,1] op_sel_hi:[1,0]
	v_pk_fma_f32 v[66:67], v[22:23], 0, v[22:23] op_sel:[0,0,1] op_sel_hi:[1,0,0]
	v_pk_fma_f32 v[68:69], v[22:23], 0, v[22:23] op_sel:[0,0,1] op_sel_hi:[1,0,0] neg_lo:[0,0,1] neg_hi:[0,0,1]
	v_pk_mul_f32 v[16:17], v[0:1], 0 op_sel_hi:[1,0]
	v_mov_b32_e32 v5, v3
	v_pk_add_f32 v[2:3], v[30:31], 0 op_sel_hi:[1,0]
	v_pk_mul_f32 v[6:7], v[30:31], s[84:85] op_sel_hi:[1,0]
	v_mov_b32_e32 v67, v69
	v_pk_add_f32 v[68:69], v[32:33], 0 op_sel_hi:[1,0]
	v_pk_add_f32 v[82:83], v[0:1], v[16:17] op_sel:[0,1] op_sel_hi:[1,0] neg_lo:[0,1] neg_hi:[0,1]
	v_pk_add_f32 v[0:1], v[0:1], v[16:17] op_sel:[0,1] op_sel_hi:[1,0]
	v_pk_fma_f32 v[8:9], v[30:31], s[16:17], v[6:7] op_sel:[0,0,1] op_sel_hi:[1,0,0]
	v_pk_fma_f32 v[6:7], v[30:31], s[16:17], v[6:7] op_sel:[0,0,1] op_sel_hi:[1,0,0] neg_lo:[0,0,1] neg_hi:[0,0,1]
	v_mov_b32_e32 v83, v1
	v_pk_add_f32 v[0:1], v[2:3], v[68:69]
	v_pk_add_f32 v[2:3], v[2:3], v[68:69] neg_lo:[0,1] neg_hi:[0,1]
	v_mov_b32_e32 v9, v7
	v_pk_add_f32 v[6:7], v[28:29], 0 op_sel_hi:[1,0]
	v_pk_add_f32 v[72:73], v[34:35], 0 op_sel_hi:[1,0]
	v_pk_mul_f32 v[16:17], v[2:3], s[18:19] op_sel_hi:[1,0]
	v_pk_mul_f32 v[10:11], v[28:29], s[18:19] op_sel_hi:[1,0]
	v_pk_fma_f32 v[68:69], v[2:3], s[18:19], v[16:17] op_sel:[0,0,1] op_sel_hi:[1,0,0]
	v_pk_fma_f32 v[2:3], v[2:3], s[18:19], v[16:17] op_sel_hi:[1,0,0] neg_lo:[0,0,1] neg_hi:[0,0,1]
	v_pk_add_f32 v[16:17], v[6:7], v[72:73]
	v_pk_add_f32 v[6:7], v[6:7], v[72:73] neg_lo:[0,1] neg_hi:[0,1]
	v_pk_add_f32 v[14:15], v[26:27], 0 op_sel_hi:[1,0]
	v_pk_add_f32 v[76:77], v[36:37], 0 op_sel_hi:[1,0]
	v_pk_fma_f32 v[72:73], v[6:7], 0, v[6:7] op_sel:[0,0,1] op_sel_hi:[1,0,0]
	v_pk_fma_f32 v[6:7], v[6:7], 0, v[6:7] op_sel:[0,0,1] op_sel_hi:[1,0,0] neg_lo:[0,0,1] neg_hi:[0,0,1]
	v_pk_fma_f32 v[12:13], v[28:29], s[18:19], v[10:11] op_sel:[0,0,1] op_sel_hi:[1,0,0]
	v_pk_fma_f32 v[10:11], v[28:29], s[18:19], v[10:11] op_sel_hi:[1,0,0] neg_lo:[0,0,1] neg_hi:[0,0,1]
	v_mov_b32_e32 v73, v7
	v_pk_add_f32 v[6:7], v[14:15], v[76:77]
	v_pk_add_f32 v[14:15], v[14:15], v[76:77] neg_lo:[0,1] neg_hi:[0,1]
	v_pk_add_f32 v[76:77], v[4:5], v[66:67]
	v_pk_add_f32 v[4:5], v[4:5], v[66:67] neg_lo:[0,1] neg_hi:[0,1]
	v_mov_b32_e32 v10, v33
	s_mov_b32 s30, s85
	s_mov_b32 s31, s0
	v_pk_mul_f32 v[70:71], v[32:33], s[84:85] op_sel_hi:[0,1]
	v_pk_mul_f32 v[66:67], v[4:5], 0 op_sel_hi:[1,0]
	v_pk_fma_f32 v[70:71], v[10:11], s[30:31], v[70:71] op_sel_hi:[0,1,1] neg_lo:[0,0,1] neg_hi:[0,0,1]
	v_pk_add_f32 v[84:85], v[4:5], v[66:67] op_sel:[0,1] op_sel_hi:[1,0] neg_lo:[0,1] neg_hi:[0,1]
	v_pk_add_f32 v[4:5], v[4:5], v[66:67] op_sel:[0,1] op_sel_hi:[1,0]
	v_mul_f32_e32 v10, 0x3f3504f3, v34
	v_mov_b32_e32 v74, v35
	s_mov_b32 s28, s97
	s_mov_b32 s29, s96
	s_mov_b32 s24, s85
	s_mov_b32 s25, s84
	v_mov_b32_e32 v85, v5
	v_pk_add_f32 v[4:5], v[8:9], v[70:71]
	v_pk_add_f32 v[8:9], v[8:9], v[70:71] neg_lo:[0,1] neg_hi:[0,1]
	v_pk_fma_f32 v[74:75], v[74:75], s[28:29], v[10:11] op_sel_hi:[0,1,0] neg_lo:[0,0,1] neg_hi:[0,0,1]
	v_mov_b32_e32 v10, v37
	s_mov_b32 s34, s84
	s_mov_b32 s35, s88
	v_pk_mul_f32 v[78:79], v[36:37], s[24:25] op_sel_hi:[0,1]
	v_pk_mul_f32 v[66:67], v[8:9], s[18:19] op_sel_hi:[1,0]
	v_mov_b32_e32 v13, v11
	v_pk_fma_f32 v[78:79], v[10:11], s[34:35], v[78:79] op_sel_hi:[0,1,1] neg_lo:[0,0,1] neg_hi:[0,0,1]
	v_pk_fma_f32 v[70:71], v[8:9], s[18:19], v[66:67] op_sel:[0,0,1] op_sel_hi:[1,0,0]
	v_pk_fma_f32 v[8:9], v[8:9], s[18:19], v[66:67] op_sel_hi:[1,0,0] neg_lo:[0,0,1] neg_hi:[0,0,1]
	v_pk_add_f32 v[10:11], v[12:13], v[74:75] neg_lo:[0,1] neg_hi:[0,1]
	v_pk_add_f32 v[66:67], v[80:81], v[16:17]
	v_pk_add_f32 v[16:17], v[80:81], v[16:17] neg_lo:[0,1] neg_hi:[0,1]
	v_mov_b32_e32 v71, v9
	v_pk_add_f32 v[8:9], v[12:13], v[74:75]
	v_pk_fma_f32 v[12:13], v[10:11], 0, v[10:11] op_sel:[0,0,1] op_sel_hi:[1,0,0]
	v_pk_fma_f32 v[10:11], v[10:11], 0, v[10:11] op_sel:[0,0,1] op_sel_hi:[1,0,0] neg_lo:[0,0,1] neg_hi:[0,0,1]
	v_pk_mul_f32 v[74:75], v[16:17], 0 op_sel_hi:[1,0]
	v_mov_b32_e32 v13, v11
	v_pk_add_f32 v[10:11], v[18:19], v[78:79]
	v_pk_add_f32 v[18:19], v[18:19], v[78:79] neg_lo:[0,1] neg_hi:[0,1]
	v_pk_add_f32 v[78:79], v[16:17], v[74:75] op_sel:[0,1] op_sel_hi:[1,0] neg_lo:[0,1] neg_hi:[0,1]
	v_pk_add_f32 v[16:17], v[16:17], v[74:75] op_sel:[0,1] op_sel_hi:[1,0]
	v_mul_f32_e32 v2, 0x3f3504f3, v14
	v_mov_b32_e32 v79, v17
	v_pk_add_f32 v[16:17], v[0:1], v[6:7]
	v_pk_add_f32 v[0:1], v[0:1], v[6:7] neg_lo:[0,1] neg_hi:[0,1]
	v_pk_add_f32 v[74:75], v[82:83], v[72:73]
	v_pk_fma_f32 v[6:7], v[0:1], 0, v[0:1] op_sel:[0,0,1] op_sel_hi:[1,0,0]
	v_pk_fma_f32 v[0:1], v[0:1], 0, v[0:1] op_sel:[0,0,1] op_sel_hi:[1,0,0] neg_lo:[0,0,1] neg_hi:[0,0,1]
	v_pk_fma_f32 v[14:15], v[14:15], s[28:29], v[2:3] op_sel:[1,0,0] op_sel_hi:[1,1,0] neg_lo:[0,0,1] neg_hi:[0,0,1]
	v_mov_b32_e32 v7, v1
	v_pk_add_f32 v[0:1], v[82:83], v[72:73] neg_lo:[0,1] neg_hi:[0,1]
	v_mov_b32_e32 v69, v3
	v_pk_mul_f32 v[72:73], v[0:1], 0 op_sel_hi:[1,0]
	v_mul_f32_e32 v2, 0x3f3504f3, v18
; template <int R, bool INV> DEV void dft_regs(cf (&v)[R]) {
; #pragma unroll
;     for (int s = R; s >= 2; s >>= 1) {
;         const int h = s >> 1;
; #pragma unroll
;         for (int b = 0; b < R; b += s) {
; #pragma unroll
;             for (int k = 0; k < h; ++k) {
;                 const cf a = v[b + k], c = v[b + k + h];
;                 v[b + k] = a + c;
;                 const cf d = a - c;
;                 const int m = k * (32 / s);
;                 const float wr = tw_cos(m), wi = INV ? tw_sin(m) : -tw_sin(m);
;                 v[b + k + h] = cf{d.x * wr - d.y * wi, d.x * wi + d.y * wr};
;             }
;         }
;     }
; }
	v_pk_add_f32 v[80:81], v[0:1], v[72:73] op_sel:[0,1] op_sel_hi:[1,0] neg_lo:[0,1] neg_hi:[0,1]
	v_pk_add_f32 v[0:1], v[0:1], v[72:73] op_sel:[0,1] op_sel_hi:[1,0]
	v_pk_fma_f32 v[18:19], v[18:19], s[28:29], v[2:3] op_sel:[1,0,0] op_sel_hi:[1,1,0] neg_lo:[0,0,1] neg_hi:[0,0,1]
	v_mov_b32_e32 v81, v1
	v_pk_add_f32 v[0:1], v[68:69], v[14:15] neg_lo:[0,1] neg_hi:[0,1]
	v_pk_add_f32 v[2:3], v[68:69], v[14:15]
	v_pk_fma_f32 v[14:15], v[0:1], 0, v[0:1] op_sel:[0,0,1] op_sel_hi:[1,0,0]
	v_pk_fma_f32 v[0:1], v[0:1], 0, v[0:1] op_sel:[0,0,1] op_sel_hi:[1,0,0] neg_lo:[0,0,1] neg_hi:[0,0,1]
	v_pk_add_f32 v[72:73], v[76:77], v[8:9]
	v_mov_b32_e32 v15, v1
	v_pk_add_f32 v[0:1], v[76:77], v[8:9] neg_lo:[0,1] neg_hi:[0,1]
	v_pk_add_f32 v[86:87], v[84:85], v[12:13]
	v_pk_mul_f32 v[8:9], v[0:1], 0 op_sel_hi:[1,0]
	v_pk_add_f32 v[68:69], v[66:67], v[16:17]
	v_pk_add_f32 v[82:83], v[0:1], v[8:9] op_sel:[0,1] op_sel_hi:[1,0] neg_lo:[0,1] neg_hi:[0,1]
	v_pk_add_f32 v[0:1], v[0:1], v[8:9] op_sel:[0,1] op_sel_hi:[1,0]
	v_pk_add_f32 v[8:9], v[4:5], v[10:11]
	v_mov_b32_e32 v83, v1
	v_pk_add_f32 v[0:1], v[4:5], v[10:11] neg_lo:[0,1] neg_hi:[0,1]
	v_pk_add_f32 v[88:89], v[70:71], v[18:19]
	v_pk_fma_f32 v[10:11], v[0:1], 0, v[0:1] op_sel:[0,0,1] op_sel_hi:[1,0,0]
	v_pk_fma_f32 v[0:1], v[0:1], 0, v[0:1] op_sel:[0,0,1] op_sel_hi:[1,0,0] neg_lo:[0,0,1] neg_hi:[0,0,1]
	v_pk_add_f32 v[76:77], v[72:73], v[8:9]
	v_mov_b32_e32 v11, v1
	v_pk_add_f32 v[0:1], v[84:85], v[12:13] neg_lo:[0,1] neg_hi:[0,1]
	v_pk_add_f32 v[8:9], v[72:73], v[8:9] neg_lo:[0,1] neg_hi:[0,1]
	v_pk_mul_f32 v[4:5], v[0:1], 0 op_sel_hi:[1,0]
	v_pk_add_f32 v[72:73], v[82:83], v[10:11]
	v_pk_add_f32 v[84:85], v[0:1], v[4:5] op_sel:[0,1] op_sel_hi:[1,0] neg_lo:[0,1] neg_hi:[0,1]
	v_pk_add_f32 v[0:1], v[0:1], v[4:5] op_sel:[0,1] op_sel_hi:[1,0]
	v_pk_add_f32 v[10:11], v[82:83], v[10:11] neg_lo:[0,1] neg_hi:[0,1]
	v_mov_b32_e32 v85, v1
	v_pk_add_f32 v[0:1], v[70:71], v[18:19] neg_lo:[0,1] neg_hi:[0,1]
	v_pk_add_f32 v[70:71], v[74:75], v[2:3]
	v_pk_fma_f32 v[90:91], v[0:1], 0, v[0:1] op_sel:[0,0,1] op_sel_hi:[1,0,0]
	v_pk_fma_f32 v[0:1], v[0:1], 0, v[0:1] op_sel:[0,0,1] op_sel_hi:[1,0,0] neg_lo:[0,0,1] neg_hi:[0,0,1]
	v_pk_add_f32 v[2:3], v[74:75], v[2:3] neg_lo:[0,1] neg_hi:[0,1]
	v_mov_b32_e32 v91, v1
	v_pk_add_f32 v[0:1], v[66:67], v[16:17] neg_lo:[0,1] neg_hi:[0,1]
	v_pk_add_f32 v[16:17], v[78:79], v[6:7]
	v_pk_mul_f32 v[12:13], v[0:1], 0 op_sel_hi:[1,0]
	v_pk_add_f32 v[6:7], v[78:79], v[6:7] neg_lo:[0,1] neg_hi:[0,1]
	v_pk_add_f32 v[4:5], v[0:1], v[12:13] op_sel:[0,1] op_sel_hi:[1,0] neg_lo:[0,1] neg_hi:[0,1]
	v_pk_add_f32 v[0:1], v[0:1], v[12:13] op_sel:[0,1] op_sel_hi:[1,0]
	v_pk_mul_f32 v[12:13], v[6:7], 0 op_sel_hi:[1,0]
	v_mov_b32_e32 v5, v1
	v_pk_add_f32 v[0:1], v[6:7], v[12:13] op_sel:[0,1] op_sel_hi:[1,0] neg_lo:[0,1] neg_hi:[0,1]
	v_pk_add_f32 v[6:7], v[6:7], v[12:13] op_sel:[0,1] op_sel_hi:[1,0]
	v_pk_mul_f32 v[12:13], v[2:3], 0 op_sel_hi:[1,0]
	v_mov_b32_e32 v1, v7
	v_pk_add_f32 v[6:7], v[2:3], v[12:13] op_sel:[0,1] op_sel_hi:[1,0] neg_lo:[0,1] neg_hi:[0,1]
	v_pk_add_f32 v[2:3], v[2:3], v[12:13] op_sel:[0,1] op_sel_hi:[1,0]
	v_pk_add_f32 v[12:13], v[80:81], v[14:15] neg_lo:[0,1] neg_hi:[0,1]
	v_pk_add_f32 v[18:19], v[80:81], v[14:15]
	v_pk_mul_f32 v[14:15], v[12:13], 0 op_sel_hi:[1,0]
	v_mov_b32_e32 v7, v3
	v_pk_add_f32 v[2:3], v[12:13], v[14:15] op_sel:[0,1] op_sel_hi:[1,0] neg_lo:[0,1] neg_hi:[0,1]
	v_pk_add_f32 v[12:13], v[12:13], v[14:15] op_sel:[0,1] op_sel_hi:[1,0]
	v_pk_mul_f32 v[14:15], v[8:9], 0 op_sel_hi:[1,0]
	v_mov_b32_e32 v3, v13
	v_pk_add_f32 v[12:13], v[8:9], v[14:15] op_sel:[0,1] op_sel_hi:[1,0] neg_lo:[0,1] neg_hi:[0,1]
	v_pk_add_f32 v[8:9], v[8:9], v[14:15] op_sel:[0,1] op_sel_hi:[1,0]
	v_pk_mul_f32 v[14:15], v[10:11], 0 op_sel_hi:[1,0]
	v_mov_b32_e32 v13, v9
	v_pk_add_f32 v[8:9], v[10:11], v[14:15] op_sel:[0,1] op_sel_hi:[1,0] neg_lo:[0,1] neg_hi:[0,1]
	v_pk_add_f32 v[10:11], v[10:11], v[14:15] op_sel:[0,1] op_sel_hi:[1,0]
	v_pk_mul_f32 v[92:93], v[50:51], s[16:17] op_sel_hi:[1,0]
	v_mov_b32_e32 v9, v11
	v_pk_add_f32 v[10:11], v[86:87], v[88:89] neg_lo:[0,1] neg_hi:[0,1]
	v_pk_fma_f32 v[94:95], v[50:51], s[84:85], v[92:93] op_sel:[0,0,1] op_sel_hi:[1,0,0]
	v_pk_mul_f32 v[66:67], v[10:11], 0 op_sel_hi:[1,0]
	v_pk_fma_f32 v[92:93], v[50:51], s[84:85], v[92:93] op_sel:[0,0,1] op_sel_hi:[1,0,0] neg_lo:[0,0,1] neg_hi:[0,0,1]
	v_pk_add_f32 v[14:15], v[10:11], v[66:67] op_sel:[0,1] op_sel_hi:[1,0] neg_lo:[0,1] neg_hi:[0,1]
	v_pk_add_f32 v[10:11], v[10:11], v[66:67] op_sel:[0,1] op_sel_hi:[1,0]
	v_pk_add_f32 v[66:67], v[84:85], v[90:91] neg_lo:[0,1] neg_hi:[0,1]
	v_mov_b32_e32 v15, v11
	v_pk_mul_f32 v[80:81], v[66:67], 0 op_sel_hi:[1,0]
	v_mov_b32_e32 v95, v93
	v_pk_add_f32 v[10:11], v[66:67], v[80:81] op_sel:[0,1] op_sel_hi:[1,0] neg_lo:[0,1] neg_hi:[0,1]
	v_pk_add_f32 v[66:67], v[66:67], v[80:81] op_sel:[0,1] op_sel_hi:[1,0]
	v_pk_add_f32 v[92:93], v[46:47], 0 op_sel_hi:[1,0]
	v_mov_b32_e32 v11, v67
	v_pk_add_f32 v[66:67], v[38:39], 0 op_sel_hi:[1,0]
	v_mov_b32_e32 v108, v41
	v_pk_mul_f32 v[110:111], v[40:41], s[24:25] op_sel_hi:[0,1]
	v_pk_mul_f32 v[80:81], v[38:39], 0 op_sel_hi:[1,0]
	v_pk_fma_f32 v[108:109], v[108:109], s[34:35], v[110:111] op_sel_hi:[0,1,1] neg_lo:[0,0,1] neg_hi:[0,0,1]
	v_pk_add_f32 v[110:111], v[66:67], v[92:93]
	v_pk_add_f32 v[66:67], v[66:67], v[92:93] neg_lo:[0,1] neg_hi:[0,1]
	v_pk_add_f32 v[82:83], v[38:39], v[80:81] op_sel:[0,1] op_sel_hi:[1,0] neg_lo:[0,1] neg_hi:[0,1]
	v_pk_add_f32 v[80:81], v[38:39], v[80:81] op_sel:[0,1] op_sel_hi:[1,0]
	v_pk_fma_f32 v[96:97], v[46:47], 0, v[46:47] op_sel:[0,0,1] op_sel_hi:[1,0,0]
; template <int R, bool INV> DEV void dft_regs(cf (&v)[R]) {
; #pragma unroll
;     for (int s = R; s >= 2; s >>= 1) {
;         const int h = s >> 1;
; #pragma unroll
;         for (int b = 0; b < R; b += s) {
; #pragma unroll
;             for (int k = 0; k < h; ++k) {
;                 const cf a = v[b + k], c = v[b + k + h];
;                 v[b + k] = a + c;
;                 const cf d = a - c;
;                 const int m = k * (32 / s);
;                 const float wr = tw_cos(m), wi = INV ? tw_sin(m) : -tw_sin(m);
;                 v[b + k + h] = cf{d.x * wr - d.y * wi, d.x * wi + d.y * wr};
;             }
;         }
;     }
; }
	v_pk_fma_f32 v[98:99], v[46:47], 0, v[46:47] op_sel:[0,0,1] op_sel_hi:[1,0,0] neg_lo:[0,0,1] neg_hi:[0,0,1]
	v_pk_mul_f32 v[92:93], v[66:67], 0 op_sel_hi:[1,0]
	v_mov_b32_e32 v83, v81
	v_pk_add_f32 v[80:81], v[42:43], 0 op_sel_hi:[1,0]
	v_mov_b32_e32 v97, v99
	v_pk_add_f32 v[98:99], v[48:49], 0 op_sel_hi:[1,0]
	v_pk_add_f32 v[112:113], v[66:67], v[92:93] op_sel:[0,1] op_sel_hi:[1,0] neg_lo:[0,1] neg_hi:[0,1]
	v_pk_add_f32 v[66:67], v[66:67], v[92:93] op_sel:[0,1] op_sel_hi:[1,0]
	v_pk_add_f32 v[74:75], v[84:85], v[90:91]
	v_pk_mul_f32 v[84:85], v[42:43], s[84:85] op_sel_hi:[1,0]
	v_mov_b32_e32 v113, v67
	v_pk_add_f32 v[66:67], v[80:81], v[98:99]
	v_pk_add_f32 v[80:81], v[80:81], v[98:99] neg_lo:[0,1] neg_hi:[0,1]
	v_pk_add_f32 v[78:79], v[86:87], v[88:89]
	v_pk_fma_f32 v[86:87], v[42:43], s[16:17], v[84:85] op_sel:[0,0,1] op_sel_hi:[1,0,0]
	v_pk_fma_f32 v[84:85], v[42:43], s[16:17], v[84:85] op_sel:[0,0,1] op_sel_hi:[1,0,0] neg_lo:[0,0,1] neg_hi:[0,0,1]
	v_mov_b32_e32 v100, v49
	v_pk_mul_f32 v[102:103], v[48:49], s[84:85] op_sel_hi:[0,1]
	v_pk_mul_f32 v[92:93], v[80:81], s[18:19] op_sel_hi:[1,0]
	v_mov_b32_e32 v87, v85
	v_pk_add_f32 v[84:85], v[44:45], 0 op_sel_hi:[1,0]
	v_pk_mul_f32 v[88:89], v[44:45], s[18:19] op_sel_hi:[1,0]
	v_pk_fma_f32 v[100:101], v[100:101], s[30:31], v[102:103] op_sel_hi:[0,1,1] neg_lo:[0,0,1] neg_hi:[0,0,1]
	v_pk_add_f32 v[102:103], v[52:53], 0 op_sel_hi:[1,0]
	v_pk_fma_f32 v[98:99], v[80:81], s[18:19], v[92:93] op_sel:[0,0,1] op_sel_hi:[1,0,0]
	v_pk_fma_f32 v[80:81], v[80:81], s[18:19], v[92:93] op_sel_hi:[1,0,0] neg_lo:[0,0,1] neg_hi:[0,0,1]
	v_pk_fma_f32 v[90:91], v[44:45], s[18:19], v[88:89] op_sel:[0,0,1] op_sel_hi:[1,0,0]
	v_pk_fma_f32 v[88:89], v[44:45], s[18:19], v[88:89] op_sel_hi:[1,0,0] neg_lo:[0,0,1] neg_hi:[0,0,1]
	v_mul_f32_e32 v104, 0x3f3504f3, v52
	v_mov_b32_e32 v106, v53
	v_mov_b32_e32 v99, v81
	v_pk_add_f32 v[80:81], v[84:85], v[102:103]
	v_pk_add_f32 v[84:85], v[84:85], v[102:103] neg_lo:[0,1] neg_hi:[0,1]
	v_mov_b32_e32 v91, v89
	v_pk_add_f32 v[88:89], v[50:51], 0 op_sel_hi:[1,0]
	v_pk_fma_f32 v[104:105], v[106:107], s[28:29], v[104:105] op_sel_hi:[0,1,0] neg_lo:[0,0,1] neg_hi:[0,0,1]
	v_pk_add_f32 v[106:107], v[40:41], 0 op_sel_hi:[1,0]
	v_pk_fma_f32 v[92:93], v[84:85], 0, v[84:85] op_sel:[0,0,1] op_sel_hi:[1,0,0]
	v_pk_fma_f32 v[84:85], v[84:85], 0, v[84:85] op_sel:[0,0,1] op_sel_hi:[1,0,0] neg_lo:[0,0,1] neg_hi:[0,0,1]
	v_mov_b32_e32 v114, v21
	v_mov_b32_e32 v93, v85
	v_pk_add_f32 v[84:85], v[88:89], v[106:107]
	v_pk_add_f32 v[88:89], v[88:89], v[106:107] neg_lo:[0,1] neg_hi:[0,1]
	s_mov_b32 s2, s86
	v_mul_f32_e32 v102, 0x3f3504f3, v88
	v_pk_fma_f32 v[88:89], v[88:89], s[28:29], v[102:103] op_sel:[1,0,0] op_sel_hi:[1,1,0] neg_lo:[0,0,1] neg_hi:[0,0,1]
	v_pk_add_f32 v[102:103], v[82:83], v[96:97]
	v_pk_add_f32 v[82:83], v[82:83], v[96:97] neg_lo:[0,1] neg_hi:[0,1]
	s_mov_b32 s3, s4
	v_pk_mul_f32 v[96:97], v[82:83], 0 op_sel_hi:[1,0]
	s_mov_b32 s10, s4
	v_pk_add_f32 v[106:107], v[82:83], v[96:97] op_sel:[0,1] op_sel_hi:[1,0] neg_lo:[0,1] neg_hi:[0,1]
	v_pk_add_f32 v[82:83], v[82:83], v[96:97] op_sel:[0,1] op_sel_hi:[1,0]
	s_mov_b32 s6, s94
	v_mov_b32_e32 v107, v83
	v_pk_add_f32 v[82:83], v[86:87], v[100:101]
	v_pk_add_f32 v[86:87], v[86:87], v[100:101] neg_lo:[0,1] neg_hi:[0,1]
	s_mov_b32 s7, s82
	v_pk_mul_f32 v[96:97], v[86:87], s[18:19] op_sel_hi:[1,0]
	s_mov_b32 s8, s82
	v_pk_fma_f32 v[100:101], v[86:87], s[18:19], v[96:97] op_sel:[0,0,1] op_sel_hi:[1,0,0]
	v_pk_fma_f32 v[86:87], v[86:87], s[18:19], v[96:97] op_sel_hi:[1,0,0] neg_lo:[0,0,1] neg_hi:[0,0,1]
	s_lshl_b32 s92, s19, 13
	v_mov_b32_e32 v101, v87
	v_pk_add_f32 v[86:87], v[90:91], v[104:105]
	v_pk_add_f32 v[90:91], v[90:91], v[104:105] neg_lo:[0,1] neg_hi:[0,1]
	s_mov_b32 s1, s85
	v_pk_fma_f32 v[96:97], v[90:91], 0, v[90:91] op_sel:[0,0,1] op_sel_hi:[1,0,0]
	v_pk_fma_f32 v[90:91], v[90:91], 0, v[90:91] op_sel:[0,0,1] op_sel_hi:[1,0,0] neg_lo:[0,0,1] neg_hi:[0,0,1]
	s_mov_b32 s89, s84
	v_mov_b32_e32 v97, v91
	v_pk_add_f32 v[90:91], v[94:95], v[108:109]
	v_pk_add_f32 v[94:95], v[94:95], v[108:109] neg_lo:[0,1] neg_hi:[0,1]
	v_mul_f32_e32 v104, 0x3f3504f3, v94
	v_pk_fma_f32 v[94:95], v[94:95], s[28:29], v[104:105] op_sel:[1,0,0] op_sel_hi:[1,1,0] neg_lo:[0,0,1] neg_hi:[0,0,1]
	v_pk_add_f32 v[104:105], v[110:111], v[80:81]
	v_pk_add_f32 v[80:81], v[110:111], v[80:81] neg_lo:[0,1] neg_hi:[0,1]
	v_pk_mul_f32 v[108:109], v[80:81], 0 op_sel_hi:[1,0]
	v_pk_add_f32 v[110:111], v[80:81], v[108:109] op_sel:[0,1] op_sel_hi:[1,0] neg_lo:[0,1] neg_hi:[0,1]
	v_pk_add_f32 v[80:81], v[80:81], v[108:109] op_sel:[0,1] op_sel_hi:[1,0]
	v_mov_b32_e32 v111, v81
	v_pk_add_f32 v[80:81], v[66:67], v[84:85]
	v_pk_add_f32 v[66:67], v[66:67], v[84:85] neg_lo:[0,1] neg_hi:[0,1]
	v_pk_fma_f32 v[84:85], v[66:67], 0, v[66:67] op_sel:[0,0,1] op_sel_hi:[1,0,0]
	v_pk_fma_f32 v[66:67], v[66:67], 0, v[66:67] op_sel:[0,0,1] op_sel_hi:[1,0,0] neg_lo:[0,0,1] neg_hi:[0,0,1]
	v_mov_b32_e32 v85, v67
	v_pk_add_f32 v[66:67], v[112:113], v[92:93]
	v_pk_add_f32 v[92:93], v[112:113], v[92:93] neg_lo:[0,1] neg_hi:[0,1]
	v_pk_mul_f32 v[108:109], v[92:93], 0 op_sel_hi:[1,0]
	v_pk_add_f32 v[112:113], v[92:93], v[108:109] op_sel:[0,1] op_sel_hi:[1,0] neg_lo:[0,1] neg_hi:[0,1]
	v_pk_add_f32 v[92:93], v[92:93], v[108:109] op_sel:[0,1] op_sel_hi:[1,0]
	v_mov_b32_e32 v113, v93
	v_pk_add_f32 v[92:93], v[98:99], v[88:89]
	v_pk_add_f32 v[88:89], v[98:99], v[88:89] neg_lo:[0,1] neg_hi:[0,1]
	v_pk_fma_f32 v[98:99], v[88:89], 0, v[88:89] op_sel:[0,0,1] op_sel_hi:[1,0,0]
	v_pk_fma_f32 v[88:89], v[88:89], 0, v[88:89] op_sel:[0,0,1] op_sel_hi:[1,0,0] neg_lo:[0,0,1] neg_hi:[0,0,1]
	v_mov_b32_e32 v99, v89
; #define LAS __attribute__((address_space(3)))
; #define SINCOSPI(x, s, c) do { const float hx_ = 0.5f * (x); *(s) = __builtin_amdgcn_sinf(hx_); *(c) = __builtin_amdgcn_cosf(hx_); } while (0)
; template <int R, bool INV> DEV void dft_regs(cf (&v)[R]) {
; #pragma unroll
;     for (int s = R; s >= 2; s >>= 1) {
;         const int h = s >> 1;
; #pragma unroll
;         for (int b = 0; b < R; b += s) {
; #pragma unroll
;             for (int k = 0; k < h; ++k) {
;                 const cf a = v[b + k], c = v[b + k + h];
;                 v[b + k] = a + c;
;                 const cf d = a - c;
;                 const int m = k * (32 / s);
;                 const float wr = tw_cos(m), wi = INV ? tw_sin(m) : -tw_sin(m);
;                 v[b + k + h] = cf{d.x * wr - d.y * wi, d.x * wi + d.y * wr};
;             }
;         }
;     }
; }
; DEV void fft_f1x2(LAS cf* buf0, LAS cf* buf1, const cf (&z0)[8], const cf (&z1)[8], int tid) {
;     ...
;     float sn, cs; SINCOSPI(-(float)tid * (2.0f / 8192.0f), &sn, &cs);
;     const cf w = cf{cs, sn}; cf wp = cf{1.f, 0.f};
;     LAS cf* p0 = buf0 + PADI(tid); LAS cf* p1 = buf1 + PADI(tid);
; #pragma unroll
;     for (int p = 0; p < 16; ++p) { p0[544 * p] = cmul(v[BR16[p]], wp); p1[544 * p] = cmul(u[BR16[p]], wp); wp = cmul(wp, w); }
	v_pk_add_f32 v[88:89], v[102:103], v[86:87]
	v_pk_add_f32 v[86:87], v[102:103], v[86:87] neg_lo:[0,1] neg_hi:[0,1]
	v_pk_mul_f32 v[102:103], v[86:87], 0 op_sel_hi:[1,0]
	v_pk_add_f32 v[108:109], v[86:87], v[102:103] op_sel:[0,1] op_sel_hi:[1,0] neg_lo:[0,1] neg_hi:[0,1]
	v_pk_add_f32 v[86:87], v[86:87], v[102:103] op_sel:[0,1] op_sel_hi:[1,0]
	v_mov_b32_e32 v109, v87
	v_pk_add_f32 v[86:87], v[82:83], v[90:91]
	v_pk_add_f32 v[82:83], v[82:83], v[90:91] neg_lo:[0,1] neg_hi:[0,1]
	v_pk_fma_f32 v[90:91], v[82:83], 0, v[82:83] op_sel:[0,0,1] op_sel_hi:[1,0,0]
	v_pk_fma_f32 v[82:83], v[82:83], 0, v[82:83] op_sel:[0,0,1] op_sel_hi:[1,0,0] neg_lo:[0,0,1] neg_hi:[0,0,1]
	v_mov_b32_e32 v91, v83
	v_pk_add_f32 v[82:83], v[106:107], v[96:97]
	v_pk_add_f32 v[96:97], v[106:107], v[96:97] neg_lo:[0,1] neg_hi:[0,1]
	v_pk_mul_f32 v[102:103], v[96:97], 0 op_sel_hi:[1,0]
	v_pk_add_f32 v[106:107], v[96:97], v[102:103] op_sel:[0,1] op_sel_hi:[1,0] neg_lo:[0,1] neg_hi:[0,1]
	v_pk_add_f32 v[96:97], v[96:97], v[102:103] op_sel:[0,1] op_sel_hi:[1,0]
	v_mov_b32_e32 v107, v97
	v_pk_add_f32 v[96:97], v[100:101], v[94:95]
	v_pk_add_f32 v[94:95], v[100:101], v[94:95] neg_lo:[0,1] neg_hi:[0,1]
	v_pk_fma_f32 v[100:101], v[94:95], 0, v[94:95] op_sel:[0,0,1] op_sel_hi:[1,0,0]
	v_pk_fma_f32 v[94:95], v[94:95], 0, v[94:95] op_sel:[0,0,1] op_sel_hi:[1,0,0] neg_lo:[0,0,1] neg_hi:[0,0,1]
	v_mov_b32_e32 v101, v95
	v_pk_add_f32 v[94:95], v[104:105], v[80:81]
	v_pk_add_f32 v[80:81], v[104:105], v[80:81] neg_lo:[0,1] neg_hi:[0,1]
	v_pk_mul_f32 v[102:103], v[80:81], 0 op_sel_hi:[1,0]
	v_pk_add_f32 v[104:105], v[80:81], v[102:103] op_sel:[0,1] op_sel_hi:[1,0] neg_lo:[0,1] neg_hi:[0,1]
	v_pk_add_f32 v[80:81], v[80:81], v[102:103] op_sel:[0,1] op_sel_hi:[1,0]
	v_mov_b32_e32 v105, v81
	v_pk_add_f32 v[80:81], v[110:111], v[84:85]
	v_pk_add_f32 v[84:85], v[110:111], v[84:85] neg_lo:[0,1] neg_hi:[0,1]
	v_pk_mul_f32 v[102:103], v[84:85], 0 op_sel_hi:[1,0]
	v_pk_add_f32 v[110:111], v[84:85], v[102:103] op_sel:[0,1] op_sel_hi:[1,0] neg_lo:[0,1] neg_hi:[0,1]
	v_pk_add_f32 v[84:85], v[84:85], v[102:103] op_sel:[0,1] op_sel_hi:[1,0]
	v_mov_b32_e32 v111, v85
	v_pk_add_f32 v[84:85], v[66:67], v[92:93]
	v_pk_add_f32 v[66:67], v[66:67], v[92:93] neg_lo:[0,1] neg_hi:[0,1]
	v_pk_mul_f32 v[92:93], v[66:67], 0 op_sel_hi:[1,0]
	v_pk_add_f32 v[102:103], v[66:67], v[92:93] op_sel:[0,1] op_sel_hi:[1,0] neg_lo:[0,1] neg_hi:[0,1]
	v_pk_add_f32 v[66:67], v[66:67], v[92:93] op_sel:[0,1] op_sel_hi:[1,0]
	v_pk_add_f32 v[92:93], v[112:113], v[98:99]
	v_mov_b32_e32 v103, v67
	v_pk_add_f32 v[66:67], v[112:113], v[98:99] neg_lo:[0,1] neg_hi:[0,1]
	v_pk_mul_f32 v[98:99], v[66:67], 0 op_sel_hi:[1,0]
	v_pk_add_f32 v[112:113], v[66:67], v[98:99] op_sel:[0,1] op_sel_hi:[1,0] neg_lo:[0,1] neg_hi:[0,1]
	v_pk_add_f32 v[66:67], v[66:67], v[98:99] op_sel:[0,1] op_sel_hi:[1,0]
	v_pk_add_f32 v[98:99], v[88:89], v[86:87]
	v_mov_b32_e32 v113, v67
	v_pk_add_f32 v[66:67], v[88:89], v[86:87] neg_lo:[0,1] neg_hi:[0,1]
	v_pk_mul_f32 v[86:87], v[66:67], 0 op_sel_hi:[1,0]
	v_pk_add_f32 v[88:89], v[66:67], v[86:87] op_sel:[0,1] op_sel_hi:[1,0] neg_lo:[0,1] neg_hi:[0,1]
	v_pk_add_f32 v[66:67], v[66:67], v[86:87] op_sel:[0,1] op_sel_hi:[1,0]
	v_pk_add_f32 v[86:87], v[108:109], v[90:91]
	v_mov_b32_e32 v89, v67
	v_pk_add_f32 v[66:67], v[108:109], v[90:91] neg_lo:[0,1] neg_hi:[0,1]
	v_pk_mul_f32 v[90:91], v[66:67], 0 op_sel_hi:[1,0]
	v_pk_add_f32 v[108:109], v[66:67], v[90:91] op_sel:[0,1] op_sel_hi:[1,0] neg_lo:[0,1] neg_hi:[0,1]
	v_pk_add_f32 v[66:67], v[66:67], v[90:91] op_sel:[0,1] op_sel_hi:[1,0]
	v_pk_add_f32 v[90:91], v[82:83], v[96:97]
	v_mov_b32_e32 v109, v67
	v_pk_add_f32 v[66:67], v[82:83], v[96:97] neg_lo:[0,1] neg_hi:[0,1]
	v_pk_mul_f32 v[82:83], v[66:67], 0 op_sel_hi:[1,0]
	v_pk_add_f32 v[96:97], v[66:67], v[82:83] op_sel:[0,1] op_sel_hi:[1,0] neg_lo:[0,1] neg_hi:[0,1]
	v_pk_add_f32 v[66:67], v[66:67], v[82:83] op_sel:[0,1] op_sel_hi:[1,0]
	v_pk_add_f32 v[82:83], v[106:107], v[100:101]
	v_mov_b32_e32 v97, v67
	v_pk_add_f32 v[66:67], v[106:107], v[100:101] neg_lo:[0,1] neg_hi:[0,1]
	v_pk_mul_f32 v[100:101], v[66:67], 0 op_sel_hi:[1,0]
	v_pk_add_f32 v[106:107], v[66:67], v[100:101] op_sel:[0,1] op_sel_hi:[1,0] neg_lo:[0,1] neg_hi:[0,1]
	v_pk_add_f32 v[66:67], v[66:67], v[100:101] op_sel:[0,1] op_sel_hi:[1,0]
	s_nop 0
	v_cvt_f32_i32_e32 v66, v114
	v_mov_b32_e32 v107, v67
	v_mul_f32_e32 v66, 0xb9800000, v66
	v_mul_f32_e32 v66, 0.5, v66
	v_sin_f32_e32 v101, v66
	v_cos_f32_e32 v100, v66
	v_ashrrev_i32_e32 v66, 4, v114
	v_add_lshl_u32 v66, v66, v114, 3
	v_add_u32_e32 v116, 0, v66
	v_add_u32_e32 v117, s33, v66
	v_mov_b64_e32 v[66:67], s[90:91]
	v_pk_mul_f32 v[114:115], v[68:69], v[66:67] op_sel:[1,1] op_sel_hi:[1,0] neg_lo:[1,0]
	v_pk_fma_f32 v[68:69], v[68:69], v[66:67], v[114:115] op_sel_hi:[0,1,1]
	ds_write_b64 v116, v[68:69]
	v_pk_mul_f32 v[114:115], v[94:95], v[66:67] op_sel:[1,1] op_sel_hi:[1,0] neg_lo:[1,0]
	v_pk_fma_f32 v[68:69], v[94:95], v[66:67], v[114:115] op_sel_hi:[0,1,1]
	ds_write_b64 v117, v[68:69]
	v_pk_mul_f32 v[68:69], v[66:67], v[100:101] op_sel:[1,1] op_sel_hi:[1,0] neg_lo:[1,0]
	v_pk_fma_f32 v[94:95], v[66:67], v[100:101], v[68:69] op_sel_hi:[0,1,1]
	v_pk_mul_f32 v[114:115], v[76:77], v[94:95] op_sel:[1,1] op_sel_hi:[1,0] neg_lo:[1,0]
	v_pk_fma_f32 v[68:69], v[76:77], v[94:95], v[114:115] op_sel_hi:[0,1,1]
	ds_write_b64 v116, v[68:69] offset:4352
	v_pk_mul_f32 v[76:77], v[98:99], v[94:95] op_sel:[1,1] op_sel_hi:[1,0] neg_lo:[1,0]
	v_pk_fma_f32 v[68:69], v[98:99], v[94:95], v[76:77] op_sel_hi:[0,1,1]
	ds_write_b64 v117, v[68:69] offset:4352
	v_pk_mul_f32 v[68:69], v[94:95], v[100:101] op_sel:[1,1] op_sel_hi:[1,0] neg_lo:[1,0]
; #define LAS __attribute__((address_space(3)))
; DEV void fft_f1x2(LAS cf* buf0, LAS cf* buf1, const cf (&z0)[8], const cf (&z1)[8], int tid) {
;     ...
;     LAS cf* p0 = buf0 + PADI(tid); LAS cf* p1 = buf1 + PADI(tid);
; #pragma unroll
;     for (int p = 0; p < 16; ++p) { p0[544 * p] = cmul(v[BR16[p]], wp); p1[544 * p] = cmul(u[BR16[p]], wp); wp = cmul(wp, w); }
	v_pk_fma_f32 v[76:77], v[94:95], v[100:101], v[68:69] op_sel_hi:[0,1,1]
	v_pk_mul_f32 v[94:95], v[70:71], v[76:77] op_sel:[1,1] op_sel_hi:[1,0] neg_lo:[1,0]
	v_pk_fma_f32 v[68:69], v[70:71], v[76:77], v[94:95] op_sel_hi:[0,1,1]
	ds_write_b64 v116, v[68:69] offset:8704
	v_pk_mul_f32 v[70:71], v[84:85], v[76:77] op_sel:[1,1] op_sel_hi:[1,0] neg_lo:[1,0]
	v_pk_fma_f32 v[68:69], v[84:85], v[76:77], v[70:71] op_sel_hi:[0,1,1]
	ds_write_b64 v117, v[68:69] offset:8704
	v_pk_mul_f32 v[68:69], v[76:77], v[100:101] op_sel:[1,1] op_sel_hi:[1,0] neg_lo:[1,0]
	v_pk_fma_f32 v[70:71], v[76:77], v[100:101], v[68:69] op_sel_hi:[0,1,1]
	v_pk_mul_f32 v[76:77], v[78:79], v[70:71] op_sel:[1,1] op_sel_hi:[1,0] neg_lo:[1,0]
	v_pk_fma_f32 v[68:69], v[78:79], v[70:71], v[76:77] op_sel_hi:[0,1,1]
	ds_write_b64 v116, v[68:69] offset:13056
	v_pk_mul_f32 v[76:77], v[90:91], v[70:71] op_sel:[1,1] op_sel_hi:[1,0] neg_lo:[1,0]
	v_pk_fma_f32 v[68:69], v[90:91], v[70:71], v[76:77] op_sel_hi:[0,1,1]
	ds_write_b64 v117, v[68:69] offset:13056
	v_pk_mul_f32 v[68:69], v[70:71], v[100:101] op_sel:[1,1] op_sel_hi:[1,0] neg_lo:[1,0]
	v_pk_fma_f32 v[70:71], v[70:71], v[100:101], v[68:69] op_sel_hi:[0,1,1]
	v_pk_mul_f32 v[68:69], v[16:17], v[70:71] op_sel:[1,1] op_sel_hi:[1,0] neg_lo:[1,0]
	v_pk_fma_f32 v[16:17], v[16:17], v[70:71], v[68:69] op_sel_hi:[0,1,1]
	ds_write_b64 v116, v[16:17] offset:17408
	v_pk_mul_f32 v[68:69], v[80:81], v[70:71] op_sel:[1,1] op_sel_hi:[1,0] neg_lo:[1,0]
	v_pk_fma_f32 v[16:17], v[80:81], v[70:71], v[68:69] op_sel_hi:[0,1,1]
	ds_write_b64 v117, v[16:17] offset:17408
	v_pk_mul_f32 v[16:17], v[70:71], v[100:101] op_sel:[1,1] op_sel_hi:[1,0] neg_lo:[1,0]
	v_pk_fma_f32 v[68:69], v[70:71], v[100:101], v[16:17] op_sel_hi:[0,1,1]
	v_pk_mul_f32 v[70:71], v[72:73], v[68:69] op_sel:[1,1] op_sel_hi:[1,0] neg_lo:[1,0]
	v_pk_fma_f32 v[16:17], v[72:73], v[68:69], v[70:71] op_sel_hi:[0,1,1]
	ds_write_b64 v116, v[16:17] offset:21760
	v_pk_mul_f32 v[70:71], v[86:87], v[68:69] op_sel:[1,1] op_sel_hi:[1,0] neg_lo:[1,0]
	v_pk_fma_f32 v[16:17], v[86:87], v[68:69], v[70:71] op_sel_hi:[0,1,1]
	ds_write_b64 v117, v[16:17] offset:21760
	v_pk_mul_f32 v[16:17], v[68:69], v[100:101] op_sel:[1,1] op_sel_hi:[1,0] neg_lo:[1,0]
	v_pk_fma_f32 v[68:69], v[68:69], v[100:101], v[16:17] op_sel_hi:[0,1,1]
	v_pk_mul_f32 v[70:71], v[18:19], v[68:69] op_sel:[1,1] op_sel_hi:[1,0] neg_lo:[1,0]
	v_pk_fma_f32 v[16:17], v[18:19], v[68:69], v[70:71] op_sel_hi:[0,1,1]
	ds_write_b64 v116, v[16:17] offset:26112
	v_pk_mul_f32 v[18:19], v[92:93], v[68:69] op_sel:[1,1] op_sel_hi:[1,0] neg_lo:[1,0]
	v_pk_fma_f32 v[16:17], v[92:93], v[68:69], v[18:19] op_sel_hi:[0,1,1]
	ds_write_b64 v117, v[16:17] offset:26112
	v_pk_mul_f32 v[16:17], v[68:69], v[100:101] op_sel:[1,1] op_sel_hi:[1,0] neg_lo:[1,0]
	v_pk_fma_f32 v[18:19], v[68:69], v[100:101], v[16:17] op_sel_hi:[0,1,1]
	v_pk_mul_f32 v[68:69], v[74:75], v[18:19] op_sel:[1,1] op_sel_hi:[1,0] neg_lo:[1,0]
	v_pk_fma_f32 v[16:17], v[74:75], v[18:19], v[68:69] op_sel_hi:[0,1,1]
	ds_write_b64 v116, v[16:17] offset:30464
	v_pk_mul_f32 v[68:69], v[82:83], v[18:19] op_sel:[1,1] op_sel_hi:[1,0] neg_lo:[1,0]
	v_pk_fma_f32 v[16:17], v[82:83], v[18:19], v[68:69] op_sel_hi:[0,1,1]
	ds_write_b64 v117, v[16:17] offset:30464
	v_pk_mul_f32 v[16:17], v[18:19], v[100:101] op_sel:[1,1] op_sel_hi:[1,0] neg_lo:[1,0]
	v_pk_fma_f32 v[18:19], v[18:19], v[100:101], v[16:17] op_sel_hi:[0,1,1]
	v_pk_mul_f32 v[16:17], v[4:5], v[18:19] op_sel:[1,1] op_sel_hi:[1,0] neg_lo:[1,0]
	v_pk_fma_f32 v[4:5], v[4:5], v[18:19], v[16:17] op_sel_hi:[0,1,1]
	ds_write_b64 v116, v[4:5] offset:34816
	v_pk_mul_f32 v[16:17], v[104:105], v[18:19] op_sel:[1,1] op_sel_hi:[1,0] neg_lo:[1,0]
	v_pk_fma_f32 v[4:5], v[104:105], v[18:19], v[16:17] op_sel_hi:[0,1,1]
	ds_write_b64 v117, v[4:5] offset:34816
	v_pk_mul_f32 v[4:5], v[18:19], v[100:101] op_sel:[1,1] op_sel_hi:[1,0] neg_lo:[1,0]
	v_pk_fma_f32 v[16:17], v[18:19], v[100:101], v[4:5] op_sel_hi:[0,1,1]
	v_pk_mul_f32 v[18:19], v[12:13], v[16:17] op_sel:[1,1] op_sel_hi:[1,0] neg_lo:[1,0]
	v_pk_fma_f32 v[4:5], v[12:13], v[16:17], v[18:19] op_sel_hi:[0,1,1]
	ds_write_b64 v116, v[4:5] offset:39168
	v_pk_mul_f32 v[12:13], v[88:89], v[16:17] op_sel:[1,1] op_sel_hi:[1,0] neg_lo:[1,0]
	v_pk_fma_f32 v[4:5], v[88:89], v[16:17], v[12:13] op_sel_hi:[0,1,1]
	ds_write_b64 v117, v[4:5] offset:39168
	v_pk_mul_f32 v[4:5], v[16:17], v[100:101] op_sel:[1,1] op_sel_hi:[1,0] neg_lo:[1,0]
	v_pk_fma_f32 v[12:13], v[16:17], v[100:101], v[4:5] op_sel_hi:[0,1,1]
	v_pk_mul_f32 v[16:17], v[6:7], v[12:13] op_sel:[1,1] op_sel_hi:[1,0] neg_lo:[1,0]
	v_pk_fma_f32 v[4:5], v[6:7], v[12:13], v[16:17] op_sel_hi:[0,1,1]
	ds_write_b64 v116, v[4:5] offset:43520
	v_pk_mul_f32 v[6:7], v[102:103], v[12:13] op_sel:[1,1] op_sel_hi:[1,0] neg_lo:[1,0]
	v_pk_fma_f32 v[4:5], v[102:103], v[12:13], v[6:7] op_sel_hi:[0,1,1]
	ds_write_b64 v117, v[4:5] offset:43520
	v_pk_mul_f32 v[4:5], v[12:13], v[100:101] op_sel:[1,1] op_sel_hi:[1,0] neg_lo:[1,0]
	v_pk_fma_f32 v[6:7], v[12:13], v[100:101], v[4:5] op_sel_hi:[0,1,1]
	v_pk_mul_f32 v[12:13], v[14:15], v[6:7] op_sel:[1,1] op_sel_hi:[1,0] neg_lo:[1,0]
	v_pk_fma_f32 v[4:5], v[14:15], v[6:7], v[12:13] op_sel_hi:[0,1,1]
	ds_write_b64 v116, v[4:5] offset:47872
	v_pk_mul_f32 v[12:13], v[96:97], v[6:7] op_sel:[1,1] op_sel_hi:[1,0] neg_lo:[1,0]
	v_pk_fma_f32 v[4:5], v[96:97], v[6:7], v[12:13] op_sel_hi:[0,1,1]
	ds_write_b64 v117, v[4:5] offset:47872
	v_pk_mul_f32 v[4:5], v[6:7], v[100:101] op_sel:[1,1] op_sel_hi:[1,0] neg_lo:[1,0]
	v_pk_fma_f32 v[6:7], v[6:7], v[100:101], v[4:5] op_sel_hi:[0,1,1]
	v_pk_mul_f32 v[4:5], v[0:1], v[6:7] op_sel:[1,1] op_sel_hi:[1,0] neg_lo:[1,0]
; #define LAS __attribute__((address_space(3)))
; #define OPAQUE_I(x) asm volatile("" : "+v"(x))
; DEV void fft_f1x2(LAS cf* buf0, LAS cf* buf1, const cf (&z0)[8], const cf (&z1)[8], int tid) {
;     ...
;     LAS cf* p0 = buf0 + PADI(tid); LAS cf* p1 = buf1 + PADI(tid);
; #pragma unroll
;     for (int p = 0; p < 16; ++p) { p0[544 * p] = cmul(v[BR16[p]], wp); p1[544 * p] = cmul(u[BR16[p]], wp); wp = cmul(wp, w); }
; DEV void fft_f2(LAS cf* buf, int t8) {
;     OPAQUE_I(t8);
;     LAS cf* pb = buf + (t8 >> 4) * 544 + (t8 & 15);
;     cf v[32];
; #pragma unroll
;     for (int q = 0; q < 32; ++q) v[q] = pb[17 * q];
;     dft_regs<32, false>(v);
	v_pk_fma_f32 v[0:1], v[0:1], v[6:7], v[4:5] op_sel_hi:[0,1,1]
	ds_write_b64 v116, v[0:1] offset:52224
	v_pk_mul_f32 v[4:5], v[110:111], v[6:7] op_sel:[1,1] op_sel_hi:[1,0] neg_lo:[1,0]
	v_pk_fma_f32 v[0:1], v[110:111], v[6:7], v[4:5] op_sel_hi:[0,1,1]
	ds_write_b64 v117, v[0:1] offset:52224
	v_pk_mul_f32 v[0:1], v[6:7], v[100:101] op_sel:[1,1] op_sel_hi:[1,0] neg_lo:[1,0]
	v_pk_fma_f32 v[4:5], v[6:7], v[100:101], v[0:1] op_sel_hi:[0,1,1]
	v_pk_mul_f32 v[6:7], v[8:9], v[4:5] op_sel:[1,1] op_sel_hi:[1,0] neg_lo:[1,0]
	v_pk_fma_f32 v[0:1], v[8:9], v[4:5], v[6:7] op_sel_hi:[0,1,1]
	ds_write_b64 v116, v[0:1] offset:56576
	v_pk_mul_f32 v[6:7], v[108:109], v[4:5] op_sel:[1,1] op_sel_hi:[1,0] neg_lo:[1,0]
	v_pk_fma_f32 v[0:1], v[108:109], v[4:5], v[6:7] op_sel_hi:[0,1,1]
	ds_write_b64 v117, v[0:1] offset:56576
	v_pk_mul_f32 v[0:1], v[4:5], v[100:101] op_sel:[1,1] op_sel_hi:[1,0] neg_lo:[1,0]
	v_pk_fma_f32 v[4:5], v[4:5], v[100:101], v[0:1] op_sel_hi:[0,1,1]
	v_pk_mul_f32 v[6:7], v[2:3], v[4:5] op_sel:[1,1] op_sel_hi:[1,0] neg_lo:[1,0]
	v_pk_fma_f32 v[0:1], v[2:3], v[4:5], v[6:7] op_sel_hi:[0,1,1]
	ds_write_b64 v116, v[0:1] offset:60928
	v_pk_mul_f32 v[2:3], v[112:113], v[4:5] op_sel:[1,1] op_sel_hi:[1,0] neg_lo:[1,0]
	v_pk_fma_f32 v[0:1], v[112:113], v[4:5], v[2:3] op_sel_hi:[0,1,1]
	ds_write_b64 v117, v[0:1] offset:60928
	v_pk_mul_f32 v[0:1], v[4:5], v[100:101] op_sel:[1,1] op_sel_hi:[1,0] neg_lo:[1,0]
	v_pk_fma_f32 v[2:3], v[4:5], v[100:101], v[0:1] op_sel_hi:[0,1,1]
	v_pk_mul_f32 v[4:5], v[10:11], v[2:3] op_sel:[1,1] op_sel_hi:[1,0] neg_lo:[1,0]
	v_pk_fma_f32 v[0:1], v[10:11], v[2:3], v[4:5] op_sel_hi:[0,1,1]
	ds_write_b64 v116, v[0:1] offset:65280
	v_pk_mul_f32 v[4:5], v[106:107], v[2:3] op_sel:[1,1] op_sel_hi:[1,0] neg_lo:[1,0]
	v_pk_fma_f32 v[0:1], v[106:107], v[2:3], v[4:5] op_sel_hi:[0,1,1]
	ds_write_b64 v117, v[0:1] offset:65280
	v_mov_b32_e32 v0, v160
	s_waitcnt lgkmcnt(0)
	s_barrier
	s_nop 0
	v_lshrrev_b32_e32 v1, 4, v0
	v_and_b32_e32 v3, 15, v0
	v_mul_lo_u32 v1, v1, s15
	v_lshlrev_b32_e32 v0, 3, v3
	v_add3_u32 v2, v159, v1, v0
	ds_read2_b64 v[4:7], v2 offset1:17
	ds_read2_b64 v[8:11], v2 offset0:34 offset1:51
	ds_read2_b64 v[12:15], v2 offset0:68 offset1:85
	ds_read2_b64 v[16:19], v2 offset0:102 offset1:119
	ds_read2_b64 v[68:71], v2 offset0:136 offset1:153
	ds_read2_b64 v[72:75], v2 offset0:170 offset1:187
	ds_read2_b64 v[76:79], v2 offset0:204 offset1:221
	ds_read2_b64 v[80:83], v2 offset0:238 offset1:255
	v_add_u32_e32 v0, 0x800, v2
	ds_read2_b64 v[84:87], v0 offset0:16 offset1:33
	ds_read2_b64 v[88:91], v0 offset0:50 offset1:67
	ds_read2_b64 v[92:95], v0 offset0:84 offset1:101
	ds_read2_b64 v[96:99], v0 offset0:118 offset1:135
	ds_read2_b64 v[100:103], v0 offset0:152 offset1:169
	ds_read2_b64 v[104:107], v0 offset0:186 offset1:203
	ds_read2_b64 v[108:111], v0 offset0:220 offset1:237
	s_waitcnt lgkmcnt(6)
	v_pk_add_f32 v[116:117], v[4:5], v[84:85]
	v_pk_add_f32 v[4:5], v[4:5], v[84:85] neg_lo:[0,1] neg_hi:[0,1]
	v_add_u32_e32 v1, 0xc00, v2
	v_pk_mul_f32 v[84:85], v[4:5], 0 op_sel_hi:[1,0]
	ds_read2_b64 v[112:115], v1 offset0:126 offset1:143
	v_pk_add_f32 v[118:119], v[4:5], v[84:85] op_sel:[0,1] op_sel_hi:[1,0] neg_lo:[0,1] neg_hi:[0,1]
	v_pk_add_f32 v[4:5], v[4:5], v[84:85] op_sel:[0,1] op_sel_hi:[1,0]
	v_cvt_f32_ubyte0_e32 v3, v3
	v_mov_b32_e32 v119, v5
	v_pk_add_f32 v[4:5], v[6:7], v[86:87]
	v_pk_add_f32 v[6:7], v[6:7], v[86:87] neg_lo:[0,1] neg_hi:[0,1]
	v_mul_f32_e32 v3, 0xbb800000, v3
	v_pk_mul_f32 v[84:85], v[6:7], s[82:83] op_sel_hi:[1,0]
	v_mul_f32_e32 v3, 0.5, v3
	v_pk_fma_f32 v[86:87], v[6:7], s[94:95], v[84:85] op_sel:[0,0,1] op_sel_hi:[1,0,0]
	v_pk_fma_f32 v[6:7], v[6:7], s[94:95], v[84:85] op_sel:[0,0,1] op_sel_hi:[1,0,0] neg_lo:[0,0,1] neg_hi:[0,0,1]
	v_mov_b32_e32 v87, v7
	s_waitcnt lgkmcnt(6)
	v_pk_add_f32 v[6:7], v[8:9], v[88:89]
	v_pk_add_f32 v[8:9], v[8:9], v[88:89] neg_lo:[0,1] neg_hi:[0,1]
	v_pk_mul_f32 v[84:85], v[8:9], s[84:85] op_sel_hi:[1,0]
	v_pk_fma_f32 v[88:89], v[8:9], s[16:17], v[84:85] op_sel:[0,0,1] op_sel_hi:[1,0,0]
	v_pk_fma_f32 v[8:9], v[8:9], s[16:17], v[84:85] op_sel:[0,0,1] op_sel_hi:[1,0,0] neg_lo:[0,0,1] neg_hi:[0,0,1]
	v_mov_b32_e32 v89, v9
	v_pk_add_f32 v[8:9], v[10:11], v[90:91]
	v_pk_add_f32 v[10:11], v[10:11], v[90:91] neg_lo:[0,1] neg_hi:[0,1]
	v_pk_mul_f32 v[84:85], v[10:11], s[4:5] op_sel_hi:[1,0]
	v_pk_fma_f32 v[90:91], v[10:11], s[86:87], v[84:85] op_sel:[0,0,1] op_sel_hi:[1,0,0]
	v_pk_fma_f32 v[10:11], v[10:11], s[86:87], v[84:85] op_sel:[0,0,1] op_sel_hi:[1,0,0] neg_lo:[0,0,1] neg_hi:[0,0,1]
	v_mov_b32_e32 v91, v11
	s_waitcnt lgkmcnt(5)
	v_pk_add_f32 v[10:11], v[12:13], v[92:93]
	v_pk_add_f32 v[12:13], v[12:13], v[92:93] neg_lo:[0,1] neg_hi:[0,1]
	v_pk_mul_f32 v[84:85], v[12:13], s[18:19] op_sel_hi:[1,0]
	v_pk_fma_f32 v[92:93], v[12:13], s[18:19], v[84:85] op_sel:[0,0,1] op_sel_hi:[1,0,0]
	v_pk_fma_f32 v[12:13], v[12:13], s[18:19], v[84:85] op_sel_hi:[1,0,0] neg_lo:[0,0,1] neg_hi:[0,0,1]
	v_mov_b32_e32 v93, v13
	v_pk_add_f32 v[12:13], v[14:15], v[94:95]
	v_pk_add_f32 v[14:15], v[14:15], v[94:95] neg_lo:[0,1] neg_hi:[0,1]
	v_pk_mul_f32 v[84:85], v[14:15], s[86:87] op_sel_hi:[1,0]
	v_pk_fma_f32 v[94:95], v[14:15], s[4:5], v[84:85] op_sel:[0,0,1] op_sel_hi:[1,0,0]
	v_pk_fma_f32 v[14:15], v[14:15], s[4:5], v[84:85] op_sel:[0,0,1] op_sel_hi:[1,0,0] neg_lo:[0,0,1] neg_hi:[0,0,1]
	s_mov_b32 s5, s86
	v_mov_b32_e32 v95, v15
	s_waitcnt lgkmcnt(4)
; template <int R, bool INV> DEV void dft_regs(cf (&v)[R]) {
; #pragma unroll
;     for (int s = R; s >= 2; s >>= 1) {
;         const int h = s >> 1;
; #pragma unroll
;         for (int b = 0; b < R; b += s) {
; #pragma unroll
;             for (int k = 0; k < h; ++k) {
;                 const cf a = v[b + k], c = v[b + k + h];
;                 v[b + k] = a + c;
;                 const cf d = a - c;
;                 const int m = k * (32 / s);
;                 const float wr = tw_cos(m), wi = INV ? tw_sin(m) : -tw_sin(m);
;                 v[b + k + h] = cf{d.x * wr - d.y * wi, d.x * wi + d.y * wr};
;             }
;         }
;     }
; }
	v_pk_add_f32 v[14:15], v[16:17], v[96:97]
	v_pk_add_f32 v[16:17], v[16:17], v[96:97] neg_lo:[0,1] neg_hi:[0,1]
	v_pk_mul_f32 v[84:85], v[16:17], s[16:17] op_sel_hi:[1,0]
	v_pk_fma_f32 v[96:97], v[16:17], s[84:85], v[84:85] op_sel:[0,0,1] op_sel_hi:[1,0,0]
	v_pk_fma_f32 v[16:17], v[16:17], s[84:85], v[84:85] op_sel:[0,0,1] op_sel_hi:[1,0,0] neg_lo:[0,0,1] neg_hi:[0,0,1]
	v_mov_b32_e32 v97, v17
	v_pk_add_f32 v[16:17], v[18:19], v[98:99]
	v_pk_add_f32 v[18:19], v[18:19], v[98:99] neg_lo:[0,1] neg_hi:[0,1]
	v_pk_mul_f32 v[84:85], v[18:19], s[94:95] op_sel_hi:[1,0]
	v_pk_fma_f32 v[98:99], v[18:19], s[82:83], v[84:85] op_sel:[0,0,1] op_sel_hi:[1,0,0]
	v_pk_fma_f32 v[18:19], v[18:19], s[82:83], v[84:85] op_sel:[0,0,1] op_sel_hi:[1,0,0] neg_lo:[0,0,1] neg_hi:[0,0,1]
	s_mov_b32 s83, s94
	v_mov_b32_e32 v99, v19
	s_waitcnt lgkmcnt(3)
	v_pk_add_f32 v[18:19], v[68:69], v[100:101]
	v_pk_add_f32 v[68:69], v[68:69], v[100:101] neg_lo:[0,1] neg_hi:[0,1]
	v_pk_fma_f32 v[84:85], v[68:69], 0, v[68:69] op_sel:[0,0,1] op_sel_hi:[1,0,0]
	v_pk_fma_f32 v[68:69], v[68:69], 0, v[68:69] op_sel:[0,0,1] op_sel_hi:[1,0,0] neg_lo:[0,0,1] neg_hi:[0,0,1]
	v_mov_b32_e32 v85, v69
	v_pk_add_f32 v[68:69], v[70:71], v[102:103]
	v_pk_add_f32 v[70:71], v[70:71], v[102:103] neg_lo:[0,1] neg_hi:[0,1]
	v_pk_mul_f32 v[100:101], v[70:71], s[82:83] op_sel_hi:[0,1]
	v_pk_fma_f32 v[70:71], v[70:71], s[94:95], v[100:101] op_sel:[1,0,0] neg_lo:[0,0,1] neg_hi:[0,0,1]
	s_waitcnt lgkmcnt(2)
	v_pk_add_f32 v[100:101], v[72:73], v[104:105]
	v_pk_add_f32 v[72:73], v[72:73], v[104:105] neg_lo:[0,1] neg_hi:[0,1]
	v_pk_mul_f32 v[102:103], v[72:73], s[84:85] op_sel_hi:[0,1]
	v_pk_fma_f32 v[72:73], v[72:73], s[30:31], v[102:103] op_sel:[1,0,0] neg_lo:[0,0,1] neg_hi:[0,0,1]
	v_pk_add_f32 v[102:103], v[74:75], v[106:107]
	v_pk_add_f32 v[74:75], v[74:75], v[106:107] neg_lo:[0,1] neg_hi:[0,1]
	v_pk_mul_f32 v[104:105], v[74:75], s[4:5] op_sel_hi:[0,1]
	v_pk_fma_f32 v[74:75], v[74:75], s[86:87], v[104:105] op_sel:[1,0,0] neg_lo:[0,0,1] neg_hi:[0,0,1]
	s_waitcnt lgkmcnt(1)
	v_pk_add_f32 v[104:105], v[76:77], v[108:109]
	v_pk_add_f32 v[76:77], v[76:77], v[108:109] neg_lo:[0,1] neg_hi:[0,1]
	v_mul_f32_e32 v106, 0x3f3504f3, v76
	v_pk_fma_f32 v[76:77], v[76:77], s[28:29], v[106:107] op_sel:[1,0,0] op_sel_hi:[1,1,0] neg_lo:[0,0,1] neg_hi:[0,0,1]
	v_pk_add_f32 v[106:107], v[78:79], v[110:111]
	v_pk_add_f32 v[78:79], v[78:79], v[110:111] neg_lo:[0,1] neg_hi:[0,1]
	v_pk_mul_f32 v[108:109], v[78:79], s[2:3] op_sel_hi:[0,1]
	v_pk_fma_f32 v[78:79], v[78:79], s[10:11], v[108:109] op_sel:[1,0,0] neg_lo:[0,0,1] neg_hi:[0,0,1]
	s_waitcnt lgkmcnt(0)
	v_pk_add_f32 v[108:109], v[80:81], v[112:113]
	v_pk_add_f32 v[80:81], v[80:81], v[112:113] neg_lo:[0,1] neg_hi:[0,1]
	v_pk_mul_f32 v[110:111], v[80:81], s[24:25] op_sel_hi:[0,1]
	v_pk_fma_f32 v[80:81], v[80:81], s[34:35], v[110:111] op_sel:[1,0,0] neg_lo:[0,0,1] neg_hi:[0,0,1]
	v_pk_add_f32 v[110:111], v[82:83], v[114:115]
	v_pk_add_f32 v[82:83], v[82:83], v[114:115] neg_lo:[0,1] neg_hi:[0,1]
	v_pk_mul_f32 v[112:113], v[82:83], s[6:7] op_sel_hi:[0,1]
	v_pk_fma_f32 v[82:83], v[82:83], s[8:9], v[112:113] op_sel:[1,0,0] neg_lo:[0,0,1] neg_hi:[0,0,1]
	v_pk_add_f32 v[112:113], v[116:117], v[18:19]
	v_pk_add_f32 v[18:19], v[116:117], v[18:19] neg_lo:[0,1] neg_hi:[0,1]
	v_pk_mul_f32 v[114:115], v[18:19], 0 op_sel_hi:[1,0]
	v_pk_add_f32 v[116:117], v[18:19], v[114:115] op_sel:[0,1] op_sel_hi:[1,0] neg_lo:[0,1] neg_hi:[0,1]
	v_pk_add_f32 v[18:19], v[18:19], v[114:115] op_sel:[0,1] op_sel_hi:[1,0]
	v_mov_b32_e32 v117, v19
	v_pk_add_f32 v[18:19], v[4:5], v[68:69]
	v_pk_add_f32 v[4:5], v[4:5], v[68:69] neg_lo:[0,1] neg_hi:[0,1]
	v_pk_mul_f32 v[68:69], v[4:5], s[84:85] op_sel_hi:[1,0]
	v_pk_fma_f32 v[114:115], v[4:5], s[16:17], v[68:69] op_sel:[0,0,1] op_sel_hi:[1,0,0]
	v_pk_fma_f32 v[4:5], v[4:5], s[16:17], v[68:69] op_sel:[0,0,1] op_sel_hi:[1,0,0] neg_lo:[0,0,1] neg_hi:[0,0,1]
	v_mov_b32_e32 v115, v5
	v_pk_add_f32 v[4:5], v[6:7], v[100:101]
	v_pk_add_f32 v[6:7], v[6:7], v[100:101] neg_lo:[0,1] neg_hi:[0,1]
	v_pk_mul_f32 v[68:69], v[6:7], s[18:19] op_sel_hi:[1,0]
	v_pk_fma_f32 v[100:101], v[6:7], s[18:19], v[68:69] op_sel:[0,0,1] op_sel_hi:[1,0,0]
	v_pk_fma_f32 v[6:7], v[6:7], s[18:19], v[68:69] op_sel_hi:[1,0,0] neg_lo:[0,0,1] neg_hi:[0,0,1]
	v_mov_b32_e32 v101, v7
	v_pk_add_f32 v[6:7], v[8:9], v[102:103]
	v_pk_add_f32 v[8:9], v[8:9], v[102:103] neg_lo:[0,1] neg_hi:[0,1]
	v_pk_mul_f32 v[68:69], v[8:9], s[16:17] op_sel_hi:[1,0]
	v_pk_fma_f32 v[102:103], v[8:9], s[84:85], v[68:69] op_sel:[0,0,1] op_sel_hi:[1,0,0]
	v_pk_fma_f32 v[8:9], v[8:9], s[84:85], v[68:69] op_sel:[0,0,1] op_sel_hi:[1,0,0] neg_lo:[0,0,1] neg_hi:[0,0,1]
	v_mov_b32_e32 v103, v9
	v_pk_add_f32 v[8:9], v[10:11], v[104:105]
	v_pk_add_f32 v[10:11], v[10:11], v[104:105] neg_lo:[0,1] neg_hi:[0,1]
	v_pk_fma_f32 v[68:69], v[10:11], 0, v[10:11] op_sel:[0,0,1] op_sel_hi:[1,0,0]
	v_pk_fma_f32 v[10:11], v[10:11], 0, v[10:11] op_sel:[0,0,1] op_sel_hi:[1,0,0] neg_lo:[0,0,1] neg_hi:[0,0,1]
	v_mov_b32_e32 v69, v11
	v_pk_add_f32 v[10:11], v[12:13], v[106:107]
	v_pk_add_f32 v[12:13], v[12:13], v[106:107] neg_lo:[0,1] neg_hi:[0,1]
	v_pk_mul_f32 v[104:105], v[12:13], s[84:85] op_sel_hi:[0,1]
	v_pk_fma_f32 v[12:13], v[12:13], s[30:31], v[104:105] op_sel:[1,0,0] neg_lo:[0,0,1] neg_hi:[0,0,1]
	v_pk_add_f32 v[104:105], v[14:15], v[108:109]
	v_pk_add_f32 v[14:15], v[14:15], v[108:109] neg_lo:[0,1] neg_hi:[0,1]
	v_mul_f32_e32 v106, 0x3f3504f3, v14
	v_pk_fma_f32 v[14:15], v[14:15], s[28:29], v[106:107] op_sel:[1,0,0] op_sel_hi:[1,1,0] neg_lo:[0,0,1] neg_hi:[0,0,1]
	v_pk_add_f32 v[106:107], v[16:17], v[110:111]
; template <int R, bool INV> DEV void dft_regs(cf (&v)[R]) {
; #pragma unroll
;     for (int s = R; s >= 2; s >>= 1) {
;         const int h = s >> 1;
; #pragma unroll
;         for (int b = 0; b < R; b += s) {
; #pragma unroll
;             for (int k = 0; k < h; ++k) {
;                 const cf a = v[b + k], c = v[b + k + h];
;                 v[b + k] = a + c;
;                 const cf d = a - c;
;                 const int m = k * (32 / s);
;                 const float wr = tw_cos(m), wi = INV ? tw_sin(m) : -tw_sin(m);
;                 v[b + k + h] = cf{d.x * wr - d.y * wi, d.x * wi + d.y * wr};
;             }
;         }
;     }
; }
	v_pk_add_f32 v[16:17], v[16:17], v[110:111] neg_lo:[0,1] neg_hi:[0,1]
	v_pk_mul_f32 v[108:109], v[16:17], s[24:25] op_sel_hi:[0,1]
	v_pk_fma_f32 v[16:17], v[16:17], s[34:35], v[108:109] op_sel:[1,0,0] neg_lo:[0,0,1] neg_hi:[0,0,1]
	v_pk_add_f32 v[108:109], v[118:119], v[84:85]
	v_pk_add_f32 v[84:85], v[118:119], v[84:85] neg_lo:[0,1] neg_hi:[0,1]
	v_pk_mul_f32 v[110:111], v[84:85], 0 op_sel_hi:[1,0]
	v_pk_add_f32 v[118:119], v[84:85], v[110:111] op_sel:[0,1] op_sel_hi:[1,0] neg_lo:[0,1] neg_hi:[0,1]
	v_pk_add_f32 v[84:85], v[84:85], v[110:111] op_sel:[0,1] op_sel_hi:[1,0]
	v_mov_b32_e32 v119, v85
	v_pk_add_f32 v[84:85], v[86:87], v[70:71]
	v_pk_add_f32 v[70:71], v[86:87], v[70:71] neg_lo:[0,1] neg_hi:[0,1]
	v_pk_mul_f32 v[86:87], v[70:71], s[84:85] op_sel_hi:[1,0]
	v_pk_fma_f32 v[110:111], v[70:71], s[16:17], v[86:87] op_sel:[0,0,1] op_sel_hi:[1,0,0]
	v_pk_fma_f32 v[70:71], v[70:71], s[16:17], v[86:87] op_sel:[0,0,1] op_sel_hi:[1,0,0] neg_lo:[0,0,1] neg_hi:[0,0,1]
	v_mov_b32_e32 v111, v71
	v_pk_add_f32 v[70:71], v[88:89], v[72:73]
	v_pk_add_f32 v[72:73], v[88:89], v[72:73] neg_lo:[0,1] neg_hi:[0,1]
	v_pk_mul_f32 v[86:87], v[72:73], s[18:19] op_sel_hi:[1,0]
	v_pk_fma_f32 v[88:89], v[72:73], s[18:19], v[86:87] op_sel:[0,0,1] op_sel_hi:[1,0,0]
	v_pk_fma_f32 v[72:73], v[72:73], s[18:19], v[86:87] op_sel_hi:[1,0,0] neg_lo:[0,0,1] neg_hi:[0,0,1]
	v_mov_b32_e32 v89, v73
	v_pk_add_f32 v[72:73], v[90:91], v[74:75]
	v_pk_add_f32 v[74:75], v[90:91], v[74:75] neg_lo:[0,1] neg_hi:[0,1]
	v_pk_mul_f32 v[86:87], v[74:75], s[16:17] op_sel_hi:[1,0]
	v_pk_fma_f32 v[90:91], v[74:75], s[84:85], v[86:87] op_sel:[0,0,1] op_sel_hi:[1,0,0]
	v_pk_fma_f32 v[74:75], v[74:75], s[84:85], v[86:87] op_sel:[0,0,1] op_sel_hi:[1,0,0] neg_lo:[0,0,1] neg_hi:[0,0,1]
	v_mov_b32_e32 v91, v75
	v_pk_add_f32 v[74:75], v[92:93], v[76:77]
	v_pk_add_f32 v[76:77], v[92:93], v[76:77] neg_lo:[0,1] neg_hi:[0,1]
	v_pk_fma_f32 v[86:87], v[76:77], 0, v[76:77] op_sel:[0,0,1] op_sel_hi:[1,0,0]
	v_pk_fma_f32 v[76:77], v[76:77], 0, v[76:77] op_sel:[0,0,1] op_sel_hi:[1,0,0] neg_lo:[0,0,1] neg_hi:[0,0,1]
	v_mov_b32_e32 v87, v77
	v_pk_add_f32 v[76:77], v[94:95], v[78:79]
	v_pk_add_f32 v[78:79], v[94:95], v[78:79] neg_lo:[0,1] neg_hi:[0,1]
	v_pk_mul_f32 v[92:93], v[78:79], s[84:85] op_sel_hi:[0,1]
	v_pk_fma_f32 v[78:79], v[78:79], s[30:31], v[92:93] op_sel:[1,0,0] neg_lo:[0,0,1] neg_hi:[0,0,1]
	v_pk_add_f32 v[92:93], v[96:97], v[80:81]
	v_pk_add_f32 v[80:81], v[96:97], v[80:81] neg_lo:[0,1] neg_hi:[0,1]
	v_mul_f32_e32 v94, 0x3f3504f3, v80
	v_pk_fma_f32 v[80:81], v[80:81], s[28:29], v[94:95] op_sel:[1,0,0] op_sel_hi:[1,1,0] neg_lo:[0,0,1] neg_hi:[0,0,1]
	v_pk_add_f32 v[94:95], v[98:99], v[82:83]
	v_pk_add_f32 v[82:83], v[98:99], v[82:83] neg_lo:[0,1] neg_hi:[0,1]
	v_pk_mul_f32 v[96:97], v[82:83], s[24:25] op_sel_hi:[0,1]
	v_pk_fma_f32 v[82:83], v[82:83], s[34:35], v[96:97] op_sel:[1,0,0] neg_lo:[0,0,1] neg_hi:[0,0,1]
	v_pk_add_f32 v[96:97], v[112:113], v[8:9]
	v_pk_add_f32 v[8:9], v[112:113], v[8:9] neg_lo:[0,1] neg_hi:[0,1]
	v_pk_mul_f32 v[98:99], v[8:9], 0 op_sel_hi:[1,0]
	v_pk_add_f32 v[112:113], v[8:9], v[98:99] op_sel:[0,1] op_sel_hi:[1,0] neg_lo:[0,1] neg_hi:[0,1]
	v_pk_add_f32 v[8:9], v[8:9], v[98:99] op_sel:[0,1] op_sel_hi:[1,0]
	v_mov_b32_e32 v113, v9
	v_pk_add_f32 v[8:9], v[18:19], v[10:11]
	v_pk_add_f32 v[10:11], v[18:19], v[10:11] neg_lo:[0,1] neg_hi:[0,1]
	v_pk_mul_f32 v[18:19], v[10:11], s[18:19] op_sel_hi:[1,0]
	v_pk_fma_f32 v[98:99], v[10:11], s[18:19], v[18:19] op_sel:[0,0,1] op_sel_hi:[1,0,0]
	v_pk_fma_f32 v[10:11], v[10:11], s[18:19], v[18:19] op_sel_hi:[1,0,0] neg_lo:[0,0,1] neg_hi:[0,0,1]
	v_mov_b32_e32 v99, v11
	v_pk_add_f32 v[10:11], v[4:5], v[104:105]
	v_pk_add_f32 v[4:5], v[4:5], v[104:105] neg_lo:[0,1] neg_hi:[0,1]
	v_pk_fma_f32 v[18:19], v[4:5], 0, v[4:5] op_sel:[0,0,1] op_sel_hi:[1,0,0]
	v_pk_fma_f32 v[4:5], v[4:5], 0, v[4:5] op_sel:[0,0,1] op_sel_hi:[1,0,0] neg_lo:[0,0,1] neg_hi:[0,0,1]
	v_mov_b32_e32 v19, v5
	v_pk_add_f32 v[4:5], v[6:7], v[106:107]
	v_pk_add_f32 v[6:7], v[6:7], v[106:107] neg_lo:[0,1] neg_hi:[0,1]
	v_mul_f32_e32 v104, 0x3f3504f3, v6
	v_pk_fma_f32 v[6:7], v[6:7], s[28:29], v[104:105] op_sel:[1,0,0] op_sel_hi:[1,1,0] neg_lo:[0,0,1] neg_hi:[0,0,1]
	v_pk_add_f32 v[104:105], v[116:117], v[68:69]
	v_pk_add_f32 v[68:69], v[116:117], v[68:69] neg_lo:[0,1] neg_hi:[0,1]
	v_pk_mul_f32 v[106:107], v[68:69], 0 op_sel_hi:[1,0]
	v_pk_add_f32 v[116:117], v[68:69], v[106:107] op_sel:[0,1] op_sel_hi:[1,0] neg_lo:[0,1] neg_hi:[0,1]
	v_pk_add_f32 v[68:69], v[68:69], v[106:107] op_sel:[0,1] op_sel_hi:[1,0]
	v_mov_b32_e32 v117, v69
	v_pk_add_f32 v[68:69], v[114:115], v[12:13]
	v_pk_add_f32 v[12:13], v[114:115], v[12:13] neg_lo:[0,1] neg_hi:[0,1]
	v_pk_mul_f32 v[106:107], v[12:13], s[18:19] op_sel_hi:[1,0]
	v_pk_fma_f32 v[114:115], v[12:13], s[18:19], v[106:107] op_sel:[0,0,1] op_sel_hi:[1,0,0]
	v_pk_fma_f32 v[12:13], v[12:13], s[18:19], v[106:107] op_sel_hi:[1,0,0] neg_lo:[0,0,1] neg_hi:[0,0,1]
	v_mov_b32_e32 v115, v13
	v_pk_add_f32 v[12:13], v[100:101], v[14:15]
	v_pk_add_f32 v[14:15], v[100:101], v[14:15] neg_lo:[0,1] neg_hi:[0,1]
	v_pk_fma_f32 v[100:101], v[14:15], 0, v[14:15] op_sel:[0,0,1] op_sel_hi:[1,0,0]
	v_pk_fma_f32 v[14:15], v[14:15], 0, v[14:15] op_sel:[0,0,1] op_sel_hi:[1,0,0] neg_lo:[0,0,1] neg_hi:[0,0,1]
	v_mov_b32_e32 v101, v15
	v_pk_add_f32 v[14:15], v[102:103], v[16:17]
	v_pk_add_f32 v[16:17], v[102:103], v[16:17] neg_lo:[0,1] neg_hi:[0,1]
	v_mul_f32_e32 v102, 0x3f3504f3, v16
	v_pk_fma_f32 v[16:17], v[16:17], s[28:29], v[102:103] op_sel:[1,0,0] op_sel_hi:[1,1,0] neg_lo:[0,0,1] neg_hi:[0,0,1]
	v_pk_add_f32 v[102:103], v[108:109], v[74:75]
; template <int R, bool INV> DEV void dft_regs(cf (&v)[R]) {
; #pragma unroll
;     for (int s = R; s >= 2; s >>= 1) {
;         const int h = s >> 1;
; #pragma unroll
;         for (int b = 0; b < R; b += s) {
; #pragma unroll
;             for (int k = 0; k < h; ++k) {
;                 const cf a = v[b + k], c = v[b + k + h];
;                 v[b + k] = a + c;
;                 const cf d = a - c;
;                 const int m = k * (32 / s);
;                 const float wr = tw_cos(m), wi = INV ? tw_sin(m) : -tw_sin(m);
;                 v[b + k + h] = cf{d.x * wr - d.y * wi, d.x * wi + d.y * wr};
;             }
;         }
;     }
; }
	v_pk_add_f32 v[74:75], v[108:109], v[74:75] neg_lo:[0,1] neg_hi:[0,1]
	v_pk_mul_f32 v[106:107], v[74:75], 0 op_sel_hi:[1,0]
	v_pk_add_f32 v[108:109], v[74:75], v[106:107] op_sel:[0,1] op_sel_hi:[1,0] neg_lo:[0,1] neg_hi:[0,1]
	v_pk_add_f32 v[74:75], v[74:75], v[106:107] op_sel:[0,1] op_sel_hi:[1,0]
	v_mov_b32_e32 v109, v75
	v_pk_add_f32 v[74:75], v[84:85], v[76:77]
	v_pk_add_f32 v[76:77], v[84:85], v[76:77] neg_lo:[0,1] neg_hi:[0,1]
	v_pk_mul_f32 v[84:85], v[76:77], s[18:19] op_sel_hi:[1,0]
	v_pk_fma_f32 v[106:107], v[76:77], s[18:19], v[84:85] op_sel:[0,0,1] op_sel_hi:[1,0,0]
	v_pk_fma_f32 v[76:77], v[76:77], s[18:19], v[84:85] op_sel_hi:[1,0,0] neg_lo:[0,0,1] neg_hi:[0,0,1]
	v_mov_b32_e32 v107, v77
	v_pk_add_f32 v[76:77], v[70:71], v[92:93]
	v_pk_add_f32 v[70:71], v[70:71], v[92:93] neg_lo:[0,1] neg_hi:[0,1]
	v_pk_fma_f32 v[84:85], v[70:71], 0, v[70:71] op_sel:[0,0,1] op_sel_hi:[1,0,0]
	v_pk_fma_f32 v[70:71], v[70:71], 0, v[70:71] op_sel:[0,0,1] op_sel_hi:[1,0,0] neg_lo:[0,0,1] neg_hi:[0,0,1]
	v_mov_b32_e32 v85, v71
	v_pk_add_f32 v[70:71], v[72:73], v[94:95]
	v_pk_add_f32 v[72:73], v[72:73], v[94:95] neg_lo:[0,1] neg_hi:[0,1]
	v_mul_f32_e32 v92, 0x3f3504f3, v72
	v_pk_fma_f32 v[72:73], v[72:73], s[28:29], v[92:93] op_sel:[1,0,0] op_sel_hi:[1,1,0] neg_lo:[0,0,1] neg_hi:[0,0,1]
	v_pk_add_f32 v[92:93], v[118:119], v[86:87]
	v_pk_add_f32 v[86:87], v[118:119], v[86:87] neg_lo:[0,1] neg_hi:[0,1]
	v_pk_mul_f32 v[94:95], v[86:87], 0 op_sel_hi:[1,0]
	v_pk_add_f32 v[118:119], v[86:87], v[94:95] op_sel:[0,1] op_sel_hi:[1,0] neg_lo:[0,1] neg_hi:[0,1]
	v_pk_add_f32 v[86:87], v[86:87], v[94:95] op_sel:[0,1] op_sel_hi:[1,0]
	v_mov_b32_e32 v119, v87
	v_pk_add_f32 v[86:87], v[110:111], v[78:79]
	v_pk_add_f32 v[78:79], v[110:111], v[78:79] neg_lo:[0,1] neg_hi:[0,1]
	v_pk_mul_f32 v[94:95], v[78:79], s[18:19] op_sel_hi:[1,0]
	v_pk_fma_f32 v[110:111], v[78:79], s[18:19], v[94:95] op_sel:[0,0,1] op_sel_hi:[1,0,0]
	v_pk_fma_f32 v[78:79], v[78:79], s[18:19], v[94:95] op_sel_hi:[1,0,0] neg_lo:[0,0,1] neg_hi:[0,0,1]
	v_mov_b32_e32 v111, v79
	v_pk_add_f32 v[78:79], v[88:89], v[80:81]
	v_pk_add_f32 v[80:81], v[88:89], v[80:81] neg_lo:[0,1] neg_hi:[0,1]
	v_pk_fma_f32 v[88:89], v[80:81], 0, v[80:81] op_sel:[0,0,1] op_sel_hi:[1,0,0]
	v_pk_fma_f32 v[80:81], v[80:81], 0, v[80:81] op_sel:[0,0,1] op_sel_hi:[1,0,0] neg_lo:[0,0,1] neg_hi:[0,0,1]
	v_mov_b32_e32 v89, v81
	v_pk_add_f32 v[80:81], v[90:91], v[82:83]
	v_pk_add_f32 v[82:83], v[90:91], v[82:83] neg_lo:[0,1] neg_hi:[0,1]
	v_mul_f32_e32 v90, 0x3f3504f3, v82
	v_pk_fma_f32 v[82:83], v[82:83], s[28:29], v[90:91] op_sel:[1,0,0] op_sel_hi:[1,1,0] neg_lo:[0,0,1] neg_hi:[0,0,1]
	v_pk_add_f32 v[90:91], v[96:97], v[10:11]
	v_pk_add_f32 v[10:11], v[96:97], v[10:11] neg_lo:[0,1] neg_hi:[0,1]
	v_pk_mul_f32 v[94:95], v[10:11], 0 op_sel_hi:[1,0]
	v_pk_add_f32 v[96:97], v[10:11], v[94:95] op_sel:[0,1] op_sel_hi:[1,0] neg_lo:[0,1] neg_hi:[0,1]
	v_pk_add_f32 v[10:11], v[10:11], v[94:95] op_sel:[0,1] op_sel_hi:[1,0]
	v_mov_b32_e32 v97, v11
	v_pk_add_f32 v[10:11], v[8:9], v[4:5]
	v_pk_add_f32 v[4:5], v[8:9], v[4:5] neg_lo:[0,1] neg_hi:[0,1]
	v_pk_fma_f32 v[8:9], v[4:5], 0, v[4:5] op_sel:[0,0,1] op_sel_hi:[1,0,0]
	v_pk_fma_f32 v[4:5], v[4:5], 0, v[4:5] op_sel:[0,0,1] op_sel_hi:[1,0,0] neg_lo:[0,0,1] neg_hi:[0,0,1]
	v_mov_b32_e32 v9, v5
	v_pk_add_f32 v[4:5], v[112:113], v[18:19]
	v_pk_add_f32 v[18:19], v[112:113], v[18:19] neg_lo:[0,1] neg_hi:[0,1]
	v_pk_mul_f32 v[94:95], v[18:19], 0 op_sel_hi:[1,0]
	v_pk_add_f32 v[112:113], v[18:19], v[94:95] op_sel:[0,1] op_sel_hi:[1,0] neg_lo:[0,1] neg_hi:[0,1]
	v_pk_add_f32 v[18:19], v[18:19], v[94:95] op_sel:[0,1] op_sel_hi:[1,0]
	v_mov_b32_e32 v113, v19
	v_pk_add_f32 v[18:19], v[98:99], v[6:7]
	v_pk_add_f32 v[6:7], v[98:99], v[6:7] neg_lo:[0,1] neg_hi:[0,1]
	v_pk_fma_f32 v[94:95], v[6:7], 0, v[6:7] op_sel:[0,0,1] op_sel_hi:[1,0,0]
	v_pk_fma_f32 v[6:7], v[6:7], 0, v[6:7] op_sel:[0,0,1] op_sel_hi:[1,0,0] neg_lo:[0,0,1] neg_hi:[0,0,1]
	v_mov_b32_e32 v95, v7
	v_pk_add_f32 v[6:7], v[104:105], v[12:13]
	v_pk_add_f32 v[12:13], v[104:105], v[12:13] neg_lo:[0,1] neg_hi:[0,1]
	v_pk_mul_f32 v[98:99], v[12:13], 0 op_sel_hi:[1,0]
	v_pk_add_f32 v[104:105], v[12:13], v[98:99] op_sel:[0,1] op_sel_hi:[1,0] neg_lo:[0,1] neg_hi:[0,1]
	v_pk_add_f32 v[12:13], v[12:13], v[98:99] op_sel:[0,1] op_sel_hi:[1,0]
	v_pk_add_f32 v[98:99], v[116:117], v[100:101] neg_lo:[0,1] neg_hi:[0,1]
	v_mov_b32_e32 v105, v13
	v_pk_add_f32 v[12:13], v[68:69], v[14:15]
	v_pk_add_f32 v[14:15], v[68:69], v[14:15] neg_lo:[0,1] neg_hi:[0,1]
	v_pk_fma_f32 v[68:69], v[14:15], 0, v[14:15] op_sel:[0,0,1] op_sel_hi:[1,0,0]
	v_pk_fma_f32 v[14:15], v[14:15], 0, v[14:15] op_sel:[0,0,1] op_sel_hi:[1,0,0] neg_lo:[0,0,1] neg_hi:[0,0,1]
	v_mov_b32_e32 v69, v15
	v_pk_add_f32 v[14:15], v[116:117], v[100:101]
	v_pk_mul_f32 v[100:101], v[98:99], 0 op_sel_hi:[1,0]
	v_pk_add_f32 v[116:117], v[98:99], v[100:101] op_sel:[0,1] op_sel_hi:[1,0] neg_lo:[0,1] neg_hi:[0,1]
	v_pk_add_f32 v[98:99], v[98:99], v[100:101] op_sel:[0,1] op_sel_hi:[1,0]
	v_mov_b32_e32 v117, v99
	v_pk_add_f32 v[98:99], v[114:115], v[16:17]
	v_pk_add_f32 v[16:17], v[114:115], v[16:17] neg_lo:[0,1] neg_hi:[0,1]
	v_pk_fma_f32 v[100:101], v[16:17], 0, v[16:17] op_sel:[0,0,1] op_sel_hi:[1,0,0]
	v_pk_fma_f32 v[16:17], v[16:17], 0, v[16:17] op_sel:[0,0,1] op_sel_hi:[1,0,0] neg_lo:[0,0,1] neg_hi:[0,0,1]
	v_mov_b32_e32 v101, v17
	v_pk_add_f32 v[16:17], v[102:103], v[76:77]
	v_pk_add_f32 v[76:77], v[102:103], v[76:77] neg_lo:[0,1] neg_hi:[0,1]
	v_pk_mul_f32 v[102:103], v[76:77], 0 op_sel_hi:[1,0]
	v_pk_add_f32 v[114:115], v[76:77], v[102:103] op_sel:[0,1] op_sel_hi:[1,0] neg_lo:[0,1] neg_hi:[0,1]
; template <int R, bool INV> DEV void dft_regs(cf (&v)[R]) {
; #pragma unroll
;     for (int s = R; s >= 2; s >>= 1) {
;         const int h = s >> 1;
; #pragma unroll
;         for (int b = 0; b < R; b += s) {
; #pragma unroll
;             for (int k = 0; k < h; ++k) {
;                 const cf a = v[b + k], c = v[b + k + h];
;                 v[b + k] = a + c;
;                 const cf d = a - c;
;                 const int m = k * (32 / s);
;                 const float wr = tw_cos(m), wi = INV ? tw_sin(m) : -tw_sin(m);
;                 v[b + k + h] = cf{d.x * wr - d.y * wi, d.x * wi + d.y * wr};
;             }
;         }
;     }
; }
	v_pk_add_f32 v[76:77], v[76:77], v[102:103] op_sel:[0,1] op_sel_hi:[1,0]
	v_mov_b32_e32 v115, v77
	v_pk_add_f32 v[76:77], v[74:75], v[70:71]
	v_pk_add_f32 v[70:71], v[74:75], v[70:71] neg_lo:[0,1] neg_hi:[0,1]
	v_pk_fma_f32 v[74:75], v[70:71], 0, v[70:71] op_sel:[0,0,1] op_sel_hi:[1,0,0]
	v_pk_fma_f32 v[70:71], v[70:71], 0, v[70:71] op_sel:[0,0,1] op_sel_hi:[1,0,0] neg_lo:[0,0,1] neg_hi:[0,0,1]
	v_mov_b32_e32 v75, v71
	v_pk_add_f32 v[70:71], v[108:109], v[84:85]
	v_pk_add_f32 v[84:85], v[108:109], v[84:85] neg_lo:[0,1] neg_hi:[0,1]
	v_pk_mul_f32 v[102:103], v[84:85], 0 op_sel_hi:[1,0]
	v_pk_add_f32 v[108:109], v[84:85], v[102:103] op_sel:[0,1] op_sel_hi:[1,0] neg_lo:[0,1] neg_hi:[0,1]
	v_pk_add_f32 v[84:85], v[84:85], v[102:103] op_sel:[0,1] op_sel_hi:[1,0]
	v_mov_b32_e32 v109, v85
	v_pk_add_f32 v[84:85], v[106:107], v[72:73]
	v_pk_add_f32 v[72:73], v[106:107], v[72:73] neg_lo:[0,1] neg_hi:[0,1]
	v_pk_fma_f32 v[102:103], v[72:73], 0, v[72:73] op_sel:[0,0,1] op_sel_hi:[1,0,0]
	v_pk_fma_f32 v[72:73], v[72:73], 0, v[72:73] op_sel:[0,0,1] op_sel_hi:[1,0,0] neg_lo:[0,0,1] neg_hi:[0,0,1]
	v_mov_b32_e32 v103, v73
	v_pk_add_f32 v[72:73], v[92:93], v[78:79]
	v_pk_add_f32 v[78:79], v[92:93], v[78:79] neg_lo:[0,1] neg_hi:[0,1]
	v_pk_mul_f32 v[92:93], v[78:79], 0 op_sel_hi:[1,0]
	v_pk_add_f32 v[106:107], v[78:79], v[92:93] op_sel:[0,1] op_sel_hi:[1,0] neg_lo:[0,1] neg_hi:[0,1]
	v_pk_add_f32 v[78:79], v[78:79], v[92:93] op_sel:[0,1] op_sel_hi:[1,0]
	v_mov_b32_e32 v107, v79
	v_pk_add_f32 v[78:79], v[86:87], v[80:81]
	v_pk_add_f32 v[80:81], v[86:87], v[80:81] neg_lo:[0,1] neg_hi:[0,1]
	v_pk_fma_f32 v[86:87], v[80:81], 0, v[80:81] op_sel:[0,0,1] op_sel_hi:[1,0,0]
	v_pk_fma_f32 v[80:81], v[80:81], 0, v[80:81] op_sel:[0,0,1] op_sel_hi:[1,0,0] neg_lo:[0,0,1] neg_hi:[0,0,1]
	v_mov_b32_e32 v87, v81
	v_pk_add_f32 v[80:81], v[118:119], v[88:89]
	v_pk_add_f32 v[88:89], v[118:119], v[88:89] neg_lo:[0,1] neg_hi:[0,1]
	v_pk_mul_f32 v[92:93], v[88:89], 0 op_sel_hi:[1,0]
	v_pk_add_f32 v[118:119], v[88:89], v[92:93] op_sel:[0,1] op_sel_hi:[1,0] neg_lo:[0,1] neg_hi:[0,1]
	v_pk_add_f32 v[88:89], v[88:89], v[92:93] op_sel:[0,1] op_sel_hi:[1,0]
	v_mov_b32_e32 v119, v89
	v_pk_add_f32 v[88:89], v[110:111], v[82:83]
	v_pk_add_f32 v[82:83], v[110:111], v[82:83] neg_lo:[0,1] neg_hi:[0,1]
	v_pk_fma_f32 v[92:93], v[82:83], 0, v[82:83] op_sel:[0,0,1] op_sel_hi:[1,0,0]
	v_pk_fma_f32 v[82:83], v[82:83], 0, v[82:83] op_sel:[0,0,1] op_sel_hi:[1,0,0] neg_lo:[0,0,1] neg_hi:[0,0,1]
	v_mov_b32_e32 v93, v83
	v_pk_add_f32 v[82:83], v[90:91], v[10:11]
	v_pk_add_f32 v[10:11], v[90:91], v[10:11] neg_lo:[0,1] neg_hi:[0,1]
	v_pk_mul_f32 v[90:91], v[10:11], 0 op_sel_hi:[1,0]
	v_pk_add_f32 v[110:111], v[10:11], v[90:91] op_sel:[0,1] op_sel_hi:[1,0] neg_lo:[0,1] neg_hi:[0,1]
	v_pk_add_f32 v[10:11], v[10:11], v[90:91] op_sel:[0,1] op_sel_hi:[1,0]
	v_mov_b32_e32 v111, v11
	v_pk_add_f32 v[10:11], v[96:97], v[8:9]
	v_pk_add_f32 v[8:9], v[96:97], v[8:9] neg_lo:[0,1] neg_hi:[0,1]
	v_pk_mul_f32 v[90:91], v[8:9], 0 op_sel_hi:[1,0]
	v_pk_add_f32 v[96:97], v[8:9], v[90:91] op_sel:[0,1] op_sel_hi:[1,0] neg_lo:[0,1] neg_hi:[0,1]
	v_pk_add_f32 v[8:9], v[8:9], v[90:91] op_sel:[0,1] op_sel_hi:[1,0]
	v_mov_b32_e32 v97, v9
	v_pk_add_f32 v[8:9], v[4:5], v[18:19]
	v_pk_add_f32 v[4:5], v[4:5], v[18:19] neg_lo:[0,1] neg_hi:[0,1]
	v_pk_mul_f32 v[18:19], v[4:5], 0 op_sel_hi:[1,0]
	v_pk_add_f32 v[90:91], v[4:5], v[18:19] op_sel:[0,1] op_sel_hi:[1,0] neg_lo:[0,1] neg_hi:[0,1]
	v_pk_add_f32 v[4:5], v[4:5], v[18:19] op_sel:[0,1] op_sel_hi:[1,0]
	v_pk_add_f32 v[18:19], v[112:113], v[94:95] neg_lo:[0,1] neg_hi:[0,1]
	v_mov_b32_e32 v91, v5
	v_pk_add_f32 v[4:5], v[112:113], v[94:95]
	v_pk_mul_f32 v[94:95], v[18:19], 0 op_sel_hi:[1,0]
	v_pk_add_f32 v[112:113], v[18:19], v[94:95] op_sel:[0,1] op_sel_hi:[1,0] neg_lo:[0,1] neg_hi:[0,1]
	v_pk_add_f32 v[18:19], v[18:19], v[94:95] op_sel:[0,1] op_sel_hi:[1,0]
	v_mov_b32_e32 v113, v19
	v_pk_add_f32 v[18:19], v[6:7], v[12:13]
	v_pk_add_f32 v[6:7], v[6:7], v[12:13] neg_lo:[0,1] neg_hi:[0,1]
	v_pk_mul_f32 v[12:13], v[6:7], 0 op_sel_hi:[1,0]
	v_pk_add_f32 v[94:95], v[6:7], v[12:13] op_sel:[0,1] op_sel_hi:[1,0] neg_lo:[0,1] neg_hi:[0,1]
	v_pk_add_f32 v[6:7], v[6:7], v[12:13] op_sel:[0,1] op_sel_hi:[1,0]
	v_pk_add_f32 v[12:13], v[104:105], v[68:69] neg_lo:[0,1] neg_hi:[0,1]
	v_mov_b32_e32 v95, v7
	v_pk_add_f32 v[6:7], v[104:105], v[68:69]
	v_pk_mul_f32 v[68:69], v[12:13], 0 op_sel_hi:[1,0]
	v_pk_add_f32 v[104:105], v[12:13], v[68:69] op_sel:[0,1] op_sel_hi:[1,0] neg_lo:[0,1] neg_hi:[0,1]
	v_pk_add_f32 v[12:13], v[12:13], v[68:69] op_sel:[0,1] op_sel_hi:[1,0]
	v_mov_b32_e32 v105, v13
	v_pk_add_f32 v[12:13], v[14:15], v[98:99]
	v_pk_add_f32 v[14:15], v[14:15], v[98:99] neg_lo:[0,1] neg_hi:[0,1]
	v_pk_mul_f32 v[68:69], v[14:15], 0 op_sel_hi:[1,0]
	v_pk_add_f32 v[98:99], v[14:15], v[68:69] op_sel:[0,1] op_sel_hi:[1,0] neg_lo:[0,1] neg_hi:[0,1]
	v_pk_add_f32 v[14:15], v[14:15], v[68:69] op_sel:[0,1] op_sel_hi:[1,0]
	v_pk_add_f32 v[68:69], v[116:117], v[100:101] neg_lo:[0,1] neg_hi:[0,1]
	v_mov_b32_e32 v99, v15
	v_pk_add_f32 v[14:15], v[116:117], v[100:101]
	v_pk_mul_f32 v[100:101], v[68:69], 0 op_sel_hi:[1,0]
	v_pk_add_f32 v[116:117], v[68:69], v[100:101] op_sel:[0,1] op_sel_hi:[1,0] neg_lo:[0,1] neg_hi:[0,1]
	v_pk_add_f32 v[68:69], v[68:69], v[100:101] op_sel:[0,1] op_sel_hi:[1,0]
	v_mov_b32_e32 v117, v69
	v_pk_add_f32 v[68:69], v[16:17], v[76:77]
	v_pk_add_f32 v[16:17], v[16:17], v[76:77] neg_lo:[0,1] neg_hi:[0,1]
	v_pk_mul_f32 v[76:77], v[16:17], 0 op_sel_hi:[1,0]
	v_pk_add_f32 v[100:101], v[16:17], v[76:77] op_sel:[0,1] op_sel_hi:[1,0] neg_lo:[0,1] neg_hi:[0,1]
; #define SINCOSPI(x, s, c) do { const float hx_ = 0.5f * (x); *(s) = __builtin_amdgcn_sinf(hx_); *(c) = __builtin_amdgcn_cosf(hx_); } while (0)
; template <int R, bool INV> DEV void dft_regs(cf (&v)[R]) {
; #pragma unroll
;     for (int s = R; s >= 2; s >>= 1) {
;         const int h = s >> 1;
; #pragma unroll
;         for (int b = 0; b < R; b += s) {
; #pragma unroll
;             for (int k = 0; k < h; ++k) {
;                 const cf a = v[b + k], c = v[b + k + h];
;                 v[b + k] = a + c;
;                 const cf d = a - c;
;                 const int m = k * (32 / s);
;                 const float wr = tw_cos(m), wi = INV ? tw_sin(m) : -tw_sin(m);
;                 v[b + k + h] = cf{d.x * wr - d.y * wi, d.x * wi + d.y * wr};
;             }
;         }
;     }
; }
; DEV void fft_f2(LAS cf* buf, int t8) {
;     ...
;     float sn, cs; SINCOSPI(-(float)(t8 & 15) * (2.0f / 512.0f), &sn, &cs);
;     const cf w = cf{cs, sn}; cf wp = cf{1.f, 0.f};
; #pragma unroll
;     for (int p = 0; p < 32; ++p) { pb[17 * p] = cmul(v[BR32[p]], wp); wp = cmul(wp, w); }
	v_pk_add_f32 v[16:17], v[16:17], v[76:77] op_sel:[0,1] op_sel_hi:[1,0]
	v_mov_b32_e32 v101, v17
	v_pk_add_f32 v[16:17], v[114:115], v[74:75]
	v_pk_add_f32 v[74:75], v[114:115], v[74:75] neg_lo:[0,1] neg_hi:[0,1]
	v_pk_mul_f32 v[76:77], v[74:75], 0 op_sel_hi:[1,0]
	v_pk_add_f32 v[114:115], v[74:75], v[76:77] op_sel:[0,1] op_sel_hi:[1,0] neg_lo:[0,1] neg_hi:[0,1]
	v_pk_add_f32 v[74:75], v[74:75], v[76:77] op_sel:[0,1] op_sel_hi:[1,0]
	v_mov_b32_e32 v115, v75
	v_pk_add_f32 v[74:75], v[70:71], v[84:85]
	v_pk_add_f32 v[70:71], v[70:71], v[84:85] neg_lo:[0,1] neg_hi:[0,1]
	v_pk_mul_f32 v[76:77], v[70:71], 0 op_sel_hi:[1,0]
	v_pk_add_f32 v[84:85], v[70:71], v[76:77] op_sel:[0,1] op_sel_hi:[1,0] neg_lo:[0,1] neg_hi:[0,1]
	v_pk_add_f32 v[70:71], v[70:71], v[76:77] op_sel:[0,1] op_sel_hi:[1,0]
	v_pk_add_f32 v[76:77], v[108:109], v[102:103] neg_lo:[0,1] neg_hi:[0,1]
	v_mov_b32_e32 v85, v71
	v_pk_add_f32 v[70:71], v[108:109], v[102:103]
	v_pk_mul_f32 v[102:103], v[76:77], 0 op_sel_hi:[1,0]
	v_pk_add_f32 v[108:109], v[76:77], v[102:103] op_sel:[0,1] op_sel_hi:[1,0] neg_lo:[0,1] neg_hi:[0,1]
	v_pk_add_f32 v[76:77], v[76:77], v[102:103] op_sel:[0,1] op_sel_hi:[1,0]
	v_mov_b32_e32 v109, v77
	v_pk_add_f32 v[76:77], v[72:73], v[78:79]
	v_pk_add_f32 v[72:73], v[72:73], v[78:79] neg_lo:[0,1] neg_hi:[0,1]
	v_pk_mul_f32 v[78:79], v[72:73], 0 op_sel_hi:[1,0]
	v_pk_add_f32 v[102:103], v[72:73], v[78:79] op_sel:[0,1] op_sel_hi:[1,0] neg_lo:[0,1] neg_hi:[0,1]
	v_pk_add_f32 v[72:73], v[72:73], v[78:79] op_sel:[0,1] op_sel_hi:[1,0]
	v_pk_add_f32 v[78:79], v[106:107], v[86:87] neg_lo:[0,1] neg_hi:[0,1]
	v_mov_b32_e32 v103, v73
	v_pk_add_f32 v[72:73], v[106:107], v[86:87]
	v_pk_mul_f32 v[86:87], v[78:79], 0 op_sel_hi:[1,0]
	v_pk_add_f32 v[106:107], v[78:79], v[86:87] op_sel:[0,1] op_sel_hi:[1,0] neg_lo:[0,1] neg_hi:[0,1]
	v_pk_add_f32 v[78:79], v[78:79], v[86:87] op_sel:[0,1] op_sel_hi:[1,0]
	v_mov_b32_e32 v107, v79
	v_pk_add_f32 v[78:79], v[80:81], v[88:89]
	v_pk_add_f32 v[80:81], v[80:81], v[88:89] neg_lo:[0,1] neg_hi:[0,1]
	v_pk_mul_f32 v[86:87], v[80:81], 0 op_sel_hi:[1,0]
	v_pk_add_f32 v[88:89], v[80:81], v[86:87] op_sel:[0,1] op_sel_hi:[1,0] neg_lo:[0,1] neg_hi:[0,1]
	v_pk_add_f32 v[80:81], v[80:81], v[86:87] op_sel:[0,1] op_sel_hi:[1,0]
	v_pk_add_f32 v[86:87], v[118:119], v[92:93] neg_lo:[0,1] neg_hi:[0,1]
	v_mov_b32_e32 v89, v81
	v_pk_add_f32 v[80:81], v[118:119], v[92:93]
	v_pk_mul_f32 v[92:93], v[86:87], 0 op_sel_hi:[1,0]
	v_pk_add_f32 v[118:119], v[86:87], v[92:93] op_sel:[0,1] op_sel_hi:[1,0] neg_lo:[0,1] neg_hi:[0,1]
	v_pk_add_f32 v[86:87], v[86:87], v[92:93] op_sel:[0,1] op_sel_hi:[1,0]
	v_pk_mul_f32 v[92:93], v[82:83], v[66:67] op_sel:[1,1] op_sel_hi:[1,0] neg_lo:[1,0]
	v_pk_fma_f32 v[82:83], v[82:83], v[66:67], v[92:93] op_sel_hi:[0,1,1]
	s_nop 0
	v_mov_b32_e32 v119, v87
	v_sin_f32_e32 v87, v3
	v_cos_f32_e32 v86, v3
	v_pk_mul_f32 v[92:93], v[66:67], v[86:87] op_sel:[1,1] op_sel_hi:[1,0] neg_lo:[1,0]
	v_pk_fma_f32 v[120:121], v[66:67], v[86:87], v[92:93] op_sel_hi:[0,1,1]
	v_pk_mul_f32 v[92:93], v[68:69], v[120:121] op_sel:[1,1] op_sel_hi:[1,0] neg_lo:[1,0]
	v_pk_fma_f32 v[68:69], v[68:69], v[120:121], v[92:93] op_sel_hi:[0,1,1]
	ds_write2_b64 v2, v[82:83], v[68:69] offset1:17
	v_pk_mul_f32 v[68:69], v[120:121], v[86:87] op_sel:[1,1] op_sel_hi:[1,0] neg_lo:[1,0]
	v_pk_fma_f32 v[82:83], v[120:121], v[86:87], v[68:69] op_sel_hi:[0,1,1]
	v_pk_mul_f32 v[68:69], v[18:19], v[82:83] op_sel:[1,1] op_sel_hi:[1,0] neg_lo:[1,0]
	v_pk_fma_f32 v[18:19], v[18:19], v[82:83], v[68:69] op_sel_hi:[0,1,1]
	s_nop 0
	v_pk_mul_f32 v[68:69], v[82:83], v[86:87] op_sel:[1,1] op_sel_hi:[1,0] neg_lo:[1,0]
	v_pk_fma_f32 v[82:83], v[82:83], v[86:87], v[68:69] op_sel_hi:[0,1,1]
	v_pk_mul_f32 v[92:93], v[76:77], v[82:83] op_sel:[1,1] op_sel_hi:[1,0] neg_lo:[1,0]
	v_pk_fma_f32 v[68:69], v[76:77], v[82:83], v[92:93] op_sel_hi:[0,1,1]
	ds_write2_b64 v2, v[18:19], v[68:69] offset0:34 offset1:51
	v_pk_mul_f32 v[18:19], v[82:83], v[86:87] op_sel:[1,1] op_sel_hi:[1,0] neg_lo:[1,0]
	v_pk_fma_f32 v[68:69], v[82:83], v[86:87], v[18:19] op_sel_hi:[0,1,1]
	v_pk_mul_f32 v[18:19], v[8:9], v[68:69] op_sel:[1,1] op_sel_hi:[1,0] neg_lo:[1,0]
	v_pk_fma_f32 v[8:9], v[8:9], v[68:69], v[18:19] op_sel_hi:[0,1,1]
	s_nop 0
	v_pk_mul_f32 v[18:19], v[68:69], v[86:87] op_sel:[1,1] op_sel_hi:[1,0] neg_lo:[1,0]
	v_pk_fma_f32 v[68:69], v[68:69], v[86:87], v[18:19] op_sel_hi:[0,1,1]
	v_pk_mul_f32 v[76:77], v[74:75], v[68:69] op_sel:[1,1] op_sel_hi:[1,0] neg_lo:[1,0]
	v_pk_fma_f32 v[18:19], v[74:75], v[68:69], v[76:77] op_sel_hi:[0,1,1]
	ds_write2_b64 v2, v[8:9], v[18:19] offset0:68 offset1:85
	v_pk_mul_f32 v[8:9], v[68:69], v[86:87] op_sel:[1,1] op_sel_hi:[1,0] neg_lo:[1,0]
	v_pk_fma_f32 v[18:19], v[68:69], v[86:87], v[8:9] op_sel_hi:[0,1,1]
	v_pk_mul_f32 v[68:69], v[12:13], v[18:19] op_sel:[1,1] op_sel_hi:[1,0] neg_lo:[1,0]
	v_pk_fma_f32 v[8:9], v[12:13], v[18:19], v[68:69] op_sel_hi:[0,1,1]
	v_pk_mul_f32 v[12:13], v[18:19], v[86:87] op_sel:[1,1] op_sel_hi:[1,0] neg_lo:[1,0]
	v_pk_fma_f32 v[18:19], v[18:19], v[86:87], v[12:13] op_sel_hi:[0,1,1]
	v_pk_mul_f32 v[68:69], v[78:79], v[18:19] op_sel:[1,1] op_sel_hi:[1,0] neg_lo:[1,0]
	v_pk_fma_f32 v[12:13], v[78:79], v[18:19], v[68:69] op_sel_hi:[0,1,1]
	ds_write2_b64 v2, v[8:9], v[12:13] offset0:102 offset1:119
	v_pk_mul_f32 v[8:9], v[18:19], v[86:87] op_sel:[1,1] op_sel_hi:[1,0] neg_lo:[1,0]
	v_pk_fma_f32 v[12:13], v[18:19], v[86:87], v[8:9] op_sel_hi:[0,1,1]
	v_pk_mul_f32 v[18:19], v[10:11], v[12:13] op_sel:[1,1] op_sel_hi:[1,0] neg_lo:[1,0]
	v_pk_fma_f32 v[8:9], v[10:11], v[12:13], v[18:19] op_sel_hi:[0,1,1]
	v_pk_mul_f32 v[10:11], v[12:13], v[86:87] op_sel:[1,1] op_sel_hi:[1,0] neg_lo:[1,0]
; #define SINCOSPI(x, s, c) do { const float hx_ = 0.5f * (x); *(s) = __builtin_amdgcn_sinf(hx_); *(c) = __builtin_amdgcn_cosf(hx_); } while (0)
; DEV void fft_f2(LAS cf* buf, int t8) {
;     ...
;     float sn, cs; SINCOSPI(-(float)(t8 & 15) * (2.0f / 512.0f), &sn, &cs);
;     const cf w = cf{cs, sn}; cf wp = cf{1.f, 0.f};
; #pragma unroll
;     for (int p = 0; p < 32; ++p) { pb[17 * p] = cmul(v[BR32[p]], wp); wp = cmul(wp, w); }
	v_pk_fma_f32 v[12:13], v[12:13], v[86:87], v[10:11] op_sel_hi:[0,1,1]
	v_pk_mul_f32 v[18:19], v[16:17], v[12:13] op_sel:[1,1] op_sel_hi:[1,0] neg_lo:[1,0]
	v_pk_fma_f32 v[10:11], v[16:17], v[12:13], v[18:19] op_sel_hi:[0,1,1]
	ds_write2_b64 v2, v[8:9], v[10:11] offset0:136 offset1:153
	v_pk_mul_f32 v[8:9], v[12:13], v[86:87] op_sel:[1,1] op_sel_hi:[1,0] neg_lo:[1,0]
	v_pk_fma_f32 v[10:11], v[12:13], v[86:87], v[8:9] op_sel_hi:[0,1,1]
	v_pk_mul_f32 v[8:9], v[6:7], v[10:11] op_sel:[1,1] op_sel_hi:[1,0] neg_lo:[1,0]
	v_pk_fma_f32 v[6:7], v[6:7], v[10:11], v[8:9] op_sel_hi:[0,1,1]
	s_nop 0
	v_pk_mul_f32 v[8:9], v[10:11], v[86:87] op_sel:[1,1] op_sel_hi:[1,0] neg_lo:[1,0]
	v_pk_fma_f32 v[10:11], v[10:11], v[86:87], v[8:9] op_sel_hi:[0,1,1]
	v_pk_mul_f32 v[12:13], v[72:73], v[10:11] op_sel:[1,1] op_sel_hi:[1,0] neg_lo:[1,0]
	v_pk_fma_f32 v[8:9], v[72:73], v[10:11], v[12:13] op_sel_hi:[0,1,1]
	ds_write2_b64 v2, v[6:7], v[8:9] offset0:170 offset1:187
	v_pk_mul_f32 v[6:7], v[10:11], v[86:87] op_sel:[1,1] op_sel_hi:[1,0] neg_lo:[1,0]
	v_pk_fma_f32 v[8:9], v[10:11], v[86:87], v[6:7] op_sel_hi:[0,1,1]
	v_pk_mul_f32 v[6:7], v[4:5], v[8:9] op_sel:[1,1] op_sel_hi:[1,0] neg_lo:[1,0]
	v_pk_fma_f32 v[4:5], v[4:5], v[8:9], v[6:7] op_sel_hi:[0,1,1]
	s_nop 0
	v_pk_mul_f32 v[6:7], v[8:9], v[86:87] op_sel:[1,1] op_sel_hi:[1,0] neg_lo:[1,0]
	v_pk_fma_f32 v[8:9], v[8:9], v[86:87], v[6:7] op_sel_hi:[0,1,1]
	v_pk_mul_f32 v[10:11], v[70:71], v[8:9] op_sel:[1,1] op_sel_hi:[1,0] neg_lo:[1,0]
	v_pk_fma_f32 v[6:7], v[70:71], v[8:9], v[10:11] op_sel_hi:[0,1,1]
	ds_write2_b64 v2, v[4:5], v[6:7] offset0:204 offset1:221
	v_pk_mul_f32 v[4:5], v[8:9], v[86:87] op_sel:[1,1] op_sel_hi:[1,0] neg_lo:[1,0]
	v_pk_fma_f32 v[6:7], v[8:9], v[86:87], v[4:5] op_sel_hi:[0,1,1]
	v_pk_mul_f32 v[8:9], v[14:15], v[6:7] op_sel:[1,1] op_sel_hi:[1,0] neg_lo:[1,0]
	v_pk_fma_f32 v[4:5], v[14:15], v[6:7], v[8:9] op_sel_hi:[0,1,1]
	s_nop 0
	v_pk_mul_f32 v[8:9], v[6:7], v[86:87] op_sel:[1,1] op_sel_hi:[1,0] neg_lo:[1,0]
	v_pk_fma_f32 v[6:7], v[6:7], v[86:87], v[8:9] op_sel_hi:[0,1,1]
	v_pk_mul_f32 v[10:11], v[80:81], v[6:7] op_sel:[1,1] op_sel_hi:[1,0] neg_lo:[1,0]
	v_pk_fma_f32 v[8:9], v[80:81], v[6:7], v[10:11] op_sel_hi:[0,1,1]
	ds_write2_b64 v2, v[4:5], v[8:9] offset0:238 offset1:255
	v_pk_mul_f32 v[2:3], v[6:7], v[86:87] op_sel:[1,1] op_sel_hi:[1,0] neg_lo:[1,0]
	v_pk_fma_f32 v[4:5], v[6:7], v[86:87], v[2:3] op_sel_hi:[0,1,1]
	v_pk_mul_f32 v[6:7], v[110:111], v[4:5] op_sel:[1,1] op_sel_hi:[1,0] neg_lo:[1,0]
	v_pk_fma_f32 v[2:3], v[110:111], v[4:5], v[6:7] op_sel_hi:[0,1,1]
	s_nop 0
	v_pk_mul_f32 v[6:7], v[4:5], v[86:87] op_sel:[1,1] op_sel_hi:[1,0] neg_lo:[1,0]
	v_pk_fma_f32 v[4:5], v[4:5], v[86:87], v[6:7] op_sel_hi:[0,1,1]
	v_pk_mul_f32 v[8:9], v[100:101], v[4:5] op_sel:[1,1] op_sel_hi:[1,0] neg_lo:[1,0]
	v_pk_fma_f32 v[6:7], v[100:101], v[4:5], v[8:9] op_sel_hi:[0,1,1]
	ds_write2_b64 v0, v[2:3], v[6:7] offset0:16 offset1:33
	v_pk_mul_f32 v[2:3], v[4:5], v[86:87] op_sel:[1,1] op_sel_hi:[1,0] neg_lo:[1,0]
	v_pk_fma_f32 v[4:5], v[4:5], v[86:87], v[2:3] op_sel_hi:[0,1,1]
	v_pk_mul_f32 v[6:7], v[94:95], v[4:5] op_sel:[1,1] op_sel_hi:[1,0] neg_lo:[1,0]
	v_pk_fma_f32 v[2:3], v[94:95], v[4:5], v[6:7] op_sel_hi:[0,1,1]
	s_nop 0
	v_pk_mul_f32 v[6:7], v[4:5], v[86:87] op_sel:[1,1] op_sel_hi:[1,0] neg_lo:[1,0]
	v_pk_fma_f32 v[4:5], v[4:5], v[86:87], v[6:7] op_sel_hi:[0,1,1]
	v_pk_mul_f32 v[8:9], v[102:103], v[4:5] op_sel:[1,1] op_sel_hi:[1,0] neg_lo:[1,0]
	v_pk_fma_f32 v[6:7], v[102:103], v[4:5], v[8:9] op_sel_hi:[0,1,1]
	ds_write2_b64 v0, v[2:3], v[6:7] offset0:50 offset1:67
	v_pk_mul_f32 v[2:3], v[4:5], v[86:87] op_sel:[1,1] op_sel_hi:[1,0] neg_lo:[1,0]
	v_pk_fma_f32 v[4:5], v[4:5], v[86:87], v[2:3] op_sel_hi:[0,1,1]
	v_pk_mul_f32 v[6:7], v[90:91], v[4:5] op_sel:[1,1] op_sel_hi:[1,0] neg_lo:[1,0]
	v_pk_fma_f32 v[2:3], v[90:91], v[4:5], v[6:7] op_sel_hi:[0,1,1]
	s_nop 0
	v_pk_mul_f32 v[6:7], v[4:5], v[86:87] op_sel:[1,1] op_sel_hi:[1,0] neg_lo:[1,0]
	v_pk_fma_f32 v[4:5], v[4:5], v[86:87], v[6:7] op_sel_hi:[0,1,1]
	v_pk_mul_f32 v[8:9], v[84:85], v[4:5] op_sel:[1,1] op_sel_hi:[1,0] neg_lo:[1,0]
	v_pk_fma_f32 v[6:7], v[84:85], v[4:5], v[8:9] op_sel_hi:[0,1,1]
	ds_write2_b64 v0, v[2:3], v[6:7] offset0:84 offset1:101
	v_pk_mul_f32 v[2:3], v[4:5], v[86:87] op_sel:[1,1] op_sel_hi:[1,0] neg_lo:[1,0]
	v_pk_fma_f32 v[4:5], v[4:5], v[86:87], v[2:3] op_sel_hi:[0,1,1]
	v_pk_mul_f32 v[6:7], v[98:99], v[4:5] op_sel:[1,1] op_sel_hi:[1,0] neg_lo:[1,0]
	v_pk_fma_f32 v[2:3], v[98:99], v[4:5], v[6:7] op_sel_hi:[0,1,1]
	s_nop 0
	v_pk_mul_f32 v[6:7], v[4:5], v[86:87] op_sel:[1,1] op_sel_hi:[1,0] neg_lo:[1,0]
	v_pk_fma_f32 v[4:5], v[4:5], v[86:87], v[6:7] op_sel_hi:[0,1,1]
	v_pk_mul_f32 v[8:9], v[88:89], v[4:5] op_sel:[1,1] op_sel_hi:[1,0] neg_lo:[1,0]
	v_pk_fma_f32 v[6:7], v[88:89], v[4:5], v[8:9] op_sel_hi:[0,1,1]
	ds_write2_b64 v0, v[2:3], v[6:7] offset0:118 offset1:135
	v_pk_mul_f32 v[2:3], v[4:5], v[86:87] op_sel:[1,1] op_sel_hi:[1,0] neg_lo:[1,0]
	v_pk_fma_f32 v[4:5], v[4:5], v[86:87], v[2:3] op_sel_hi:[0,1,1]
	v_pk_mul_f32 v[6:7], v[96:97], v[4:5] op_sel:[1,1] op_sel_hi:[1,0] neg_lo:[1,0]
	v_pk_fma_f32 v[2:3], v[96:97], v[4:5], v[6:7] op_sel_hi:[0,1,1]
	s_nop 0
	v_pk_mul_f32 v[6:7], v[4:5], v[86:87] op_sel:[1,1] op_sel_hi:[1,0] neg_lo:[1,0]
	v_pk_fma_f32 v[4:5], v[4:5], v[86:87], v[6:7] op_sel_hi:[0,1,1]
	v_pk_mul_f32 v[8:9], v[114:115], v[4:5] op_sel:[1,1] op_sel_hi:[1,0] neg_lo:[1,0]
	v_pk_fma_f32 v[6:7], v[114:115], v[4:5], v[8:9] op_sel_hi:[0,1,1]
	ds_write2_b64 v0, v[2:3], v[6:7] offset0:152 offset1:169
	v_pk_mul_f32 v[2:3], v[4:5], v[86:87] op_sel:[1,1] op_sel_hi:[1,0] neg_lo:[1,0]
; #define LAS __attribute__((address_space(3)))
; #define SINCOSPI(x, s, c) do { const float hx_ = 0.5f * (x); *(s) = __builtin_amdgcn_sinf(hx_); *(c) = __builtin_amdgcn_cosf(hx_); } while (0)
; DEV void fft_f2(LAS cf* buf, int t8) {
;     ...
;     float sn, cs; SINCOSPI(-(float)(t8 & 15) * (2.0f / 512.0f), &sn, &cs);
;     const cf w = cf{cs, sn}; cf wp = cf{1.f, 0.f};
; #pragma unroll
;     for (int p = 0; p < 32; ++p) { pb[17 * p] = cmul(v[BR32[p]], wp); wp = cmul(wp, w); }
; DEV void fft_midx2(LAS cf* buf0, LAS cf* buf1, const unsigned* Kp, int blk) {
;     const int base = 16 * blk;
;     LAS cf* p0 = buf0 + 17 * blk; LAS cf* p1 = buf1 + 17 * blk;
;     cf v[16], u[16];
; #pragma unroll
;     for (int q = 0; q < 16; ++q) { v[q] = p0[q]; u[q] = p1[q]; }
;     dft_regs<16, false>(v); dft_regs<16, false>(u);
	v_pk_fma_f32 v[4:5], v[4:5], v[86:87], v[2:3] op_sel_hi:[0,1,1]
	v_pk_mul_f32 v[6:7], v[104:105], v[4:5] op_sel:[1,1] op_sel_hi:[1,0] neg_lo:[1,0]
	v_pk_fma_f32 v[2:3], v[104:105], v[4:5], v[6:7] op_sel_hi:[0,1,1]
	s_nop 0
	v_pk_mul_f32 v[6:7], v[4:5], v[86:87] op_sel:[1,1] op_sel_hi:[1,0] neg_lo:[1,0]
	v_pk_fma_f32 v[4:5], v[4:5], v[86:87], v[6:7] op_sel_hi:[0,1,1]
	v_pk_mul_f32 v[8:9], v[106:107], v[4:5] op_sel:[1,1] op_sel_hi:[1,0] neg_lo:[1,0]
	v_pk_fma_f32 v[6:7], v[106:107], v[4:5], v[8:9] op_sel_hi:[0,1,1]
	ds_write2_b64 v0, v[2:3], v[6:7] offset0:186 offset1:203
	v_pk_mul_f32 v[2:3], v[4:5], v[86:87] op_sel:[1,1] op_sel_hi:[1,0] neg_lo:[1,0]
	v_pk_fma_f32 v[4:5], v[4:5], v[86:87], v[2:3] op_sel_hi:[0,1,1]
	v_pk_mul_f32 v[6:7], v[112:113], v[4:5] op_sel:[1,1] op_sel_hi:[1,0] neg_lo:[1,0]
	v_pk_fma_f32 v[2:3], v[112:113], v[4:5], v[6:7] op_sel_hi:[0,1,1]
	s_nop 0
	v_pk_mul_f32 v[6:7], v[4:5], v[86:87] op_sel:[1,1] op_sel_hi:[1,0] neg_lo:[1,0]
	v_pk_fma_f32 v[4:5], v[4:5], v[86:87], v[6:7] op_sel_hi:[0,1,1]
	v_pk_mul_f32 v[8:9], v[108:109], v[4:5] op_sel:[1,1] op_sel_hi:[1,0] neg_lo:[1,0]
	v_pk_fma_f32 v[6:7], v[108:109], v[4:5], v[8:9] op_sel_hi:[0,1,1]
	ds_write2_b64 v0, v[2:3], v[6:7] offset0:220 offset1:237
	v_pk_mul_f32 v[2:3], v[4:5], v[86:87] op_sel:[1,1] op_sel_hi:[1,0] neg_lo:[1,0]
	v_pk_fma_f32 v[4:5], v[4:5], v[86:87], v[2:3] op_sel_hi:[0,1,1]
	v_pk_mul_f32 v[6:7], v[116:117], v[4:5] op_sel:[1,1] op_sel_hi:[1,0] neg_lo:[1,0]
	v_pk_fma_f32 v[2:3], v[116:117], v[4:5], v[6:7] op_sel_hi:[0,1,1]
	s_nop 0
	v_pk_mul_f32 v[6:7], v[4:5], v[86:87] op_sel:[1,1] op_sel_hi:[1,0] neg_lo:[1,0]
	v_pk_fma_f32 v[4:5], v[4:5], v[86:87], v[6:7] op_sel_hi:[0,1,1]
	v_pk_mul_f32 v[6:7], v[118:119], v[4:5] op_sel:[1,1] op_sel_hi:[1,0] neg_lo:[1,0]
	v_pk_fma_f32 v[4:5], v[118:119], v[4:5], v[6:7] op_sel_hi:[0,1,1]
	ds_write2_b64 v1, v[2:3], v[4:5] offset0:126 offset1:143
	s_waitcnt lgkmcnt(0)
	s_barrier
	ds_read2_b64 v[68:71], v161 offset1:1
	ds_read2_b64 v[8:11], v162 offset1:1
	ds_read2_b64 v[72:75], v161 offset0:2 offset1:3
	ds_read2_b64 v[12:15], v162 offset0:2 offset1:3
	ds_read2_b64 v[76:79], v161 offset0:4 offset1:5
	ds_read2_b64 v[0:3], v162 offset0:4 offset1:5
	ds_read2_b64 v[80:83], v161 offset0:6 offset1:7
	ds_read2_b64 v[4:7], v162 offset0:6 offset1:7
	ds_read2_b64 v[84:87], v161 offset0:8 offset1:9
	ds_read2_b64 v[100:103], v162 offset0:8 offset1:9
	ds_read2_b64 v[88:91], v161 offset0:10 offset1:11
	ds_read2_b64 v[104:107], v162 offset0:10 offset1:11
	ds_read2_b64 v[92:95], v161 offset0:12 offset1:13
	ds_read2_b64 v[16:19], v162 offset0:12 offset1:13
	ds_read2_b64 v[96:99], v161 offset0:14 offset1:15
	ds_read2_b64 v[108:111], v162 offset0:14 offset1:15
	s_waitcnt lgkmcnt(7)
	v_pk_add_f32 v[112:113], v[68:69], v[84:85]
	v_pk_add_f32 v[68:69], v[68:69], v[84:85] neg_lo:[0,1] neg_hi:[0,1]
	v_pk_mul_f32 v[84:85], v[68:69], 0 op_sel_hi:[1,0]
	v_pk_add_f32 v[114:115], v[68:69], v[84:85] op_sel:[0,1] op_sel_hi:[1,0] neg_lo:[0,1] neg_hi:[0,1]
	v_pk_add_f32 v[68:69], v[68:69], v[84:85] op_sel:[0,1] op_sel_hi:[1,0]
	v_mov_b32_e32 v115, v69
	v_pk_add_f32 v[68:69], v[70:71], v[86:87]
	v_pk_add_f32 v[70:71], v[70:71], v[86:87] neg_lo:[0,1] neg_hi:[0,1]
	v_pk_mul_f32 v[84:85], v[70:71], s[84:85] op_sel_hi:[1,0]
	v_pk_fma_f32 v[86:87], v[70:71], s[16:17], v[84:85] op_sel:[0,0,1] op_sel_hi:[1,0,0]
	v_pk_fma_f32 v[70:71], v[70:71], s[16:17], v[84:85] op_sel:[0,0,1] op_sel_hi:[1,0,0] neg_lo:[0,0,1] neg_hi:[0,0,1]
	v_mov_b32_e32 v87, v71
	s_waitcnt lgkmcnt(5)
	v_pk_add_f32 v[70:71], v[72:73], v[88:89]
	v_pk_add_f32 v[72:73], v[72:73], v[88:89] neg_lo:[0,1] neg_hi:[0,1]
	v_pk_mul_f32 v[84:85], v[72:73], s[18:19] op_sel_hi:[1,0]
	v_pk_fma_f32 v[88:89], v[72:73], s[18:19], v[84:85] op_sel:[0,0,1] op_sel_hi:[1,0,0]
	v_pk_fma_f32 v[72:73], v[72:73], s[18:19], v[84:85] op_sel_hi:[1,0,0] neg_lo:[0,0,1] neg_hi:[0,0,1]
	v_pk_add_f32 v[84:85], v[74:75], v[90:91]
	v_pk_add_f32 v[74:75], v[74:75], v[90:91] neg_lo:[0,1] neg_hi:[0,1]
	v_mov_b32_e32 v89, v73
	v_pk_mul_f32 v[90:91], v[74:75], s[16:17] op_sel_hi:[1,0]
	v_pk_fma_f32 v[116:117], v[74:75], s[84:85], v[90:91] op_sel:[0,0,1] op_sel_hi:[1,0,0]
	v_pk_fma_f32 v[74:75], v[74:75], s[84:85], v[90:91] op_sel:[0,0,1] op_sel_hi:[1,0,0] neg_lo:[0,0,1] neg_hi:[0,0,1]
	v_mov_b32_e32 v117, v75
	s_waitcnt lgkmcnt(3)
	v_pk_add_f32 v[74:75], v[76:77], v[92:93]
	v_pk_add_f32 v[76:77], v[76:77], v[92:93] neg_lo:[0,1] neg_hi:[0,1]
	v_pk_fma_f32 v[90:91], v[76:77], 0, v[76:77] op_sel:[0,0,1] op_sel_hi:[1,0,0]
	v_pk_fma_f32 v[76:77], v[76:77], 0, v[76:77] op_sel:[0,0,1] op_sel_hi:[1,0,0] neg_lo:[0,0,1] neg_hi:[0,0,1]
	v_mov_b32_e32 v91, v77
	v_pk_add_f32 v[76:77], v[78:79], v[94:95]
	v_pk_add_f32 v[78:79], v[78:79], v[94:95] neg_lo:[0,1] neg_hi:[0,1]
	s_waitcnt lgkmcnt(1)
; template <int R, bool INV> DEV void dft_regs(cf (&v)[R]) {
; #pragma unroll
;     for (int s = R; s >= 2; s >>= 1) {
;         const int h = s >> 1;
; #pragma unroll
;         for (int b = 0; b < R; b += s) {
; #pragma unroll
;             for (int k = 0; k < h; ++k) {
;                 const cf a = v[b + k], c = v[b + k + h];
;                 v[b + k] = a + c;
;                 const cf d = a - c;
;                 const int m = k * (32 / s);
;                 const float wr = tw_cos(m), wi = INV ? tw_sin(m) : -tw_sin(m);
;                 v[b + k + h] = cf{d.x * wr - d.y * wi, d.x * wi + d.y * wr};
;             }
;         }
;     }
; }
	v_pk_add_f32 v[94:95], v[82:83], v[98:99]
	v_pk_mul_f32 v[92:93], v[78:79], s[84:85] op_sel_hi:[0,1]
	v_pk_add_f32 v[82:83], v[82:83], v[98:99] neg_lo:[0,1] neg_hi:[0,1]
	v_pk_fma_f32 v[78:79], v[78:79], s[30:31], v[92:93] op_sel:[1,0,0] neg_lo:[0,0,1] neg_hi:[0,0,1]
	v_pk_add_f32 v[92:93], v[80:81], v[96:97]
	v_pk_add_f32 v[80:81], v[80:81], v[96:97] neg_lo:[0,1] neg_hi:[0,1]
	v_pk_mul_f32 v[96:97], v[82:83], s[24:25] op_sel_hi:[0,1]
	v_pk_fma_f32 v[82:83], v[82:83], s[34:35], v[96:97] op_sel:[1,0,0] neg_lo:[0,0,1] neg_hi:[0,0,1]
	v_pk_add_f32 v[96:97], v[112:113], v[74:75]
	v_pk_add_f32 v[74:75], v[112:113], v[74:75] neg_lo:[0,1] neg_hi:[0,1]
	v_mul_f32_e32 v72, 0x3f3504f3, v80
	v_pk_mul_f32 v[98:99], v[74:75], 0 op_sel_hi:[1,0]
	v_pk_fma_f32 v[80:81], v[80:81], s[28:29], v[72:73] op_sel:[1,0,0] op_sel_hi:[1,1,0] neg_lo:[0,0,1] neg_hi:[0,0,1]
	v_pk_add_f32 v[112:113], v[74:75], v[98:99] op_sel:[0,1] op_sel_hi:[1,0] neg_lo:[0,1] neg_hi:[0,1]
	v_pk_add_f32 v[74:75], v[74:75], v[98:99] op_sel:[0,1] op_sel_hi:[1,0]
	v_pk_add_f32 v[72:73], v[88:89], v[80:81]
	v_mov_b32_e32 v113, v75
	v_pk_add_f32 v[74:75], v[68:69], v[76:77]
	v_pk_add_f32 v[68:69], v[68:69], v[76:77] neg_lo:[0,1] neg_hi:[0,1]
	v_pk_mul_f32 v[76:77], v[68:69], s[18:19] op_sel_hi:[1,0]
	v_pk_fma_f32 v[98:99], v[68:69], s[18:19], v[76:77] op_sel:[0,0,1] op_sel_hi:[1,0,0]
	v_pk_fma_f32 v[68:69], v[68:69], s[18:19], v[76:77] op_sel_hi:[1,0,0] neg_lo:[0,0,1] neg_hi:[0,0,1]
	v_pk_add_f32 v[76:77], v[70:71], v[92:93]
	v_pk_add_f32 v[70:71], v[70:71], v[92:93] neg_lo:[0,1] neg_hi:[0,1]
	v_mov_b32_e32 v99, v69
	v_pk_fma_f32 v[92:93], v[70:71], 0, v[70:71] op_sel:[0,0,1] op_sel_hi:[1,0,0]
	v_pk_fma_f32 v[70:71], v[70:71], 0, v[70:71] op_sel:[0,0,1] op_sel_hi:[1,0,0] neg_lo:[0,0,1] neg_hi:[0,0,1]
	v_mov_b32_e32 v93, v71
	v_pk_add_f32 v[70:71], v[84:85], v[94:95]
	v_pk_add_f32 v[84:85], v[84:85], v[94:95] neg_lo:[0,1] neg_hi:[0,1]
	v_pk_add_f32 v[94:95], v[114:115], v[90:91]
	v_pk_add_f32 v[90:91], v[114:115], v[90:91] neg_lo:[0,1] neg_hi:[0,1]
	v_mul_f32_e32 v68, 0x3f3504f3, v84
	v_pk_mul_f32 v[114:115], v[90:91], 0 op_sel_hi:[1,0]
	v_pk_fma_f32 v[84:85], v[84:85], s[28:29], v[68:69] op_sel:[1,0,0] op_sel_hi:[1,1,0] neg_lo:[0,0,1] neg_hi:[0,0,1]
	v_pk_add_f32 v[118:119], v[90:91], v[114:115] op_sel:[0,1] op_sel_hi:[1,0] neg_lo:[0,1] neg_hi:[0,1]
	v_pk_add_f32 v[90:91], v[90:91], v[114:115] op_sel:[0,1] op_sel_hi:[1,0]
	v_mov_b32_e32 v119, v91
	v_pk_add_f32 v[90:91], v[86:87], v[78:79]
	v_pk_add_f32 v[78:79], v[86:87], v[78:79] neg_lo:[0,1] neg_hi:[0,1]
	v_pk_mul_f32 v[86:87], v[78:79], s[18:19] op_sel_hi:[1,0]
	v_pk_fma_f32 v[114:115], v[78:79], s[18:19], v[86:87] op_sel:[0,0,1] op_sel_hi:[1,0,0]
	v_pk_fma_f32 v[78:79], v[78:79], s[18:19], v[86:87] op_sel_hi:[1,0,0] neg_lo:[0,0,1] neg_hi:[0,0,1]
	v_mov_b32_e32 v115, v79
	v_pk_add_f32 v[78:79], v[88:89], v[80:81] neg_lo:[0,1] neg_hi:[0,1]
	v_pk_add_f32 v[88:89], v[96:97], v[76:77]
	v_pk_add_f32 v[76:77], v[96:97], v[76:77] neg_lo:[0,1] neg_hi:[0,1]
	v_pk_fma_f32 v[80:81], v[78:79], 0, v[78:79] op_sel:[0,0,1] op_sel_hi:[1,0,0]
	v_pk_mul_f32 v[86:87], v[76:77], 0 op_sel_hi:[1,0]
	v_pk_fma_f32 v[78:79], v[78:79], 0, v[78:79] op_sel:[0,0,1] op_sel_hi:[1,0,0] neg_lo:[0,0,1] neg_hi:[0,0,1]
	v_pk_add_f32 v[96:97], v[76:77], v[86:87] op_sel:[0,1] op_sel_hi:[1,0] neg_lo:[0,1] neg_hi:[0,1]
	v_pk_add_f32 v[76:77], v[76:77], v[86:87] op_sel:[0,1] op_sel_hi:[1,0]
	v_mov_b32_e32 v81, v79
	v_mov_b32_e32 v97, v77
	v_pk_add_f32 v[76:77], v[74:75], v[70:71]
	v_pk_add_f32 v[70:71], v[74:75], v[70:71] neg_lo:[0,1] neg_hi:[0,1]
	v_pk_add_f32 v[78:79], v[116:117], v[82:83]
	v_pk_fma_f32 v[74:75], v[70:71], 0, v[70:71] op_sel:[0,0,1] op_sel_hi:[1,0,0]
	v_pk_fma_f32 v[70:71], v[70:71], 0, v[70:71] op_sel:[0,0,1] op_sel_hi:[1,0,0] neg_lo:[0,0,1] neg_hi:[0,0,1]
	v_pk_add_f32 v[82:83], v[116:117], v[82:83] neg_lo:[0,1] neg_hi:[0,1]
	v_mov_b32_e32 v75, v71
	v_pk_add_f32 v[70:71], v[112:113], v[92:93] neg_lo:[0,1] neg_hi:[0,1]
	v_pk_add_f32 v[116:117], v[112:113], v[92:93]
	v_pk_mul_f32 v[86:87], v[70:71], 0 op_sel_hi:[1,0]
	v_mul_f32_e32 v68, 0x3f3504f3, v82
	v_pk_add_f32 v[92:93], v[70:71], v[86:87] op_sel:[0,1] op_sel_hi:[1,0] neg_lo:[0,1] neg_hi:[0,1]
	v_pk_add_f32 v[70:71], v[70:71], v[86:87] op_sel:[0,1] op_sel_hi:[1,0]
	v_pk_fma_f32 v[82:83], v[82:83], s[28:29], v[68:69] op_sel:[1,0,0] op_sel_hi:[1,1,0] neg_lo:[0,0,1] neg_hi:[0,0,1]
	v_mov_b32_e32 v93, v71
	v_pk_add_f32 v[70:71], v[98:99], v[84:85] neg_lo:[0,1] neg_hi:[0,1]
	v_pk_add_f32 v[68:69], v[98:99], v[84:85]
	v_pk_fma_f32 v[98:99], v[70:71], 0, v[70:71] op_sel:[0,0,1] op_sel_hi:[1,0,0]
	v_pk_fma_f32 v[70:71], v[70:71], 0, v[70:71] op_sel:[0,0,1] op_sel_hi:[1,0,0] neg_lo:[0,0,1] neg_hi:[0,0,1]
	v_pk_add_f32 v[112:113], v[94:95], v[72:73]
	v_mov_b32_e32 v99, v71
	v_pk_add_f32 v[70:71], v[94:95], v[72:73] neg_lo:[0,1] neg_hi:[0,1]
	v_pk_add_f32 v[122:123], v[118:119], v[80:81]
	v_pk_mul_f32 v[72:73], v[70:71], 0 op_sel_hi:[1,0]
	v_pk_add_f32 v[124:125], v[114:115], v[82:83]
	v_pk_add_f32 v[120:121], v[70:71], v[72:73] op_sel:[0,1] op_sel_hi:[1,0] neg_lo:[0,1] neg_hi:[0,1]
	v_pk_add_f32 v[70:71], v[70:71], v[72:73] op_sel:[0,1] op_sel_hi:[1,0]
	v_pk_add_f32 v[72:73], v[90:91], v[78:79]
	v_mov_b32_e32 v121, v71
	v_pk_add_f32 v[70:71], v[90:91], v[78:79] neg_lo:[0,1] neg_hi:[0,1]
	v_pk_add_f32 v[86:87], v[88:89], v[76:77]
	v_pk_fma_f32 v[78:79], v[70:71], 0, v[70:71] op_sel:[0,0,1] op_sel_hi:[1,0,0]
	v_pk_fma_f32 v[70:71], v[70:71], 0, v[70:71] op_sel:[0,0,1] op_sel_hi:[1,0,0] neg_lo:[0,0,1] neg_hi:[0,0,1]
	v_pk_add_f32 v[94:95], v[112:113], v[72:73]
	v_mov_b32_e32 v79, v71
; template <int R, bool INV> DEV void dft_regs(cf (&v)[R]) {
; #pragma unroll
;     for (int s = R; s >= 2; s >>= 1) {
;         const int h = s >> 1;
; #pragma unroll
;         for (int b = 0; b < R; b += s) {
; #pragma unroll
;             for (int k = 0; k < h; ++k) {
;                 const cf a = v[b + k], c = v[b + k + h];
;                 v[b + k] = a + c;
;                 const cf d = a - c;
;                 const int m = k * (32 / s);
;                 const float wr = tw_cos(m), wi = INV ? tw_sin(m) : -tw_sin(m);
;                 v[b + k + h] = cf{d.x * wr - d.y * wi, d.x * wi + d.y * wr};
;             }
;         }
;     }
; }
	v_pk_add_f32 v[70:71], v[118:119], v[80:81] neg_lo:[0,1] neg_hi:[0,1]
	v_pk_add_f32 v[72:73], v[112:113], v[72:73] neg_lo:[0,1] neg_hi:[0,1]
	v_pk_mul_f32 v[80:81], v[70:71], 0 op_sel_hi:[1,0]
	v_pk_add_f32 v[84:85], v[92:93], v[98:99]
	v_pk_add_f32 v[118:119], v[70:71], v[80:81] op_sel:[0,1] op_sel_hi:[1,0] neg_lo:[0,1] neg_hi:[0,1]
	v_pk_add_f32 v[70:71], v[70:71], v[80:81] op_sel:[0,1] op_sel_hi:[1,0]
	v_pk_add_f32 v[112:113], v[8:9], v[100:101]
	v_mov_b32_e32 v119, v71
	v_pk_add_f32 v[70:71], v[114:115], v[82:83] neg_lo:[0,1] neg_hi:[0,1]
	v_pk_add_f32 v[82:83], v[96:97], v[74:75]
	v_pk_fma_f32 v[114:115], v[70:71], 0, v[70:71] op_sel:[0,0,1] op_sel_hi:[1,0,0]
	v_pk_fma_f32 v[70:71], v[70:71], 0, v[70:71] op_sel:[0,0,1] op_sel_hi:[1,0,0] neg_lo:[0,0,1] neg_hi:[0,0,1]
	v_pk_add_f32 v[74:75], v[96:97], v[74:75] neg_lo:[0,1] neg_hi:[0,1]
	v_mov_b32_e32 v115, v71
	v_pk_add_f32 v[70:71], v[88:89], v[76:77] neg_lo:[0,1] neg_hi:[0,1]
	v_pk_add_f32 v[88:89], v[116:117], v[68:69]
	v_pk_mul_f32 v[80:81], v[70:71], 0 op_sel_hi:[1,0]
	v_pk_add_f32 v[68:69], v[116:117], v[68:69] neg_lo:[0,1] neg_hi:[0,1]
	v_pk_add_f32 v[76:77], v[70:71], v[80:81] op_sel:[0,1] op_sel_hi:[1,0] neg_lo:[0,1] neg_hi:[0,1]
	v_pk_add_f32 v[70:71], v[70:71], v[80:81] op_sel:[0,1] op_sel_hi:[1,0]
	v_pk_mul_f32 v[80:81], v[74:75], 0 op_sel_hi:[1,0]
	v_mov_b32_e32 v77, v71
	v_pk_add_f32 v[70:71], v[74:75], v[80:81] op_sel:[0,1] op_sel_hi:[1,0] neg_lo:[0,1] neg_hi:[0,1]
	v_pk_add_f32 v[74:75], v[74:75], v[80:81] op_sel:[0,1] op_sel_hi:[1,0]
	v_pk_mul_f32 v[80:81], v[68:69], 0 op_sel_hi:[1,0]
	v_mov_b32_e32 v71, v75
	v_pk_add_f32 v[74:75], v[68:69], v[80:81] op_sel:[0,1] op_sel_hi:[1,0] neg_lo:[0,1] neg_hi:[0,1]
	v_pk_add_f32 v[68:69], v[68:69], v[80:81] op_sel:[0,1] op_sel_hi:[1,0]
	v_pk_add_f32 v[80:81], v[92:93], v[98:99] neg_lo:[0,1] neg_hi:[0,1]
	v_mov_b32_e32 v75, v69
	v_pk_mul_f32 v[90:91], v[80:81], 0 op_sel_hi:[1,0]
	v_pk_add_f32 v[8:9], v[8:9], v[100:101] neg_lo:[0,1] neg_hi:[0,1]
	v_pk_add_f32 v[68:69], v[80:81], v[90:91] op_sel:[0,1] op_sel_hi:[1,0] neg_lo:[0,1] neg_hi:[0,1]
	v_pk_add_f32 v[80:81], v[80:81], v[90:91] op_sel:[0,1] op_sel_hi:[1,0]
	v_pk_mul_f32 v[90:91], v[72:73], 0 op_sel_hi:[1,0]
	v_mov_b32_e32 v69, v81
	v_pk_add_f32 v[80:81], v[72:73], v[90:91] op_sel:[0,1] op_sel_hi:[1,0] neg_lo:[0,1] neg_hi:[0,1]
	v_pk_add_f32 v[72:73], v[72:73], v[90:91] op_sel:[0,1] op_sel_hi:[1,0]
	v_pk_add_f32 v[90:91], v[120:121], v[78:79]
	v_pk_add_f32 v[78:79], v[120:121], v[78:79] neg_lo:[0,1] neg_hi:[0,1]
	v_mov_b32_e32 v81, v73
	v_pk_mul_f32 v[92:93], v[78:79], 0 op_sel_hi:[1,0]
	v_pk_mul_f32 v[100:101], v[8:9], 0 op_sel_hi:[1,0]
	v_pk_add_f32 v[72:73], v[78:79], v[92:93] op_sel:[0,1] op_sel_hi:[1,0] neg_lo:[0,1] neg_hi:[0,1]
	v_pk_add_f32 v[78:79], v[78:79], v[92:93] op_sel:[0,1] op_sel_hi:[1,0]
	v_pk_add_f32 v[92:93], v[122:123], v[124:125] neg_lo:[0,1] neg_hi:[0,1]
	v_mov_b32_e32 v73, v79
	v_pk_mul_f32 v[98:99], v[92:93], 0 op_sel_hi:[1,0]
	v_pk_add_f32 v[96:97], v[122:123], v[124:125]
	v_pk_add_f32 v[78:79], v[92:93], v[98:99] op_sel:[0,1] op_sel_hi:[1,0] neg_lo:[0,1] neg_hi:[0,1]
	v_pk_add_f32 v[92:93], v[92:93], v[98:99] op_sel:[0,1] op_sel_hi:[1,0]
	v_pk_add_f32 v[98:99], v[118:119], v[114:115] neg_lo:[0,1] neg_hi:[0,1]
	v_mov_b32_e32 v79, v93
	v_pk_add_f32 v[92:93], v[118:119], v[114:115]
	v_pk_add_f32 v[114:115], v[8:9], v[100:101] op_sel:[0,1] op_sel_hi:[1,0] neg_lo:[0,1] neg_hi:[0,1]
	v_pk_add_f32 v[8:9], v[8:9], v[100:101] op_sel:[0,1] op_sel_hi:[1,0]
	v_mov_b32_e32 v115, v9
	v_pk_add_f32 v[8:9], v[10:11], v[102:103]
	v_pk_add_f32 v[10:11], v[10:11], v[102:103] neg_lo:[0,1] neg_hi:[0,1]
	v_pk_mul_f32 v[100:101], v[10:11], s[84:85] op_sel_hi:[1,0]
	v_pk_fma_f32 v[102:103], v[10:11], s[16:17], v[100:101] op_sel:[0,0,1] op_sel_hi:[1,0,0]
	v_pk_fma_f32 v[10:11], v[10:11], s[16:17], v[100:101] op_sel:[0,0,1] op_sel_hi:[1,0,0] neg_lo:[0,0,1] neg_hi:[0,0,1]
	v_mov_b32_e32 v103, v11
	v_pk_add_f32 v[10:11], v[12:13], v[104:105]
	v_pk_add_f32 v[12:13], v[12:13], v[104:105] neg_lo:[0,1] neg_hi:[0,1]
	v_pk_mul_f32 v[100:101], v[12:13], s[18:19] op_sel_hi:[1,0]
	v_pk_fma_f32 v[104:105], v[12:13], s[18:19], v[100:101] op_sel:[0,0,1] op_sel_hi:[1,0,0]
	v_pk_fma_f32 v[12:13], v[12:13], s[18:19], v[100:101] op_sel_hi:[1,0,0] neg_lo:[0,0,1] neg_hi:[0,0,1]
	v_mov_b32_e32 v105, v13
	v_pk_add_f32 v[12:13], v[14:15], v[106:107]
	v_pk_add_f32 v[14:15], v[14:15], v[106:107] neg_lo:[0,1] neg_hi:[0,1]
	v_pk_mul_f32 v[100:101], v[14:15], s[16:17] op_sel_hi:[1,0]
	v_pk_fma_f32 v[106:107], v[14:15], s[84:85], v[100:101] op_sel:[0,0,1] op_sel_hi:[1,0,0]
	v_pk_fma_f32 v[14:15], v[14:15], s[84:85], v[100:101] op_sel:[0,0,1] op_sel_hi:[1,0,0] neg_lo:[0,0,1] neg_hi:[0,0,1]
	v_mov_b32_e32 v107, v15
	v_pk_add_f32 v[14:15], v[0:1], v[16:17]
	v_pk_add_f32 v[0:1], v[0:1], v[16:17] neg_lo:[0,1] neg_hi:[0,1]
	v_pk_fma_f32 v[16:17], v[0:1], 0, v[0:1] op_sel:[0,0,1] op_sel_hi:[1,0,0]
	v_pk_fma_f32 v[0:1], v[0:1], 0, v[0:1] op_sel:[0,0,1] op_sel_hi:[1,0,0] neg_lo:[0,0,1] neg_hi:[0,0,1]
	v_mov_b32_e32 v17, v1
	v_pk_add_f32 v[0:1], v[2:3], v[18:19]
	v_pk_add_f32 v[2:3], v[2:3], v[18:19] neg_lo:[0,1] neg_hi:[0,1]
	v_pk_mul_f32 v[18:19], v[2:3], s[84:85] op_sel_hi:[0,1]
	v_pk_fma_f32 v[2:3], v[2:3], s[30:31], v[18:19] op_sel:[1,0,0] neg_lo:[0,0,1] neg_hi:[0,0,1]
	s_waitcnt lgkmcnt(0)
; template <int R, bool INV> DEV void dft_regs(cf (&v)[R]) {
; #pragma unroll
;     for (int s = R; s >= 2; s >>= 1) {
;         const int h = s >> 1;
; #pragma unroll
;         for (int b = 0; b < R; b += s) {
; #pragma unroll
;             for (int k = 0; k < h; ++k) {
;                 const cf a = v[b + k], c = v[b + k + h];
;                 v[b + k] = a + c;
;                 const cf d = a - c;
;                 const int m = k * (32 / s);
;                 const float wr = tw_cos(m), wi = INV ? tw_sin(m) : -tw_sin(m);
;                 v[b + k + h] = cf{d.x * wr - d.y * wi, d.x * wi + d.y * wr};
;             }
;         }
;     }
; }
	v_pk_add_f32 v[18:19], v[4:5], v[108:109]
	v_pk_add_f32 v[4:5], v[4:5], v[108:109] neg_lo:[0,1] neg_hi:[0,1]
	v_mul_f32_e32 v100, 0x3f3504f3, v4
	v_pk_fma_f32 v[4:5], v[4:5], s[28:29], v[100:101] op_sel:[1,0,0] op_sel_hi:[1,1,0] neg_lo:[0,0,1] neg_hi:[0,0,1]
	v_pk_add_f32 v[100:101], v[6:7], v[110:111]
	v_pk_add_f32 v[6:7], v[6:7], v[110:111] neg_lo:[0,1] neg_hi:[0,1]
	v_pk_mul_f32 v[108:109], v[6:7], s[24:25] op_sel_hi:[0,1]
	v_pk_fma_f32 v[6:7], v[6:7], s[34:35], v[108:109] op_sel:[1,0,0] neg_lo:[0,0,1] neg_hi:[0,0,1]
	v_pk_add_f32 v[108:109], v[112:113], v[14:15]
	v_pk_add_f32 v[14:15], v[112:113], v[14:15] neg_lo:[0,1] neg_hi:[0,1]
	v_pk_mul_f32 v[110:111], v[14:15], 0 op_sel_hi:[1,0]
	v_pk_add_f32 v[112:113], v[14:15], v[110:111] op_sel:[0,1] op_sel_hi:[1,0] neg_lo:[0,1] neg_hi:[0,1]
	v_pk_add_f32 v[14:15], v[14:15], v[110:111] op_sel:[0,1] op_sel_hi:[1,0]
	v_mov_b32_e32 v113, v15
	v_pk_add_f32 v[14:15], v[8:9], v[0:1]
	v_pk_add_f32 v[0:1], v[8:9], v[0:1] neg_lo:[0,1] neg_hi:[0,1]
	v_pk_mul_f32 v[8:9], v[0:1], s[18:19] op_sel_hi:[1,0]
	v_pk_fma_f32 v[110:111], v[0:1], s[18:19], v[8:9] op_sel:[0,0,1] op_sel_hi:[1,0,0]
	v_pk_fma_f32 v[0:1], v[0:1], s[18:19], v[8:9] op_sel_hi:[1,0,0] neg_lo:[0,0,1] neg_hi:[0,0,1]
	v_pk_add_f32 v[8:9], v[10:11], v[18:19] neg_lo:[0,1] neg_hi:[0,1]
	v_mov_b32_e32 v111, v1
	v_pk_add_f32 v[0:1], v[10:11], v[18:19]
	v_pk_fma_f32 v[10:11], v[8:9], 0, v[8:9] op_sel:[0,0,1] op_sel_hi:[1,0,0]
	v_pk_fma_f32 v[8:9], v[8:9], 0, v[8:9] op_sel:[0,0,1] op_sel_hi:[1,0,0] neg_lo:[0,0,1] neg_hi:[0,0,1]
	v_mov_b32_e32 v11, v9
	v_pk_add_f32 v[8:9], v[12:13], v[100:101]
	v_pk_add_f32 v[12:13], v[12:13], v[100:101] neg_lo:[0,1] neg_hi:[0,1]
	v_mul_f32_e32 v18, 0x3f3504f3, v12
	v_pk_fma_f32 v[12:13], v[12:13], s[28:29], v[18:19] op_sel:[1,0,0] op_sel_hi:[1,1,0] neg_lo:[0,0,1] neg_hi:[0,0,1]
	v_pk_add_f32 v[18:19], v[114:115], v[16:17]
	v_pk_add_f32 v[16:17], v[114:115], v[16:17] neg_lo:[0,1] neg_hi:[0,1]
	v_pk_mul_f32 v[100:101], v[16:17], 0 op_sel_hi:[1,0]
	v_pk_add_f32 v[114:115], v[16:17], v[100:101] op_sel:[0,1] op_sel_hi:[1,0] neg_lo:[0,1] neg_hi:[0,1]
	v_pk_add_f32 v[16:17], v[16:17], v[100:101] op_sel:[0,1] op_sel_hi:[1,0]
	v_mov_b32_e32 v115, v17
	v_pk_add_f32 v[16:17], v[102:103], v[2:3]
	v_pk_add_f32 v[2:3], v[102:103], v[2:3] neg_lo:[0,1] neg_hi:[0,1]
	v_pk_mul_f32 v[100:101], v[2:3], s[18:19] op_sel_hi:[1,0]
	v_pk_fma_f32 v[102:103], v[2:3], s[18:19], v[100:101] op_sel:[0,0,1] op_sel_hi:[1,0,0]
	v_pk_fma_f32 v[2:3], v[2:3], s[18:19], v[100:101] op_sel_hi:[1,0,0] neg_lo:[0,0,1] neg_hi:[0,0,1]
	v_mov_b32_e32 v103, v3
	v_pk_add_f32 v[2:3], v[104:105], v[4:5]
	v_pk_add_f32 v[4:5], v[104:105], v[4:5] neg_lo:[0,1] neg_hi:[0,1]
	v_pk_fma_f32 v[100:101], v[4:5], 0, v[4:5] op_sel:[0,0,1] op_sel_hi:[1,0,0]
	v_pk_fma_f32 v[4:5], v[4:5], 0, v[4:5] op_sel:[0,0,1] op_sel_hi:[1,0,0] neg_lo:[0,0,1] neg_hi:[0,0,1]
	v_mov_b32_e32 v101, v5
	v_pk_add_f32 v[4:5], v[106:107], v[6:7]
	v_pk_add_f32 v[6:7], v[106:107], v[6:7] neg_lo:[0,1] neg_hi:[0,1]
	v_mul_f32_e32 v104, 0x3f3504f3, v6
	v_pk_fma_f32 v[6:7], v[6:7], s[28:29], v[104:105] op_sel:[1,0,0] op_sel_hi:[1,1,0] neg_lo:[0,0,1] neg_hi:[0,0,1]
	v_pk_add_f32 v[104:105], v[108:109], v[0:1]
	v_pk_add_f32 v[0:1], v[108:109], v[0:1] neg_lo:[0,1] neg_hi:[0,1]
	v_pk_add_f32 v[166:167], v[102:103], v[6:7]
	v_pk_mul_f32 v[106:107], v[0:1], 0 op_sel_hi:[1,0]
	v_pk_add_f32 v[6:7], v[102:103], v[6:7] neg_lo:[0,1] neg_hi:[0,1]
	v_pk_add_f32 v[108:109], v[0:1], v[106:107] op_sel:[0,1] op_sel_hi:[1,0] neg_lo:[0,1] neg_hi:[0,1]
	v_pk_add_f32 v[0:1], v[0:1], v[106:107] op_sel:[0,1] op_sel_hi:[1,0]
	v_pk_fma_f32 v[168:169], v[6:7], 0, v[6:7] op_sel:[0,0,1] op_sel_hi:[1,0,0]
	v_mov_b32_e32 v109, v1
	v_pk_add_f32 v[0:1], v[14:15], v[8:9]
	v_pk_add_f32 v[8:9], v[14:15], v[8:9] neg_lo:[0,1] neg_hi:[0,1]
	v_pk_fma_f32 v[6:7], v[6:7], 0, v[6:7] op_sel:[0,0,1] op_sel_hi:[1,0,0] neg_lo:[0,0,1] neg_hi:[0,0,1]
	v_pk_fma_f32 v[14:15], v[8:9], 0, v[8:9] op_sel:[0,0,1] op_sel_hi:[1,0,0]
	v_pk_fma_f32 v[8:9], v[8:9], 0, v[8:9] op_sel:[0,0,1] op_sel_hi:[1,0,0] neg_lo:[0,0,1] neg_hi:[0,0,1]
	v_pk_add_f32 v[122:123], v[104:105], v[0:1]
	v_mov_b32_e32 v15, v9
	v_pk_add_f32 v[8:9], v[112:113], v[10:11]
	v_pk_add_f32 v[10:11], v[112:113], v[10:11] neg_lo:[0,1] neg_hi:[0,1]
	v_pk_add_f32 v[0:1], v[104:105], v[0:1] neg_lo:[0,1] neg_hi:[0,1]
	v_pk_mul_f32 v[106:107], v[10:11], 0 op_sel_hi:[1,0]
	v_mov_b32_e32 v169, v7
	v_pk_add_f32 v[116:117], v[10:11], v[106:107] op_sel:[0,1] op_sel_hi:[1,0] neg_lo:[0,1] neg_hi:[0,1]
	v_pk_add_f32 v[10:11], v[10:11], v[106:107] op_sel:[0,1] op_sel_hi:[1,0]
	v_pk_mul_f32 v[6:7], v[0:1], 0 op_sel_hi:[1,0]
	v_mov_b32_e32 v117, v11
	v_pk_add_f32 v[10:11], v[110:111], v[12:13]
	v_pk_add_f32 v[12:13], v[110:111], v[12:13] neg_lo:[0,1] neg_hi:[0,1]
	v_pk_add_f32 v[106:107], v[0:1], v[6:7] op_sel:[0,1] op_sel_hi:[1,0] neg_lo:[0,1] neg_hi:[0,1]
	v_pk_fma_f32 v[110:111], v[12:13], 0, v[12:13] op_sel:[0,0,1] op_sel_hi:[1,0,0]
	v_pk_fma_f32 v[12:13], v[12:13], 0, v[12:13] op_sel:[0,0,1] op_sel_hi:[1,0,0] neg_lo:[0,0,1] neg_hi:[0,0,1]
	v_pk_add_f32 v[0:1], v[0:1], v[6:7] op_sel:[0,1] op_sel_hi:[1,0]
	v_mov_b32_e32 v111, v13
	v_pk_add_f32 v[12:13], v[18:19], v[2:3]
	v_pk_add_f32 v[2:3], v[18:19], v[2:3] neg_lo:[0,1] neg_hi:[0,1]
	v_mov_b32_e32 v107, v1
	v_pk_mul_f32 v[18:19], v[2:3], 0 op_sel_hi:[1,0]
	v_pk_add_f32 v[0:1], v[108:109], v[14:15] neg_lo:[0,1] neg_hi:[0,1]
	v_pk_add_f32 v[124:125], v[2:3], v[18:19] op_sel:[0,1] op_sel_hi:[1,0] neg_lo:[0,1] neg_hi:[0,1]
	v_pk_add_f32 v[2:3], v[2:3], v[18:19] op_sel:[0,1] op_sel_hi:[1,0]
	v_pk_mul_f32 v[6:7], v[0:1], 0 op_sel_hi:[1,0]
	v_mov_b32_e32 v125, v3
; DEV cf kunpack(unsigned w) { return cf{U2F(w << 16), U2F(w & 0xffff0000u)}; }
; DEV void fft_midx2(LAS cf* buf0, LAS cf* buf1, const unsigned* Kp, int blk) {
;     ...
;     dft_regs<16, false>(v); dft_regs<16, false>(u);
;     cf w[16], x[16];
;     u32x4 kw[4];
; #pragma unroll
;     for (int j = 0; j < 4; ++j) kw[j] = *(const u32x4*)(Kp + base + 4 * j);
; #pragma unroll
;     for (int p = 0; p < 16; ++p) { const cf k = kunpack(kw[p >> 2][p & 3]); w[p] = cmul(v[BR16[p]], k); x[p] = cmul(u[BR16[p]], k); }
	v_pk_add_f32 v[2:3], v[16:17], v[4:5]
	v_pk_add_f32 v[4:5], v[16:17], v[4:5] neg_lo:[0,1] neg_hi:[0,1]
	v_pk_add_f32 v[16:17], v[114:115], v[100:101] neg_lo:[0,1] neg_hi:[0,1]
	v_pk_fma_f32 v[164:165], v[4:5], 0, v[4:5] op_sel:[0,0,1] op_sel_hi:[1,0,0]
	v_pk_fma_f32 v[4:5], v[4:5], 0, v[4:5] op_sel:[0,0,1] op_sel_hi:[1,0,0] neg_lo:[0,0,1] neg_hi:[0,0,1]
	v_pk_mul_f32 v[18:19], v[16:17], 0 op_sel_hi:[1,0]
	v_mov_b32_e32 v165, v5
	v_pk_add_f32 v[4:5], v[114:115], v[100:101]
	v_pk_add_f32 v[100:101], v[16:17], v[18:19] op_sel:[0,1] op_sel_hi:[1,0] neg_lo:[0,1] neg_hi:[0,1]
	v_pk_add_f32 v[16:17], v[16:17], v[18:19] op_sel:[0,1] op_sel_hi:[1,0]
	v_pk_add_f32 v[18:19], v[0:1], v[6:7] op_sel:[0,1] op_sel_hi:[1,0] neg_lo:[0,1] neg_hi:[0,1]
	v_pk_add_f32 v[0:1], v[0:1], v[6:7] op_sel:[0,1] op_sel_hi:[1,0]
	v_mov_b32_e32 v101, v17
	v_mov_b32_e32 v19, v1
	v_pk_add_f32 v[0:1], v[8:9], v[10:11] neg_lo:[0,1] neg_hi:[0,1]
	v_pk_add_f32 v[126:127], v[12:13], v[2:3]
	v_pk_mul_f32 v[6:7], v[0:1], 0 op_sel_hi:[1,0]
	v_pk_add_f32 v[112:113], v[116:117], v[110:111]
	v_pk_add_f32 v[104:105], v[0:1], v[6:7] op_sel:[0,1] op_sel_hi:[1,0] neg_lo:[0,1] neg_hi:[0,1]
	v_pk_add_f32 v[0:1], v[0:1], v[6:7] op_sel:[0,1] op_sel_hi:[1,0]
	v_pk_add_f32 v[114:115], v[108:109], v[14:15]
	v_mov_b32_e32 v105, v1
	v_pk_add_f32 v[0:1], v[116:117], v[110:111] neg_lo:[0,1] neg_hi:[0,1]
	v_pk_add_f32 v[116:117], v[100:101], v[168:169]
	v_pk_mul_f32 v[6:7], v[0:1], 0 op_sel_hi:[1,0]
	v_pk_add_f32 v[120:121], v[8:9], v[10:11]
	v_pk_add_f32 v[16:17], v[0:1], v[6:7] op_sel:[0,1] op_sel_hi:[1,0] neg_lo:[0,1] neg_hi:[0,1]
	v_pk_add_f32 v[0:1], v[0:1], v[6:7] op_sel:[0,1] op_sel_hi:[1,0]
	v_pk_add_f32 v[118:119], v[124:125], v[164:165]
	v_mov_b32_e32 v17, v1
	v_pk_add_f32 v[0:1], v[12:13], v[2:3] neg_lo:[0,1] neg_hi:[0,1]
	v_lshl_add_u64 v[12:13], s[92:93], 2, v[54:55]
	v_pk_mul_f32 v[2:3], v[0:1], 0 op_sel_hi:[1,0]
	s_mov_b32 s28, s95
	v_pk_add_f32 v[110:111], v[0:1], v[2:3] op_sel:[0,1] op_sel_hi:[1,0] neg_lo:[0,1] neg_hi:[0,1]
	v_pk_add_f32 v[0:1], v[0:1], v[2:3] op_sel:[0,1] op_sel_hi:[1,0]
	s_mov_b32 s29, s94
	v_mov_b32_e32 v111, v1
	v_pk_add_f32 v[0:1], v[124:125], v[164:165] neg_lo:[0,1] neg_hi:[0,1]
	v_pk_add_f32 v[124:125], v[4:5], v[166:167]
	v_pk_mul_f32 v[2:3], v[0:1], 0 op_sel_hi:[1,0]
	v_pk_mul_f32 v[164:165], v[98:99], 0 op_sel_hi:[1,0]
	v_pk_add_f32 v[102:103], v[0:1], v[2:3] op_sel:[0,1] op_sel_hi:[1,0] neg_lo:[0,1] neg_hi:[0,1]
	v_pk_add_f32 v[0:1], v[0:1], v[2:3] op_sel:[0,1] op_sel_hi:[1,0]
	v_mov_b32_e32 v103, v1
	v_pk_add_f32 v[0:1], v[4:5], v[166:167] neg_lo:[0,1] neg_hi:[0,1]
	v_pk_add_f32 v[166:167], v[98:99], v[164:165] op_sel:[0,1] op_sel_hi:[1,0] neg_lo:[0,1] neg_hi:[0,1]
	v_pk_mul_f32 v[2:3], v[0:1], 0 op_sel_hi:[1,0]
	v_pk_add_f32 v[98:99], v[98:99], v[164:165] op_sel:[0,1] op_sel_hi:[1,0]
	v_pk_add_f32 v[108:109], v[0:1], v[2:3] op_sel:[0,1] op_sel_hi:[1,0] neg_lo:[0,1] neg_hi:[0,1]
	v_pk_add_f32 v[0:1], v[0:1], v[2:3] op_sel:[0,1] op_sel_hi:[1,0]
	v_mov_b32_e32 v167, v99
	v_mov_b32_e32 v109, v1
	v_pk_add_f32 v[0:1], v[100:101], v[168:169] neg_lo:[0,1] neg_hi:[0,1]
	v_pk_mul_f32 v[2:3], v[0:1], 0 op_sel_hi:[1,0]
	v_pk_add_f32 v[100:101], v[0:1], v[2:3] op_sel:[0,1] op_sel_hi:[1,0] neg_lo:[0,1] neg_hi:[0,1]
	v_pk_add_f32 v[0:1], v[0:1], v[2:3] op_sel:[0,1] op_sel_hi:[1,0]
	v_mov_b32_e32 v101, v1
	global_load_dwordx4 v[0:3], v[12:13], off offset:48
	global_load_dwordx4 v[4:7], v[12:13], off offset:32
	global_load_dwordx4 v[8:11], v[12:13], off offset:16
	s_nop 0
	global_load_dwordx4 v[12:15], v[12:13], off
	s_waitcnt vmcnt(0)
	v_lshlrev_b32_e32 v98, 16, v12
	v_and_b32_e32 v99, 0xffff0000, v12
	v_lshlrev_b32_e32 v12, 16, v13
	v_and_b32_e32 v13, 0xffff0000, v13
	v_pk_mul_f32 v[168:169], v[86:87], v[98:99] op_sel:[1,1] op_sel_hi:[1,0] neg_lo:[1,0]
	v_pk_fma_f32 v[164:165], v[86:87], v[98:99], v[168:169] op_sel_hi:[0,1,1]
	s_nop 0
	v_pk_mul_f32 v[168:169], v[122:123], v[98:99] op_sel:[1,1] op_sel_hi:[1,0] neg_lo:[1,0]
	v_pk_fma_f32 v[86:87], v[122:123], v[98:99], v[168:169] op_sel_hi:[0,1,1]
	v_pk_mul_f32 v[98:99], v[94:95], v[12:13] op_sel:[1,1] op_sel_hi:[1,0] neg_lo:[1,0]
	v_pk_fma_f32 v[94:95], v[94:95], v[12:13], v[98:99] op_sel_hi:[0,1,1]
	s_nop 0
	v_pk_mul_f32 v[98:99], v[126:127], v[12:13] op_sel:[1,1] op_sel_hi:[1,0] neg_lo:[1,0]
	v_pk_fma_f32 v[12:13], v[126:127], v[12:13], v[98:99] op_sel_hi:[0,1,1]
	s_nop 0
	v_lshlrev_b32_e32 v98, 16, v14
	v_and_b32_e32 v99, 0xffff0000, v14
	v_lshlrev_b32_e32 v14, 16, v15
	v_and_b32_e32 v15, 0xffff0000, v15
	v_pk_mul_f32 v[126:127], v[88:89], v[98:99] op_sel:[1,1] op_sel_hi:[1,0] neg_lo:[1,0]
	v_pk_fma_f32 v[122:123], v[88:89], v[98:99], v[126:127] op_sel_hi:[0,1,1]
	s_nop 0
	v_pk_mul_f32 v[126:127], v[120:121], v[98:99] op_sel:[1,1] op_sel_hi:[1,0] neg_lo:[1,0]
	v_pk_fma_f32 v[88:89], v[120:121], v[98:99], v[126:127] op_sel_hi:[0,1,1]
	v_pk_mul_f32 v[98:99], v[96:97], v[14:15] op_sel:[1,1] op_sel_hi:[1,0] neg_lo:[1,0]
	v_pk_fma_f32 v[96:97], v[96:97], v[14:15], v[98:99] op_sel_hi:[0,1,1]
	s_nop 0
	v_pk_mul_f32 v[98:99], v[124:125], v[14:15] op_sel:[1,1] op_sel_hi:[1,0] neg_lo:[1,0]
	v_pk_fma_f32 v[14:15], v[124:125], v[14:15], v[98:99] op_sel_hi:[0,1,1]
	s_nop 0
	v_lshlrev_b32_e32 v98, 16, v8
	v_and_b32_e32 v99, 0xffff0000, v8
	v_lshlrev_b32_e32 v8, 16, v9
	v_and_b32_e32 v9, 0xffff0000, v9
	v_pk_mul_f32 v[124:125], v[82:83], v[98:99] op_sel:[1,1] op_sel_hi:[1,0] neg_lo:[1,0]
	v_pk_fma_f32 v[120:121], v[82:83], v[98:99], v[124:125] op_sel_hi:[0,1,1]
	s_nop 0
	v_pk_mul_f32 v[124:125], v[114:115], v[98:99] op_sel:[1,1] op_sel_hi:[1,0] neg_lo:[1,0]
	v_pk_fma_f32 v[82:83], v[114:115], v[98:99], v[124:125] op_sel_hi:[0,1,1]
; DEV cf kunpack(unsigned w) { return cf{U2F(w << 16), U2F(w & 0xffff0000u)}; }
; template <int R, bool INV> DEV void dft_regs(cf (&v)[R]) {
; #pragma unroll
;     for (int s = R; s >= 2; s >>= 1) {
;         const int h = s >> 1;
; #pragma unroll
;         for (int b = 0; b < R; b += s) {
; #pragma unroll
;             for (int k = 0; k < h; ++k) {
;                 const cf a = v[b + k], c = v[b + k + h];
;                 v[b + k] = a + c;
;                 const cf d = a - c;
;                 const int m = k * (32 / s);
;                 const float wr = tw_cos(m), wi = INV ? tw_sin(m) : -tw_sin(m);
;                 v[b + k + h] = cf{d.x * wr - d.y * wi, d.x * wi + d.y * wr};
;             }
;         }
;     }
; }
; DEV void fft_midx2(LAS cf* buf0, LAS cf* buf1, const unsigned* Kp, int blk) {
;     ...
;     for (int p = 0; p < 16; ++p) { const cf k = kunpack(kw[p >> 2][p & 3]); w[p] = cmul(v[BR16[p]], k); x[p] = cmul(u[BR16[p]], k); }
;     dft_regs<16, true>(w); dft_regs<16, true>(x);
	v_pk_mul_f32 v[98:99], v[90:91], v[8:9] op_sel:[1,1] op_sel_hi:[1,0] neg_lo:[1,0]
	v_pk_fma_f32 v[90:91], v[90:91], v[8:9], v[98:99] op_sel_hi:[0,1,1]
	s_nop 0
	v_pk_mul_f32 v[98:99], v[118:119], v[8:9] op_sel:[1,1] op_sel_hi:[1,0] neg_lo:[1,0]
	v_pk_fma_f32 v[8:9], v[118:119], v[8:9], v[98:99] op_sel_hi:[0,1,1]
	s_nop 0
	v_lshlrev_b32_e32 v98, 16, v10
	v_and_b32_e32 v99, 0xffff0000, v10
	v_lshlrev_b32_e32 v10, 16, v11
	v_and_b32_e32 v11, 0xffff0000, v11
	v_pk_mul_f32 v[118:119], v[84:85], v[98:99] op_sel:[1,1] op_sel_hi:[1,0] neg_lo:[1,0]
	v_pk_fma_f32 v[114:115], v[84:85], v[98:99], v[118:119] op_sel_hi:[0,1,1]
	s_nop 0
	v_pk_mul_f32 v[118:119], v[112:113], v[98:99] op_sel:[1,1] op_sel_hi:[1,0] neg_lo:[1,0]
	v_pk_fma_f32 v[84:85], v[112:113], v[98:99], v[118:119] op_sel_hi:[0,1,1]
	v_pk_mul_f32 v[98:99], v[92:93], v[10:11] op_sel:[1,1] op_sel_hi:[1,0] neg_lo:[1,0]
	v_pk_fma_f32 v[92:93], v[92:93], v[10:11], v[98:99] op_sel_hi:[0,1,1]
	s_nop 0
	v_pk_mul_f32 v[98:99], v[116:117], v[10:11] op_sel:[1,1] op_sel_hi:[1,0] neg_lo:[1,0]
	v_pk_fma_f32 v[10:11], v[116:117], v[10:11], v[98:99] op_sel_hi:[0,1,1]
	s_nop 0
	v_lshlrev_b32_e32 v98, 16, v4
	v_and_b32_e32 v99, 0xffff0000, v4
	v_pk_mul_f32 v[112:113], v[76:77], v[98:99] op_sel:[1,1] op_sel_hi:[1,0] neg_lo:[1,0]
	v_pk_fma_f32 v[76:77], v[76:77], v[98:99], v[112:113] op_sel_hi:[0,1,1]
	v_lshlrev_b32_e32 v4, 16, v5
	v_pk_mul_f32 v[112:113], v[106:107], v[98:99] op_sel:[1,1] op_sel_hi:[1,0] neg_lo:[1,0]
	v_pk_fma_f32 v[98:99], v[106:107], v[98:99], v[112:113] op_sel_hi:[0,1,1]
	v_and_b32_e32 v5, 0xffff0000, v5
	v_pk_mul_f32 v[106:107], v[80:81], v[4:5] op_sel:[1,1] op_sel_hi:[1,0] neg_lo:[1,0]
	v_pk_fma_f32 v[80:81], v[80:81], v[4:5], v[106:107] op_sel_hi:[0,1,1]
	s_nop 0
	v_pk_mul_f32 v[112:113], v[110:111], v[4:5] op_sel:[1,1] op_sel_hi:[1,0] neg_lo:[1,0]
	v_pk_fma_f32 v[106:107], v[110:111], v[4:5], v[112:113] op_sel_hi:[0,1,1]
	v_lshlrev_b32_e32 v4, 16, v6
	v_and_b32_e32 v5, 0xffff0000, v6
	v_pk_mul_f32 v[110:111], v[74:75], v[4:5] op_sel:[1,1] op_sel_hi:[1,0] neg_lo:[1,0]
	v_pk_fma_f32 v[74:75], v[74:75], v[4:5], v[110:111] op_sel_hi:[0,1,1]
	s_nop 0
	v_pk_mul_f32 v[110:111], v[104:105], v[4:5] op_sel:[1,1] op_sel_hi:[1,0] neg_lo:[1,0]
	v_pk_fma_f32 v[104:105], v[104:105], v[4:5], v[110:111] op_sel_hi:[0,1,1]
	v_lshlrev_b32_e32 v4, 16, v7
	v_and_b32_e32 v5, 0xffff0000, v7
	v_pk_mul_f32 v[110:111], v[78:79], v[4:5] op_sel:[1,1] op_sel_hi:[1,0] neg_lo:[1,0]
	v_pk_fma_f32 v[6:7], v[78:79], v[4:5], v[110:111] op_sel_hi:[0,1,1]
	v_pk_mul_f32 v[78:79], v[108:109], v[4:5] op_sel:[1,1] op_sel_hi:[1,0] neg_lo:[1,0]
	v_pk_fma_f32 v[108:109], v[108:109], v[4:5], v[78:79] op_sel_hi:[0,1,1]
	v_lshlrev_b32_e32 v4, 16, v0
	v_and_b32_e32 v5, 0xffff0000, v0
	v_lshlrev_b32_e32 v0, 16, v1
	v_and_b32_e32 v1, 0xffff0000, v1
	v_pk_mul_f32 v[78:79], v[70:71], v[4:5] op_sel:[1,1] op_sel_hi:[1,0] neg_lo:[1,0]
	v_pk_fma_f32 v[70:71], v[70:71], v[4:5], v[78:79] op_sel_hi:[0,1,1]
	s_nop 0
	v_pk_mul_f32 v[78:79], v[18:19], v[4:5] op_sel:[1,1] op_sel_hi:[1,0] neg_lo:[1,0]
	v_pk_fma_f32 v[110:111], v[18:19], v[4:5], v[78:79] op_sel_hi:[0,1,1]
	v_pk_mul_f32 v[18:19], v[72:73], v[0:1] op_sel:[1,1] op_sel_hi:[1,0] neg_lo:[1,0]
	v_pk_fma_f32 v[4:5], v[72:73], v[0:1], v[18:19] op_sel_hi:[0,1,1]
	s_nop 0
	v_pk_mul_f32 v[18:19], v[102:103], v[0:1] op_sel:[1,1] op_sel_hi:[1,0] neg_lo:[1,0]
	v_pk_fma_f32 v[102:103], v[102:103], v[0:1], v[18:19] op_sel_hi:[0,1,1]
	v_lshlrev_b32_e32 v0, 16, v2
	v_and_b32_e32 v1, 0xffff0000, v2
	v_pk_mul_f32 v[72:73], v[68:69], v[0:1] op_sel:[1,1] op_sel_hi:[1,0] neg_lo:[1,0]
	v_pk_fma_f32 v[18:19], v[68:69], v[0:1], v[72:73] op_sel_hi:[0,1,1]
	v_pk_mul_f32 v[68:69], v[16:17], v[0:1] op_sel:[1,1] op_sel_hi:[1,0] neg_lo:[1,0]
	v_pk_fma_f32 v[112:113], v[16:17], v[0:1], v[68:69] op_sel_hi:[0,1,1]
	v_lshlrev_b32_e32 v0, 16, v3
	v_and_b32_e32 v1, 0xffff0000, v3
	v_pk_mul_f32 v[16:17], v[166:167], v[0:1] op_sel:[1,1] op_sel_hi:[1,0] neg_lo:[1,0]
	v_pk_fma_f32 v[2:3], v[166:167], v[0:1], v[16:17] op_sel_hi:[0,1,1]
	s_nop 0
	v_pk_mul_f32 v[16:17], v[100:101], v[0:1] op_sel:[1,1] op_sel_hi:[1,0] neg_lo:[1,0]
	v_pk_fma_f32 v[100:101], v[100:101], v[0:1], v[16:17] op_sel_hi:[0,1,1]
	v_pk_add_f32 v[0:1], v[164:165], v[76:77]
	v_pk_add_f32 v[16:17], v[164:165], v[76:77] neg_lo:[0,1] neg_hi:[0,1]
	v_pk_mul_f32 v[68:69], v[16:17], 0 op_sel_hi:[1,0]
	v_pk_add_f32 v[72:73], v[16:17], v[68:69] op_sel:[0,1] op_sel_hi:[1,0]
	v_pk_add_f32 v[16:17], v[16:17], v[68:69] op_sel:[0,1] op_sel_hi:[1,0] neg_lo:[0,1] neg_hi:[0,1]
	v_pk_add_f32 v[68:69], v[94:95], v[80:81] neg_lo:[0,1] neg_hi:[0,1]
	v_mov_b32_e32 v73, v17
	v_pk_mul_f32 v[76:77], v[68:69], s[84:85] op_sel_hi:[1,0]
	v_pk_add_f32 v[16:17], v[94:95], v[80:81]
	v_pk_fma_f32 v[78:79], v[68:69], s[16:17], v[76:77] op_sel:[0,0,1] op_sel_hi:[1,0,0] neg_lo:[0,0,1] neg_hi:[0,0,1]
	v_pk_fma_f32 v[68:69], v[68:69], s[16:17], v[76:77] op_sel:[0,0,1] op_sel_hi:[1,0,0]
	v_mov_b32_e32 v79, v69
	v_pk_add_f32 v[68:69], v[122:123], v[74:75]
	v_pk_add_f32 v[74:75], v[122:123], v[74:75] neg_lo:[0,1] neg_hi:[0,1]
	v_pk_mul_f32 v[76:77], v[74:75], s[18:19] op_sel_hi:[1,0]
	v_pk_fma_f32 v[80:81], v[74:75], s[18:19], v[76:77] op_sel:[0,0,1] op_sel_hi:[1,0,0] neg_lo:[0,0,1] neg_hi:[0,0,1]
	v_pk_fma_f32 v[74:75], v[74:75], s[18:19], v[76:77] op_sel_hi:[1,0,0]
	v_mov_b32_e32 v81, v75
	v_pk_add_f32 v[74:75], v[96:97], v[6:7]
	v_pk_add_f32 v[6:7], v[96:97], v[6:7] neg_lo:[0,1] neg_hi:[0,1]
	v_pk_mul_f32 v[76:77], v[6:7], s[16:17] op_sel_hi:[1,0]
	v_pk_fma_f32 v[94:95], v[6:7], s[84:85], v[76:77] op_sel:[0,0,1] op_sel_hi:[1,0,0] neg_lo:[0,0,1] neg_hi:[0,0,1]
; template <int R, bool INV> DEV void dft_regs(cf (&v)[R]) {
; #pragma unroll
;     for (int s = R; s >= 2; s >>= 1) {
;         const int h = s >> 1;
; #pragma unroll
;         for (int b = 0; b < R; b += s) {
; #pragma unroll
;             for (int k = 0; k < h; ++k) {
;                 const cf a = v[b + k], c = v[b + k + h];
;                 v[b + k] = a + c;
;                 const cf d = a - c;
;                 const int m = k * (32 / s);
;                 const float wr = tw_cos(m), wi = INV ? tw_sin(m) : -tw_sin(m);
;                 v[b + k + h] = cf{d.x * wr - d.y * wi, d.x * wi + d.y * wr};
;             }
;         }
;     }
; }
	v_pk_fma_f32 v[6:7], v[6:7], s[84:85], v[76:77] op_sel:[0,0,1] op_sel_hi:[1,0,0]
	v_mov_b32_e32 v95, v7
	v_pk_add_f32 v[6:7], v[120:121], v[70:71]
	v_pk_add_f32 v[70:71], v[120:121], v[70:71] neg_lo:[0,1] neg_hi:[0,1]
	v_pk_fma_f32 v[76:77], v[70:71], 0, v[70:71] op_sel:[0,0,1] op_sel_hi:[1,0,0] neg_lo:[0,0,1] neg_hi:[0,0,1]
	v_pk_fma_f32 v[70:71], v[70:71], 0, v[70:71] op_sel:[0,0,1] op_sel_hi:[1,0,0]
	v_mov_b32_e32 v77, v71
	v_pk_add_f32 v[70:71], v[90:91], v[4:5]
	v_pk_add_f32 v[4:5], v[90:91], v[4:5] neg_lo:[0,1] neg_hi:[0,1]
	v_pk_mul_f32 v[90:91], v[4:5], s[24:25] op_sel:[1,0]
	v_pk_fma_f32 v[4:5], v[4:5], s[0:1], v[90:91] op_sel_hi:[0,1,1] neg_lo:[0,0,1] neg_hi:[0,0,1]
	v_pk_add_f32 v[90:91], v[114:115], v[18:19]
	v_pk_add_f32 v[18:19], v[114:115], v[18:19] neg_lo:[0,1] neg_hi:[0,1]
	v_mul_f32_e32 v96, 0x3f3504f3, v19
	v_pk_fma_f32 v[18:19], v[18:19], s[96:97], v[96:97] op_sel_hi:[0,1,0] neg_lo:[0,0,1] neg_hi:[0,0,1]
	v_pk_add_f32 v[96:97], v[92:93], v[2:3]
	v_pk_add_f32 v[2:3], v[92:93], v[2:3] neg_lo:[0,1] neg_hi:[0,1]
	v_pk_mul_f32 v[92:93], v[2:3], s[84:85] op_sel:[1,0]
	v_pk_fma_f32 v[2:3], v[2:3], s[88:89], v[92:93] op_sel_hi:[0,1,1] neg_lo:[0,0,1] neg_hi:[0,0,1]
	v_pk_add_f32 v[92:93], v[0:1], v[6:7]
	v_pk_add_f32 v[0:1], v[0:1], v[6:7] neg_lo:[0,1] neg_hi:[0,1]
	v_pk_mul_f32 v[6:7], v[0:1], 0 op_sel_hi:[1,0]
	v_pk_add_f32 v[114:115], v[0:1], v[6:7] op_sel:[0,1] op_sel_hi:[1,0]
	v_pk_add_f32 v[0:1], v[0:1], v[6:7] op_sel:[0,1] op_sel_hi:[1,0] neg_lo:[0,1] neg_hi:[0,1]
	v_pk_add_f32 v[6:7], v[16:17], v[70:71] neg_lo:[0,1] neg_hi:[0,1]
	v_mov_b32_e32 v115, v1
	v_pk_add_f32 v[0:1], v[16:17], v[70:71]
	v_pk_mul_f32 v[16:17], v[6:7], s[18:19] op_sel_hi:[1,0]
	v_pk_fma_f32 v[70:71], v[6:7], s[18:19], v[16:17] op_sel:[0,0,1] op_sel_hi:[1,0,0] neg_lo:[0,0,1] neg_hi:[0,0,1]
	v_pk_fma_f32 v[6:7], v[6:7], s[18:19], v[16:17] op_sel_hi:[1,0,0]
	v_pk_add_f32 v[16:17], v[68:69], v[90:91] neg_lo:[0,1] neg_hi:[0,1]
	v_mov_b32_e32 v71, v7
	v_pk_add_f32 v[6:7], v[68:69], v[90:91]
	v_pk_fma_f32 v[68:69], v[16:17], 0, v[16:17] op_sel:[0,0,1] op_sel_hi:[1,0,0] neg_lo:[0,0,1] neg_hi:[0,0,1]
	v_pk_fma_f32 v[16:17], v[16:17], 0, v[16:17] op_sel:[0,0,1] op_sel_hi:[1,0,0]
	v_mov_b32_e32 v69, v17
	v_pk_add_f32 v[16:17], v[74:75], v[96:97]
	v_pk_add_f32 v[74:75], v[74:75], v[96:97] neg_lo:[0,1] neg_hi:[0,1]
	v_mul_f32_e32 v90, 0x3f3504f3, v75
	v_pk_fma_f32 v[74:75], v[74:75], s[96:97], v[90:91] op_sel_hi:[0,1,0] neg_lo:[0,0,1] neg_hi:[0,0,1]
	v_pk_add_f32 v[90:91], v[72:73], v[76:77]
	v_pk_add_f32 v[72:73], v[72:73], v[76:77] neg_lo:[0,1] neg_hi:[0,1]
	v_pk_mul_f32 v[76:77], v[72:73], 0 op_sel_hi:[1,0]
	v_pk_add_f32 v[96:97], v[72:73], v[76:77] op_sel:[0,1] op_sel_hi:[1,0]
	v_pk_add_f32 v[72:73], v[72:73], v[76:77] op_sel:[0,1] op_sel_hi:[1,0] neg_lo:[0,1] neg_hi:[0,1]
	v_mov_b32_e32 v97, v73
	v_pk_add_f32 v[72:73], v[78:79], v[4:5]
	v_pk_add_f32 v[4:5], v[78:79], v[4:5] neg_lo:[0,1] neg_hi:[0,1]
	v_pk_mul_f32 v[76:77], v[4:5], s[18:19] op_sel_hi:[1,0]
	v_pk_fma_f32 v[78:79], v[4:5], s[18:19], v[76:77] op_sel:[0,0,1] op_sel_hi:[1,0,0] neg_lo:[0,0,1] neg_hi:[0,0,1]
	v_pk_fma_f32 v[4:5], v[4:5], s[18:19], v[76:77] op_sel_hi:[1,0,0]
	v_mov_b32_e32 v79, v5
	v_pk_add_f32 v[4:5], v[80:81], v[18:19]
	v_pk_add_f32 v[18:19], v[80:81], v[18:19] neg_lo:[0,1] neg_hi:[0,1]
	v_pk_add_f32 v[116:117], v[90:91], v[4:5]
	v_pk_fma_f32 v[76:77], v[18:19], 0, v[18:19] op_sel:[0,0,1] op_sel_hi:[1,0,0] neg_lo:[0,0,1] neg_hi:[0,0,1]
	v_pk_fma_f32 v[18:19], v[18:19], 0, v[18:19] op_sel:[0,0,1] op_sel_hi:[1,0,0]
	v_pk_add_f32 v[4:5], v[90:91], v[4:5] neg_lo:[0,1] neg_hi:[0,1]
	v_mov_b32_e32 v77, v19
	v_pk_add_f32 v[18:19], v[94:95], v[2:3]
	v_pk_add_f32 v[2:3], v[94:95], v[2:3] neg_lo:[0,1] neg_hi:[0,1]
	v_pk_add_f32 v[118:119], v[72:73], v[18:19]
	v_mul_f32_e32 v80, 0x3f3504f3, v3
	v_pk_fma_f32 v[2:3], v[2:3], s[96:97], v[80:81] op_sel_hi:[0,1,0] neg_lo:[0,0,1] neg_hi:[0,0,1]
	v_pk_add_f32 v[80:81], v[92:93], v[6:7]
	v_pk_add_f32 v[6:7], v[92:93], v[6:7] neg_lo:[0,1] neg_hi:[0,1]
	v_pk_add_f32 v[122:123], v[78:79], v[2:3]
	v_pk_mul_f32 v[92:93], v[6:7], 0 op_sel_hi:[1,0]
	v_pk_add_f32 v[2:3], v[78:79], v[2:3] neg_lo:[0,1] neg_hi:[0,1]
	v_pk_add_f32 v[94:95], v[6:7], v[92:93] op_sel:[0,1] op_sel_hi:[1,0]
	v_pk_add_f32 v[6:7], v[6:7], v[92:93] op_sel:[0,1] op_sel_hi:[1,0] neg_lo:[0,1] neg_hi:[0,1]
	v_pk_fma_f32 v[78:79], v[2:3], 0, v[2:3] op_sel:[0,0,1] op_sel_hi:[1,0,0] neg_lo:[0,0,1] neg_hi:[0,0,1]
	v_mov_b32_e32 v95, v7
	v_pk_add_f32 v[6:7], v[0:1], v[16:17]
	v_pk_add_f32 v[0:1], v[0:1], v[16:17] neg_lo:[0,1] neg_hi:[0,1]
	v_pk_fma_f32 v[2:3], v[2:3], 0, v[2:3] op_sel:[0,0,1] op_sel_hi:[1,0,0]
	v_pk_fma_f32 v[16:17], v[0:1], 0, v[0:1] op_sel:[0,0,1] op_sel_hi:[1,0,0] neg_lo:[0,0,1] neg_hi:[0,0,1]
	v_pk_fma_f32 v[0:1], v[0:1], 0, v[0:1] op_sel:[0,0,1] op_sel_hi:[1,0,0]
	v_pk_add_f32 v[120:121], v[96:97], v[76:77]
	v_mov_b32_e32 v17, v1
	v_pk_add_f32 v[0:1], v[114:115], v[68:69]
	v_pk_add_f32 v[68:69], v[114:115], v[68:69] neg_lo:[0,1] neg_hi:[0,1]
	v_mov_b32_e32 v79, v3
	v_pk_mul_f32 v[92:93], v[68:69], 0 op_sel_hi:[1,0]
	v_pk_add_f32 v[2:3], v[80:81], v[6:7] neg_lo:[0,1] neg_hi:[0,1]
	v_pk_add_f32 v[114:115], v[68:69], v[92:93] op_sel:[0,1] op_sel_hi:[1,0]
	v_pk_add_f32 v[68:69], v[68:69], v[92:93] op_sel:[0,1] op_sel_hi:[1,0] neg_lo:[0,1] neg_hi:[0,1]
	v_pk_add_f32 v[92:93], v[70:71], v[74:75]
	v_mov_b32_e32 v115, v69
	v_pk_add_f32 v[68:69], v[70:71], v[74:75] neg_lo:[0,1] neg_hi:[0,1]
	v_pk_add_f32 v[124:125], v[80:81], v[6:7]
	v_pk_fma_f32 v[74:75], v[68:69], 0, v[68:69] op_sel:[0,0,1] op_sel_hi:[1,0,0] neg_lo:[0,0,1] neg_hi:[0,0,1]
; template <int R, bool INV> DEV void dft_regs(cf (&v)[R]) {
; #pragma unroll
;     for (int s = R; s >= 2; s >>= 1) {
;         const int h = s >> 1;
; #pragma unroll
;         for (int b = 0; b < R; b += s) {
; #pragma unroll
;             for (int k = 0; k < h; ++k) {
;                 const cf a = v[b + k], c = v[b + k + h];
;                 v[b + k] = a + c;
;                 const cf d = a - c;
;                 const int m = k * (32 / s);
;                 const float wr = tw_cos(m), wi = INV ? tw_sin(m) : -tw_sin(m);
;                 v[b + k + h] = cf{d.x * wr - d.y * wi, d.x * wi + d.y * wr};
;             }
;         }
;     }
; }
	v_pk_fma_f32 v[68:69], v[68:69], 0, v[68:69] op_sel:[0,0,1] op_sel_hi:[1,0,0]
	v_pk_add_f32 v[80:81], v[94:95], v[16:17]
	v_mov_b32_e32 v75, v69
	v_pk_mul_f32 v[68:69], v[4:5], 0 op_sel_hi:[1,0]
	v_pk_add_f32 v[90:91], v[4:5], v[68:69] op_sel:[0,1] op_sel_hi:[1,0]
	v_pk_add_f32 v[4:5], v[4:5], v[68:69] op_sel:[0,1] op_sel_hi:[1,0] neg_lo:[0,1] neg_hi:[0,1]
	v_mov_b32_e32 v91, v5
	v_pk_add_f32 v[4:5], v[72:73], v[18:19] neg_lo:[0,1] neg_hi:[0,1]
	v_pk_fma_f32 v[72:73], v[4:5], 0, v[4:5] op_sel:[0,0,1] op_sel_hi:[1,0,0] neg_lo:[0,0,1] neg_hi:[0,0,1]
	v_pk_fma_f32 v[4:5], v[4:5], 0, v[4:5] op_sel:[0,0,1] op_sel_hi:[1,0,0]
	v_mov_b32_e32 v73, v5
	v_pk_add_f32 v[4:5], v[96:97], v[76:77] neg_lo:[0,1] neg_hi:[0,1]
	v_pk_add_f32 v[126:127], v[90:91], v[72:73]
	v_pk_mul_f32 v[18:19], v[4:5], 0 op_sel_hi:[1,0]
	v_pk_add_f32 v[72:73], v[90:91], v[72:73] neg_lo:[0,1] neg_hi:[0,1]
	v_pk_add_f32 v[96:97], v[4:5], v[18:19] op_sel:[0,1] op_sel_hi:[1,0]
	v_pk_add_f32 v[4:5], v[4:5], v[18:19] op_sel:[0,1] op_sel_hi:[1,0] neg_lo:[0,1] neg_hi:[0,1]
	v_pk_add_f32 v[90:91], v[120:121], v[122:123]
	v_mov_b32_e32 v97, v5
	v_pk_mul_f32 v[4:5], v[2:3], 0 op_sel_hi:[1,0]
	v_pk_add_f32 v[164:165], v[96:97], v[78:79]
	v_pk_add_f32 v[18:19], v[2:3], v[4:5] op_sel:[0,1] op_sel_hi:[1,0]
	v_pk_add_f32 v[68:69], v[2:3], v[4:5] op_sel:[0,1] op_sel_hi:[1,0] neg_lo:[0,1] neg_hi:[0,1]
	v_pk_add_f32 v[4:5], v[94:95], v[16:17] neg_lo:[0,1] neg_hi:[0,1]
	v_pk_add_f32 v[94:95], v[0:1], v[92:93]
	v_pk_mul_f32 v[6:7], v[4:5], 0 op_sel_hi:[1,0]
	v_pk_add_f32 v[0:1], v[0:1], v[92:93] neg_lo:[0,1] neg_hi:[0,1]
	v_pk_add_f32 v[2:3], v[4:5], v[6:7] op_sel:[0,1] op_sel_hi:[1,0]
	v_pk_add_f32 v[4:5], v[4:5], v[6:7] op_sel:[0,1] op_sel_hi:[1,0] neg_lo:[0,1] neg_hi:[0,1]
	v_pk_mul_f32 v[6:7], v[0:1], 0 op_sel_hi:[1,0]
	v_pk_add_f32 v[92:93], v[114:115], v[74:75]
	v_pk_add_f32 v[16:17], v[0:1], v[6:7] op_sel:[0,1] op_sel_hi:[1,0]
	v_pk_add_f32 v[70:71], v[0:1], v[6:7] op_sel:[0,1] op_sel_hi:[1,0] neg_lo:[0,1] neg_hi:[0,1]
	v_pk_add_f32 v[6:7], v[114:115], v[74:75] neg_lo:[0,1] neg_hi:[0,1]
	v_pk_add_f32 v[114:115], v[116:117], v[118:119]
	v_pk_mul_f32 v[74:75], v[6:7], 0 op_sel_hi:[1,0]
	v_pk_add_f32 v[78:79], v[96:97], v[78:79] neg_lo:[0,1] neg_hi:[0,1]
	v_pk_add_f32 v[0:1], v[6:7], v[74:75] op_sel:[0,1] op_sel_hi:[1,0]
	v_pk_add_f32 v[6:7], v[6:7], v[74:75] op_sel:[0,1] op_sel_hi:[1,0] neg_lo:[0,1] neg_hi:[0,1]
	v_pk_add_f32 v[74:75], v[116:117], v[118:119] neg_lo:[0,1] neg_hi:[0,1]
	v_pk_mul_f32 v[96:97], v[78:79], 0 op_sel_hi:[1,0]
	v_pk_mul_f32 v[76:77], v[74:75], 0 op_sel_hi:[1,0]
	v_mov_b32_e32 v1, v7
	v_pk_add_f32 v[116:117], v[74:75], v[76:77] op_sel:[0,1] op_sel_hi:[1,0]
	v_pk_add_f32 v[118:119], v[74:75], v[76:77] op_sel:[0,1] op_sel_hi:[1,0] neg_lo:[0,1] neg_hi:[0,1]
	v_pk_mul_f32 v[76:77], v[72:73], 0 op_sel_hi:[1,0]
	v_mov_b32_e32 v19, v69
	v_pk_add_f32 v[74:75], v[72:73], v[76:77] op_sel:[0,1] op_sel_hi:[1,0]
	v_pk_add_f32 v[76:77], v[72:73], v[76:77] op_sel:[0,1] op_sel_hi:[1,0] neg_lo:[0,1] neg_hi:[0,1]
	v_pk_add_f32 v[72:73], v[120:121], v[122:123] neg_lo:[0,1] neg_hi:[0,1]
	v_mov_b32_e32 v117, v119
	v_pk_mul_f32 v[120:121], v[72:73], 0 op_sel_hi:[1,0]
	v_mov_b32_e32 v17, v71
	v_pk_add_f32 v[122:123], v[72:73], v[120:121] op_sel:[0,1] op_sel_hi:[1,0]
	v_pk_add_f32 v[120:121], v[72:73], v[120:121] op_sel:[0,1] op_sel_hi:[1,0] neg_lo:[0,1] neg_hi:[0,1]
	v_pk_add_f32 v[72:73], v[78:79], v[96:97] op_sel:[0,1] op_sel_hi:[1,0]
	v_pk_add_f32 v[78:79], v[78:79], v[96:97] op_sel:[0,1] op_sel_hi:[1,0] neg_lo:[0,1] neg_hi:[0,1]
	v_pk_add_f32 v[96:97], v[86:87], v[98:99]
	v_pk_add_f32 v[86:87], v[86:87], v[98:99] neg_lo:[0,1] neg_hi:[0,1]
	v_mov_b32_e32 v73, v79
	v_pk_mul_f32 v[98:99], v[86:87], 0 op_sel_hi:[1,0]
	v_mov_b32_e32 v123, v121
	v_pk_add_f32 v[166:167], v[86:87], v[98:99] op_sel:[0,1] op_sel_hi:[1,0]
	v_pk_add_f32 v[86:87], v[86:87], v[98:99] op_sel:[0,1] op_sel_hi:[1,0] neg_lo:[0,1] neg_hi:[0,1]
	v_mov_b32_e32 v3, v5
	v_mov_b32_e32 v167, v87
	v_pk_add_f32 v[86:87], v[12:13], v[106:107]
	v_pk_add_f32 v[12:13], v[12:13], v[106:107] neg_lo:[0,1] neg_hi:[0,1]
	v_mov_b32_e32 v75, v77
	v_pk_mul_f32 v[98:99], v[12:13], s[84:85] op_sel_hi:[1,0]
	v_pk_fma_f32 v[106:107], v[12:13], s[16:17], v[98:99] op_sel:[0,0,1] op_sel_hi:[1,0,0] neg_lo:[0,0,1] neg_hi:[0,0,1]
	v_pk_fma_f32 v[12:13], v[12:13], s[16:17], v[98:99] op_sel:[0,0,1] op_sel_hi:[1,0,0]
	v_mov_b32_e32 v107, v13
	v_pk_add_f32 v[12:13], v[88:89], v[104:105]
	v_pk_add_f32 v[88:89], v[88:89], v[104:105] neg_lo:[0,1] neg_hi:[0,1]
	v_pk_mul_f32 v[98:99], v[88:89], s[18:19] op_sel_hi:[1,0]
	v_pk_fma_f32 v[104:105], v[88:89], s[18:19], v[98:99] op_sel:[0,0,1] op_sel_hi:[1,0,0] neg_lo:[0,0,1] neg_hi:[0,0,1]
	v_pk_fma_f32 v[88:89], v[88:89], s[18:19], v[98:99] op_sel_hi:[1,0,0]
	v_mov_b32_e32 v105, v89
	v_pk_add_f32 v[88:89], v[14:15], v[108:109]
	v_pk_add_f32 v[14:15], v[14:15], v[108:109] neg_lo:[0,1] neg_hi:[0,1]
	v_pk_mul_f32 v[98:99], v[14:15], s[16:17] op_sel_hi:[1,0]
	v_pk_fma_f32 v[108:109], v[14:15], s[84:85], v[98:99] op_sel:[0,0,1] op_sel_hi:[1,0,0] neg_lo:[0,0,1] neg_hi:[0,0,1]
	v_pk_fma_f32 v[14:15], v[14:15], s[84:85], v[98:99] op_sel:[0,0,1] op_sel_hi:[1,0,0]
	v_mov_b32_e32 v109, v15
	v_pk_add_f32 v[14:15], v[82:83], v[110:111]
	v_pk_add_f32 v[82:83], v[82:83], v[110:111] neg_lo:[0,1] neg_hi:[0,1]
	v_pk_add_f32 v[110:111], v[10:11], v[100:101]
	v_pk_add_f32 v[10:11], v[10:11], v[100:101] neg_lo:[0,1] neg_hi:[0,1]
	v_pk_fma_f32 v[98:99], v[82:83], 0, v[82:83] op_sel:[0,0,1] op_sel_hi:[1,0,0] neg_lo:[0,0,1] neg_hi:[0,0,1]
	v_pk_fma_f32 v[82:83], v[82:83], 0, v[82:83] op_sel:[0,0,1] op_sel_hi:[1,0,0]
; template <int R, bool INV> DEV void dft_regs(cf (&v)[R]) {
; #pragma unroll
;     for (int s = R; s >= 2; s >>= 1) {
;         const int h = s >> 1;
; #pragma unroll
;         for (int b = 0; b < R; b += s) {
; #pragma unroll
;             for (int k = 0; k < h; ++k) {
;                 const cf a = v[b + k], c = v[b + k + h];
;                 v[b + k] = a + c;
;                 const cf d = a - c;
;                 const int m = k * (32 / s);
;                 const float wr = tw_cos(m), wi = INV ? tw_sin(m) : -tw_sin(m);
;                 v[b + k + h] = cf{d.x * wr - d.y * wi, d.x * wi + d.y * wr};
;             }
;         }
;     }
; }
	v_pk_mul_f32 v[100:101], v[10:11], s[84:85] op_sel:[1,0]
	v_mov_b32_e32 v99, v83
	v_pk_add_f32 v[82:83], v[8:9], v[102:103]
	v_pk_add_f32 v[8:9], v[8:9], v[102:103] neg_lo:[0,1] neg_hi:[0,1]
	v_pk_fma_f32 v[10:11], v[10:11], s[88:89], v[100:101] op_sel_hi:[0,1,1] neg_lo:[0,0,1] neg_hi:[0,0,1]
	v_pk_add_f32 v[100:101], v[96:97], v[14:15]
	v_pk_add_f32 v[14:15], v[96:97], v[14:15] neg_lo:[0,1] neg_hi:[0,1]
	v_pk_mul_f32 v[102:103], v[8:9], s[24:25] op_sel:[1,0]
	v_pk_mul_f32 v[96:97], v[14:15], 0 op_sel_hi:[1,0]
	v_pk_fma_f32 v[8:9], v[8:9], s[0:1], v[102:103] op_sel_hi:[0,1,1] neg_lo:[0,0,1] neg_hi:[0,0,1]
	v_pk_add_f32 v[102:103], v[84:85], v[112:113]
	v_pk_add_f32 v[84:85], v[84:85], v[112:113] neg_lo:[0,1] neg_hi:[0,1]
	v_pk_add_f32 v[112:113], v[14:15], v[96:97] op_sel:[0,1] op_sel_hi:[1,0]
	v_pk_add_f32 v[14:15], v[14:15], v[96:97] op_sel:[0,1] op_sel_hi:[1,0] neg_lo:[0,1] neg_hi:[0,1]
	v_mul_f32_e32 v4, 0x3f3504f3, v85
	v_mov_b32_e32 v113, v15
	v_pk_add_f32 v[14:15], v[86:87], v[82:83]
	v_pk_add_f32 v[82:83], v[86:87], v[82:83] neg_lo:[0,1] neg_hi:[0,1]
	v_pk_fma_f32 v[84:85], v[84:85], s[96:97], v[4:5] op_sel_hi:[0,1,0] neg_lo:[0,0,1] neg_hi:[0,0,1]
	v_pk_mul_f32 v[86:87], v[82:83], s[18:19] op_sel_hi:[1,0]
	v_pk_fma_f32 v[96:97], v[82:83], s[18:19], v[86:87] op_sel:[0,0,1] op_sel_hi:[1,0,0] neg_lo:[0,0,1] neg_hi:[0,0,1]
	v_pk_fma_f32 v[82:83], v[82:83], s[18:19], v[86:87] op_sel_hi:[1,0,0]
	v_mov_b32_e32 v97, v83
	v_pk_add_f32 v[82:83], v[12:13], v[102:103]
	v_pk_add_f32 v[12:13], v[12:13], v[102:103] neg_lo:[0,1] neg_hi:[0,1]
	v_pk_add_f32 v[102:103], v[166:167], v[98:99]
	v_pk_fma_f32 v[86:87], v[12:13], 0, v[12:13] op_sel:[0,0,1] op_sel_hi:[1,0,0] neg_lo:[0,0,1] neg_hi:[0,0,1]
	v_pk_fma_f32 v[12:13], v[12:13], 0, v[12:13] op_sel:[0,0,1] op_sel_hi:[1,0,0]
	v_pk_add_f32 v[98:99], v[166:167], v[98:99] neg_lo:[0,1] neg_hi:[0,1]
	v_mov_b32_e32 v87, v13
	v_pk_add_f32 v[12:13], v[88:89], v[110:111]
	v_pk_add_f32 v[88:89], v[88:89], v[110:111] neg_lo:[0,1] neg_hi:[0,1]
	v_pk_mul_f32 v[110:111], v[98:99], 0 op_sel_hi:[1,0]
	v_mul_f32_e32 v4, 0x3f3504f3, v89
	v_pk_add_f32 v[166:167], v[98:99], v[110:111] op_sel:[0,1] op_sel_hi:[1,0]
	v_pk_add_f32 v[98:99], v[98:99], v[110:111] op_sel:[0,1] op_sel_hi:[1,0] neg_lo:[0,1] neg_hi:[0,1]
	v_pk_fma_f32 v[88:89], v[88:89], s[96:97], v[4:5] op_sel_hi:[0,1,0] neg_lo:[0,0,1] neg_hi:[0,0,1]
	v_mov_b32_e32 v167, v99
	v_pk_add_f32 v[98:99], v[106:107], v[8:9]
	v_pk_add_f32 v[8:9], v[106:107], v[8:9] neg_lo:[0,1] neg_hi:[0,1]
	v_pk_mul_f32 v[106:107], v[8:9], s[18:19] op_sel_hi:[1,0]
	v_pk_fma_f32 v[110:111], v[8:9], s[18:19], v[106:107] op_sel:[0,0,1] op_sel_hi:[1,0,0] neg_lo:[0,0,1] neg_hi:[0,0,1]
	v_pk_fma_f32 v[8:9], v[8:9], s[18:19], v[106:107] op_sel_hi:[1,0,0]
	v_pk_add_f32 v[106:107], v[100:101], v[82:83]
	v_mov_b32_e32 v111, v9
	v_pk_add_f32 v[8:9], v[104:105], v[84:85]
	v_pk_add_f32 v[84:85], v[104:105], v[84:85] neg_lo:[0,1] neg_hi:[0,1]
	v_pk_add_f32 v[82:83], v[100:101], v[82:83] neg_lo:[0,1] neg_hi:[0,1]
	v_pk_fma_f32 v[104:105], v[84:85], 0, v[84:85] op_sel:[0,0,1] op_sel_hi:[1,0,0] neg_lo:[0,0,1] neg_hi:[0,0,1]
	v_pk_fma_f32 v[84:85], v[84:85], 0, v[84:85] op_sel:[0,0,1] op_sel_hi:[1,0,0]
	v_pk_mul_f32 v[100:101], v[82:83], 0 op_sel_hi:[1,0]
	v_mov_b32_e32 v105, v85
	v_pk_add_f32 v[84:85], v[108:109], v[10:11]
	v_pk_add_f32 v[10:11], v[108:109], v[10:11] neg_lo:[0,1] neg_hi:[0,1]
	v_pk_add_f32 v[108:109], v[82:83], v[100:101] op_sel:[0,1] op_sel_hi:[1,0]
	v_pk_add_f32 v[82:83], v[82:83], v[100:101] op_sel:[0,1] op_sel_hi:[1,0] neg_lo:[0,1] neg_hi:[0,1]
	v_mul_f32_e32 v4, 0x3f3504f3, v11
	v_mov_b32_e32 v109, v83
	v_pk_add_f32 v[82:83], v[14:15], v[12:13]
	v_pk_add_f32 v[12:13], v[14:15], v[12:13] neg_lo:[0,1] neg_hi:[0,1]
	v_pk_fma_f32 v[10:11], v[10:11], s[96:97], v[4:5] op_sel_hi:[0,1,0] neg_lo:[0,0,1] neg_hi:[0,0,1]
	v_pk_fma_f32 v[14:15], v[12:13], 0, v[12:13] op_sel:[0,0,1] op_sel_hi:[1,0,0] neg_lo:[0,0,1] neg_hi:[0,0,1]
	v_pk_fma_f32 v[12:13], v[12:13], 0, v[12:13] op_sel:[0,0,1] op_sel_hi:[1,0,0]
	v_mov_b32_e32 v15, v13
	v_pk_add_f32 v[12:13], v[112:113], v[86:87]
	v_pk_add_f32 v[86:87], v[112:113], v[86:87] neg_lo:[0,1] neg_hi:[0,1]
	v_pk_mul_f32 v[100:101], v[86:87], 0 op_sel_hi:[1,0]
	v_pk_add_f32 v[112:113], v[86:87], v[100:101] op_sel:[0,1] op_sel_hi:[1,0]
	v_pk_add_f32 v[86:87], v[86:87], v[100:101] op_sel:[0,1] op_sel_hi:[1,0] neg_lo:[0,1] neg_hi:[0,1]
	v_mov_b32_e32 v113, v87
	v_pk_add_f32 v[86:87], v[96:97], v[88:89]
	v_pk_add_f32 v[88:89], v[96:97], v[88:89] neg_lo:[0,1] neg_hi:[0,1]
	v_pk_fma_f32 v[96:97], v[88:89], 0, v[88:89] op_sel:[0,0,1] op_sel_hi:[1,0,0] neg_lo:[0,0,1] neg_hi:[0,0,1]
	v_pk_fma_f32 v[88:89], v[88:89], 0, v[88:89] op_sel:[0,0,1] op_sel_hi:[1,0,0]
	v_mov_b32_e32 v97, v89
	v_pk_add_f32 v[88:89], v[102:103], v[8:9]
	v_pk_add_f32 v[8:9], v[102:103], v[8:9] neg_lo:[0,1] neg_hi:[0,1]
	v_pk_mul_f32 v[100:101], v[8:9], 0 op_sel_hi:[1,0]
	v_pk_add_f32 v[102:103], v[8:9], v[100:101] op_sel:[0,1] op_sel_hi:[1,0]
	v_pk_add_f32 v[8:9], v[8:9], v[100:101] op_sel:[0,1] op_sel_hi:[1,0] neg_lo:[0,1] neg_hi:[0,1]
	v_pk_add_f32 v[100:101], v[166:167], v[104:105] neg_lo:[0,1] neg_hi:[0,1]
	v_mov_b32_e32 v103, v9
	v_pk_add_f32 v[8:9], v[98:99], v[84:85]
	v_pk_add_f32 v[84:85], v[98:99], v[84:85] neg_lo:[0,1] neg_hi:[0,1]
	v_pk_fma_f32 v[98:99], v[84:85], 0, v[84:85] op_sel:[0,0,1] op_sel_hi:[1,0,0] neg_lo:[0,0,1] neg_hi:[0,0,1]
	v_pk_fma_f32 v[84:85], v[84:85], 0, v[84:85] op_sel:[0,0,1] op_sel_hi:[1,0,0]
	v_mov_b32_e32 v99, v85
	v_pk_add_f32 v[84:85], v[166:167], v[104:105]
	v_pk_mul_f32 v[104:105], v[100:101], 0 op_sel_hi:[1,0]
; template <int R, bool INV> DEV void dft_regs(cf (&v)[R]) {
; #pragma unroll
;     for (int s = R; s >= 2; s >>= 1) {
;         const int h = s >> 1;
; #pragma unroll
;         for (int b = 0; b < R; b += s) {
; #pragma unroll
;             for (int k = 0; k < h; ++k) {
;                 const cf a = v[b + k], c = v[b + k + h];
;                 v[b + k] = a + c;
;                 const cf d = a - c;
;                 const int m = k * (32 / s);
;                 const float wr = tw_cos(m), wi = INV ? tw_sin(m) : -tw_sin(m);
;                 v[b + k + h] = cf{d.x * wr - d.y * wi, d.x * wi + d.y * wr};
;             }
;         }
;     }
; }
; DEV void fft_midx2(LAS cf* buf0, LAS cf* buf1, const unsigned* Kp, int blk) {
;     ...
;     dft_regs<16, true>(w); dft_regs<16, true>(x);
; #pragma unroll
;     for (int q = 0; q < 16; ++q) { p0[q] = w[BR16[q]]; p1[q] = x[BR16[q]]; }
	v_pk_add_f32 v[166:167], v[100:101], v[104:105] op_sel:[0,1] op_sel_hi:[1,0]
	v_pk_add_f32 v[100:101], v[100:101], v[104:105] op_sel:[0,1] op_sel_hi:[1,0] neg_lo:[0,1] neg_hi:[0,1]
	v_mov_b32_e32 v167, v101
	v_pk_add_f32 v[100:101], v[110:111], v[10:11]
	v_pk_add_f32 v[10:11], v[110:111], v[10:11] neg_lo:[0,1] neg_hi:[0,1]
	v_pk_fma_f32 v[104:105], v[10:11], 0, v[10:11] op_sel:[0,0,1] op_sel_hi:[1,0,0] neg_lo:[0,0,1] neg_hi:[0,0,1]
	v_pk_fma_f32 v[10:11], v[10:11], 0, v[10:11] op_sel:[0,0,1] op_sel_hi:[1,0,0]
	v_mov_b32_e32 v105, v11
	v_pk_add_f32 v[10:11], v[106:107], v[82:83]
	v_pk_add_f32 v[82:83], v[106:107], v[82:83] neg_lo:[0,1] neg_hi:[0,1]
	v_pk_mul_f32 v[106:107], v[82:83], 0 op_sel_hi:[1,0]
	v_pk_add_f32 v[110:111], v[82:83], v[106:107] op_sel:[0,1] op_sel_hi:[1,0]
	v_pk_add_f32 v[82:83], v[82:83], v[106:107] op_sel:[0,1] op_sel_hi:[1,0] neg_lo:[0,1] neg_hi:[0,1]
	v_pk_add_f32 v[106:107], v[108:109], v[14:15]
	v_pk_add_f32 v[14:15], v[108:109], v[14:15] neg_lo:[0,1] neg_hi:[0,1]
	v_mov_b32_e32 v111, v83
	v_pk_mul_f32 v[108:109], v[14:15], 0 op_sel_hi:[1,0]
	v_pk_add_f32 v[168:169], v[14:15], v[108:109] op_sel:[0,1] op_sel_hi:[1,0]
	v_pk_add_f32 v[14:15], v[14:15], v[108:109] op_sel:[0,1] op_sel_hi:[1,0] neg_lo:[0,1] neg_hi:[0,1]
	v_pk_add_f32 v[108:109], v[12:13], v[86:87]
	v_pk_add_f32 v[12:13], v[12:13], v[86:87] neg_lo:[0,1] neg_hi:[0,1]
	v_mov_b32_e32 v169, v15
	v_pk_mul_f32 v[86:87], v[12:13], 0 op_sel_hi:[1,0]
	v_pk_add_f32 v[170:171], v[12:13], v[86:87] op_sel:[0,1] op_sel_hi:[1,0]
	v_pk_add_f32 v[12:13], v[12:13], v[86:87] op_sel:[0,1] op_sel_hi:[1,0] neg_lo:[0,1] neg_hi:[0,1]
	v_pk_add_f32 v[86:87], v[112:113], v[96:97]
	v_pk_add_f32 v[96:97], v[112:113], v[96:97] neg_lo:[0,1] neg_hi:[0,1]
	v_mov_b32_e32 v171, v13
	v_pk_mul_f32 v[112:113], v[96:97], 0 op_sel_hi:[1,0]
	v_pk_add_f32 v[172:173], v[96:97], v[112:113] op_sel:[0,1] op_sel_hi:[1,0]
	v_pk_add_f32 v[96:97], v[96:97], v[112:113] op_sel:[0,1] op_sel_hi:[1,0] neg_lo:[0,1] neg_hi:[0,1]
	v_pk_add_f32 v[112:113], v[88:89], v[8:9]
	v_pk_add_f32 v[8:9], v[88:89], v[8:9] neg_lo:[0,1] neg_hi:[0,1]
	v_mov_b32_e32 v173, v97
	v_pk_mul_f32 v[88:89], v[8:9], 0 op_sel_hi:[1,0]
	v_pk_add_f32 v[174:175], v[8:9], v[88:89] op_sel:[0,1] op_sel_hi:[1,0]
	v_pk_add_f32 v[8:9], v[8:9], v[88:89] op_sel:[0,1] op_sel_hi:[1,0] neg_lo:[0,1] neg_hi:[0,1]
	v_pk_add_f32 v[88:89], v[102:103], v[98:99]
	v_pk_add_f32 v[98:99], v[102:103], v[98:99] neg_lo:[0,1] neg_hi:[0,1]
	v_mov_b32_e32 v175, v9
	v_pk_mul_f32 v[102:103], v[98:99], 0 op_sel_hi:[1,0]
	v_pk_add_f32 v[176:177], v[98:99], v[102:103] op_sel:[0,1] op_sel_hi:[1,0]
	v_pk_add_f32 v[98:99], v[98:99], v[102:103] op_sel:[0,1] op_sel_hi:[1,0] neg_lo:[0,1] neg_hi:[0,1]
	v_pk_add_f32 v[102:103], v[84:85], v[100:101]
	v_pk_add_f32 v[84:85], v[84:85], v[100:101] neg_lo:[0,1] neg_hi:[0,1]
	v_mov_b32_e32 v177, v99
	v_pk_mul_f32 v[100:101], v[84:85], 0 op_sel_hi:[1,0]
	v_pk_add_f32 v[178:179], v[84:85], v[100:101] op_sel:[0,1] op_sel_hi:[1,0]
	v_pk_add_f32 v[84:85], v[84:85], v[100:101] op_sel:[0,1] op_sel_hi:[1,0] neg_lo:[0,1] neg_hi:[0,1]
	v_pk_add_f32 v[100:101], v[166:167], v[104:105]
	v_pk_add_f32 v[104:105], v[166:167], v[104:105] neg_lo:[0,1] neg_hi:[0,1]
	ds_write2_b64 v161, v[124:125], v[114:115] offset1:1
	ds_write2_b64 v162, v[10:11], v[112:113] offset1:1
	ds_write2_b64 v161, v[94:95], v[90:91] offset0:2 offset1:3
	ds_write2_b64 v162, v[108:109], v[102:103] offset0:2 offset1:3
	ds_write2_b64 v161, v[80:81], v[126:127] offset0:4 offset1:5
	ds_write2_b64 v162, v[106:107], v[88:89] offset0:4 offset1:5
	ds_write2_b64 v161, v[92:93], v[164:165] offset0:6 offset1:7
	ds_write2_b64 v162, v[86:87], v[100:101] offset0:6 offset1:7
	v_pk_mul_f32 v[166:167], v[104:105], 0 op_sel_hi:[1,0]
	v_mov_b32_e32 v179, v85
	v_pk_add_f32 v[180:181], v[104:105], v[166:167] op_sel:[0,1] op_sel_hi:[1,0]
	v_pk_add_f32 v[104:105], v[104:105], v[166:167] op_sel:[0,1] op_sel_hi:[1,0] neg_lo:[0,1] neg_hi:[0,1]
	ds_write2_b64 v161, v[0:1], v[72:73] offset0:14 offset1:15
	v_mov_b32_e32 v181, v105
	v_mov_b32_e32 v0, v160
	ds_write2_b64 v161, v[18:19], v[116:117] offset0:8 offset1:9
	ds_write2_b64 v162, v[110:111], v[174:175] offset0:8 offset1:9
	ds_write2_b64 v161, v[16:17], v[122:123] offset0:10 offset1:11
	ds_write2_b64 v162, v[170:171], v[178:179] offset0:10 offset1:11
	ds_write2_b64 v161, v[2:3], v[74:75] offset0:12 offset1:13
	ds_write2_b64 v162, v[168:169], v[176:177] offset0:12 offset1:13
	ds_write2_b64 v162, v[172:173], v[180:181] offset0:14 offset1:15
	s_waitcnt lgkmcnt(0)
	s_barrier
; #define LAS __attribute__((address_space(3)))
; #define SINCOSPI(x, s, c) do { const float hx_ = 0.5f * (x); *(s) = __builtin_amdgcn_sinf(hx_); *(c) = __builtin_amdgcn_cosf(hx_); } while (0)
; #define OPAQUE_I(x) asm volatile("" : "+v"(x))
; DEV void fft_i2(LAS cf* buf, int t8) {
;     OPAQUE_I(t8);
;     LAS cf* pb = buf + (t8 >> 4) * 544 + (t8 & 15);
;     float sn, cs; SINCOSPI(-(float)(t8 & 15) * (2.0f / 512.0f), &sn, &cs);
;     const cf w = cf{cs, sn}; cf wp = cf{1.f, 0.f};
;     cf v[32];
; #pragma unroll
;     for (int p = 0; p < 32; ++p) { v[p] = cmulc(pb[17 * p], wp); wp = cmul(wp, w); }
	s_nop 0
	v_lshrrev_b32_e32 v1, 4, v0
	v_and_b32_e32 v0, 15, v0
	v_mul_lo_u32 v1, v1, s15
	v_lshlrev_b32_e32 v2, 3, v0
	v_cvt_f32_ubyte0_e32 v0, v0
	v_add3_u32 v86, v159, v1, v2
	v_mul_f32_e32 v0, 0xbb800000, v0
	v_mul_f32_e32 v0, 0.5, v0
	v_add_u32_e32 v232, 0x800, v86
	v_add_u32_e32 v233, 0xc00, v86
	ds_read2_b64 v[166:169], v86 offset1:17
	ds_read2_b64 v[170:173], v86 offset0:34 offset1:51
	ds_read2_b64 v[174:177], v86 offset0:68 offset1:85
	ds_read2_b64 v[178:181], v86 offset0:102 offset1:119
	ds_read2_b64 v[182:185], v86 offset0:136 offset1:153
	ds_read2_b64 v[186:189], v86 offset0:170 offset1:187
	ds_read2_b64 v[190:193], v86 offset0:204 offset1:221
	ds_read2_b64 v[194:197], v86 offset0:238 offset1:255
	ds_read2_b64 v[198:201], v232 offset0:16 offset1:33
	ds_read2_b64 v[202:205], v232 offset0:50 offset1:67
	ds_read2_b64 v[208:211], v232 offset0:84 offset1:101
	ds_read2_b64 v[214:217], v232 offset0:118 offset1:135
	ds_read2_b64 v[218:221], v232 offset0:152 offset1:169
	v_sin_f32_e32 v1, v0
	v_cos_f32_e32 v0, v0
	s_waitcnt lgkmcnt(12)
	v_pk_mul_f32 v[2:3], v[166:167], v[66:67] op_sel:[1,1] op_sel_hi:[1,0]
	v_pk_fma_f32 v[4:5], v[166:167], v[66:67], v[2:3] op_sel_hi:[0,1,1] neg_hi:[1,0,0]
	v_add_u32_e32 v87, 0x800, v86
	v_pk_mul_f32 v[2:3], v[66:67], v[0:1] op_sel:[1,1] op_sel_hi:[1,0] neg_lo:[1,0]
	v_pk_fma_f32 v[8:9], v[66:67], v[0:1], v[2:3] op_sel_hi:[0,1,1]
	v_pk_mul_f32 v[10:11], v[168:169], v[8:9] op_sel:[1,1] op_sel_hi:[1,0]
	v_pk_fma_f32 v[2:3], v[168:169], v[8:9], v[10:11] op_sel_hi:[0,1,1] neg_hi:[1,0,0]
	v_pk_mul_f32 v[6:7], v[8:9], v[0:1] op_sel:[1,1] op_sel_hi:[1,0] neg_lo:[1,0]
	v_pk_fma_f32 v[12:13], v[8:9], v[0:1], v[6:7] op_sel_hi:[0,1,1]
	ds_read2_b64 v[222:225], v232 offset0:186 offset1:203
	s_waitcnt lgkmcnt(12)
	v_pk_mul_f32 v[14:15], v[170:171], v[12:13] op_sel:[1,1] op_sel_hi:[1,0]
	v_pk_fma_f32 v[10:11], v[170:171], v[12:13], v[14:15] op_sel_hi:[0,1,1] neg_hi:[1,0,0]
	v_pk_mul_f32 v[6:7], v[12:13], v[0:1] op_sel:[1,1] op_sel_hi:[1,0] neg_lo:[1,0]
	v_pk_fma_f32 v[12:13], v[12:13], v[0:1], v[6:7] op_sel_hi:[0,1,1]
	v_pk_mul_f32 v[14:15], v[172:173], v[12:13] op_sel:[1,1] op_sel_hi:[1,0]
	v_pk_fma_f32 v[6:7], v[172:173], v[12:13], v[14:15] op_sel_hi:[0,1,1] neg_hi:[1,0,0]
	v_pk_mul_f32 v[8:9], v[12:13], v[0:1] op_sel:[1,1] op_sel_hi:[1,0] neg_lo:[1,0]
	v_pk_fma_f32 v[16:17], v[12:13], v[0:1], v[8:9] op_sel_hi:[0,1,1]
	ds_read2_b64 v[226:229], v232 offset0:220 offset1:237
	s_waitcnt lgkmcnt(12)
	v_pk_mul_f32 v[8:9], v[174:175], v[16:17] op_sel:[1,1] op_sel_hi:[1,0]
	v_pk_fma_f32 v[12:13], v[174:175], v[16:17], v[8:9] op_sel_hi:[0,1,1] neg_hi:[1,0,0]
	s_nop 0
	v_pk_mul_f32 v[8:9], v[16:17], v[0:1] op_sel:[1,1] op_sel_hi:[1,0] neg_lo:[1,0]
	v_pk_fma_f32 v[16:17], v[16:17], v[0:1], v[8:9] op_sel_hi:[0,1,1]
	v_pk_mul_f32 v[18:19], v[176:177], v[16:17] op_sel:[1,1] op_sel_hi:[1,0]
	v_pk_fma_f32 v[8:9], v[176:177], v[16:17], v[18:19] op_sel_hi:[0,1,1] neg_hi:[1,0,0]
	v_pk_mul_f32 v[14:15], v[16:17], v[0:1] op_sel:[1,1] op_sel_hi:[1,0] neg_lo:[1,0]
	v_pk_fma_f32 v[68:69], v[16:17], v[0:1], v[14:15] op_sel_hi:[0,1,1]
	ds_read2_b64 v[236:239], v233 offset0:126 offset1:143
	s_waitcnt lgkmcnt(12)
	v_pk_mul_f32 v[14:15], v[178:179], v[68:69] op_sel:[1,1] op_sel_hi:[1,0]
	v_pk_fma_f32 v[16:17], v[178:179], v[68:69], v[14:15] op_sel_hi:[0,1,1] neg_hi:[1,0,0]
	s_nop 0
	v_pk_mul_f32 v[14:15], v[68:69], v[0:1] op_sel:[1,1] op_sel_hi:[1,0] neg_lo:[1,0]
	v_pk_fma_f32 v[68:69], v[68:69], v[0:1], v[14:15] op_sel_hi:[0,1,1]
	v_pk_mul_f32 v[70:71], v[180:181], v[68:69] op_sel:[1,1] op_sel_hi:[1,0]
	v_pk_fma_f32 v[14:15], v[180:181], v[68:69], v[70:71] op_sel_hi:[0,1,1] neg_hi:[1,0,0]
	v_pk_mul_f32 v[18:19], v[68:69], v[0:1] op_sel:[1,1] op_sel_hi:[1,0] neg_lo:[1,0]
	v_pk_fma_f32 v[72:73], v[68:69], v[0:1], v[18:19] op_sel_hi:[0,1,1]
	s_waitcnt lgkmcnt(11)
	v_pk_mul_f32 v[18:19], v[182:183], v[72:73] op_sel:[1,1] op_sel_hi:[1,0]
	v_pk_fma_f32 v[68:69], v[182:183], v[72:73], v[18:19] op_sel_hi:[0,1,1] neg_hi:[1,0,0]
	s_nop 0
	v_pk_mul_f32 v[18:19], v[72:73], v[0:1] op_sel:[1,1] op_sel_hi:[1,0] neg_lo:[1,0]
	v_pk_fma_f32 v[72:73], v[72:73], v[0:1], v[18:19] op_sel_hi:[0,1,1]
	v_pk_mul_f32 v[74:75], v[184:185], v[72:73] op_sel:[1,1] op_sel_hi:[1,0]
	v_pk_fma_f32 v[18:19], v[184:185], v[72:73], v[74:75] op_sel_hi:[0,1,1] neg_hi:[1,0,0]
	v_pk_mul_f32 v[70:71], v[72:73], v[0:1] op_sel:[1,1] op_sel_hi:[1,0] neg_lo:[1,0]
	v_pk_fma_f32 v[76:77], v[72:73], v[0:1], v[70:71] op_sel_hi:[0,1,1]
	s_waitcnt lgkmcnt(10)
	v_pk_mul_f32 v[70:71], v[186:187], v[76:77] op_sel:[1,1] op_sel_hi:[1,0]
	v_pk_fma_f32 v[72:73], v[186:187], v[76:77], v[70:71] op_sel_hi:[0,1,1] neg_hi:[1,0,0]
	s_nop 0
	v_pk_mul_f32 v[70:71], v[76:77], v[0:1] op_sel:[1,1] op_sel_hi:[1,0] neg_lo:[1,0]
	v_pk_fma_f32 v[76:77], v[76:77], v[0:1], v[70:71] op_sel_hi:[0,1,1]
	v_pk_mul_f32 v[78:79], v[188:189], v[76:77] op_sel:[1,1] op_sel_hi:[1,0]
	v_pk_fma_f32 v[70:71], v[188:189], v[76:77], v[78:79] op_sel_hi:[0,1,1] neg_hi:[1,0,0]
	v_pk_mul_f32 v[74:75], v[76:77], v[0:1] op_sel:[1,1] op_sel_hi:[1,0] neg_lo:[1,0]
	v_pk_fma_f32 v[80:81], v[76:77], v[0:1], v[74:75] op_sel_hi:[0,1,1]
	s_waitcnt lgkmcnt(9)
	v_pk_mul_f32 v[74:75], v[190:191], v[80:81] op_sel:[1,1] op_sel_hi:[1,0]
	v_pk_fma_f32 v[76:77], v[190:191], v[80:81], v[74:75] op_sel_hi:[0,1,1] neg_hi:[1,0,0]
	s_nop 0
	v_pk_mul_f32 v[74:75], v[80:81], v[0:1] op_sel:[1,1] op_sel_hi:[1,0] neg_lo:[1,0]
	v_pk_fma_f32 v[80:81], v[80:81], v[0:1], v[74:75] op_sel_hi:[0,1,1]
	v_pk_mul_f32 v[82:83], v[192:193], v[80:81] op_sel:[1,1] op_sel_hi:[1,0]
	v_pk_fma_f32 v[74:75], v[192:193], v[80:81], v[82:83] op_sel_hi:[0,1,1] neg_hi:[1,0,0]
	v_pk_mul_f32 v[78:79], v[80:81], v[0:1] op_sel:[1,1] op_sel_hi:[1,0] neg_lo:[1,0]
	v_pk_fma_f32 v[84:85], v[80:81], v[0:1], v[78:79] op_sel_hi:[0,1,1]
	s_waitcnt lgkmcnt(8)
; #define LAS __attribute__((address_space(3)))
; #define SINCOSPI(x, s, c) do { const float hx_ = 0.5f * (x); *(s) = __builtin_amdgcn_sinf(hx_); *(c) = __builtin_amdgcn_cosf(hx_); } while (0)
; #define OPAQUE_I(x) asm volatile("" : "+v"(x))
; DEV void fft_i2(LAS cf* buf, int t8) {
;     OPAQUE_I(t8);
;     LAS cf* pb = buf + (t8 >> 4) * 544 + (t8 & 15);
;     float sn, cs; SINCOSPI(-(float)(t8 & 15) * (2.0f / 512.0f), &sn, &cs);
;     const cf w = cf{cs, sn}; cf wp = cf{1.f, 0.f};
;     cf v[32];
; #pragma unroll
;     for (int p = 0; p < 32; ++p) { v[p] = cmulc(pb[17 * p], wp); wp = cmul(wp, w); }
	v_pk_mul_f32 v[78:79], v[194:195], v[84:85] op_sel:[1,1] op_sel_hi:[1,0]
	v_pk_fma_f32 v[80:81], v[194:195], v[84:85], v[78:79] op_sel_hi:[0,1,1] neg_hi:[1,0,0]
	s_nop 0
	v_pk_mul_f32 v[78:79], v[84:85], v[0:1] op_sel:[1,1] op_sel_hi:[1,0] neg_lo:[1,0]
	v_pk_fma_f32 v[84:85], v[84:85], v[0:1], v[78:79] op_sel_hi:[0,1,1]
	v_pk_mul_f32 v[88:89], v[196:197], v[84:85] op_sel:[1,1] op_sel_hi:[1,0]
	v_pk_fma_f32 v[78:79], v[196:197], v[84:85], v[88:89] op_sel_hi:[0,1,1] neg_hi:[1,0,0]
	v_pk_mul_f32 v[82:83], v[84:85], v[0:1] op_sel:[1,1] op_sel_hi:[1,0] neg_lo:[1,0]
	v_pk_fma_f32 v[92:93], v[84:85], v[0:1], v[82:83] op_sel_hi:[0,1,1]
	s_waitcnt lgkmcnt(7)
	v_pk_mul_f32 v[82:83], v[198:199], v[92:93] op_sel:[1,1] op_sel_hi:[1,0]
	v_pk_fma_f32 v[84:85], v[198:199], v[92:93], v[82:83] op_sel_hi:[0,1,1] neg_hi:[1,0,0]
	s_nop 0
	v_pk_mul_f32 v[82:83], v[92:93], v[0:1] op_sel:[1,1] op_sel_hi:[1,0] neg_lo:[1,0]
	v_pk_fma_f32 v[88:89], v[92:93], v[0:1], v[82:83] op_sel_hi:[0,1,1]
	v_pk_mul_f32 v[92:93], v[200:201], v[88:89] op_sel:[1,1] op_sel_hi:[1,0]
	v_pk_fma_f32 v[82:83], v[200:201], v[88:89], v[92:93] op_sel_hi:[0,1,1] neg_hi:[1,0,0]
	s_nop 0
	v_pk_mul_f32 v[90:91], v[88:89], v[0:1] op_sel:[1,1] op_sel_hi:[1,0] neg_lo:[1,0]
	v_pk_fma_f32 v[92:93], v[88:89], v[0:1], v[90:91] op_sel_hi:[0,1,1]
	s_waitcnt lgkmcnt(6)
	v_pk_mul_f32 v[96:97], v[202:203], v[92:93] op_sel:[1,1] op_sel_hi:[1,0]
	v_pk_fma_f32 v[94:95], v[202:203], v[92:93], v[96:97] op_sel_hi:[0,1,1] neg_hi:[1,0,0]
	v_pk_mul_f32 v[88:89], v[92:93], v[0:1] op_sel:[1,1] op_sel_hi:[1,0] neg_lo:[1,0]
	v_pk_fma_f32 v[92:93], v[92:93], v[0:1], v[88:89] op_sel_hi:[0,1,1]
	v_pk_mul_f32 v[88:89], v[204:205], v[92:93] op_sel:[1,1] op_sel_hi:[1,0]
	v_pk_fma_f32 v[96:97], v[204:205], v[92:93], v[88:89] op_sel_hi:[0,1,1] neg_hi:[1,0,0]
	s_nop 0
	v_pk_mul_f32 v[88:89], v[92:93], v[0:1] op_sel:[1,1] op_sel_hi:[1,0] neg_lo:[1,0]
	v_pk_fma_f32 v[92:93], v[92:93], v[0:1], v[88:89] op_sel_hi:[0,1,1]
	s_waitcnt lgkmcnt(5)
	v_pk_mul_f32 v[100:101], v[208:209], v[92:93] op_sel:[1,1] op_sel_hi:[1,0]
	v_pk_fma_f32 v[98:99], v[208:209], v[92:93], v[100:101] op_sel_hi:[0,1,1] neg_hi:[1,0,0]
	v_pk_mul_f32 v[88:89], v[92:93], v[0:1] op_sel:[1,1] op_sel_hi:[1,0] neg_lo:[1,0]
	v_pk_fma_f32 v[92:93], v[92:93], v[0:1], v[88:89] op_sel_hi:[0,1,1]
	v_pk_mul_f32 v[88:89], v[210:211], v[92:93] op_sel:[1,1] op_sel_hi:[1,0]
	v_pk_fma_f32 v[100:101], v[210:211], v[92:93], v[88:89] op_sel_hi:[0,1,1] neg_hi:[1,0,0]
	s_nop 0
	v_pk_mul_f32 v[88:89], v[92:93], v[0:1] op_sel:[1,1] op_sel_hi:[1,0] neg_lo:[1,0]
	v_pk_fma_f32 v[92:93], v[92:93], v[0:1], v[88:89] op_sel_hi:[0,1,1]
	s_waitcnt lgkmcnt(4)
	v_pk_mul_f32 v[104:105], v[214:215], v[92:93] op_sel:[1,1] op_sel_hi:[1,0]
	v_pk_fma_f32 v[102:103], v[214:215], v[92:93], v[104:105] op_sel_hi:[0,1,1] neg_hi:[1,0,0]
	v_pk_mul_f32 v[88:89], v[92:93], v[0:1] op_sel:[1,1] op_sel_hi:[1,0] neg_lo:[1,0]
	v_pk_fma_f32 v[92:93], v[92:93], v[0:1], v[88:89] op_sel_hi:[0,1,1]
	v_pk_mul_f32 v[88:89], v[216:217], v[92:93] op_sel:[1,1] op_sel_hi:[1,0]
	v_pk_fma_f32 v[104:105], v[216:217], v[92:93], v[88:89] op_sel_hi:[0,1,1] neg_hi:[1,0,0]
	s_nop 0
	v_pk_mul_f32 v[88:89], v[92:93], v[0:1] op_sel:[1,1] op_sel_hi:[1,0] neg_lo:[1,0]
	v_pk_fma_f32 v[92:93], v[92:93], v[0:1], v[88:89] op_sel_hi:[0,1,1]
	s_waitcnt lgkmcnt(3)
	v_pk_mul_f32 v[108:109], v[218:219], v[92:93] op_sel:[1,1] op_sel_hi:[1,0]
	v_pk_fma_f32 v[106:107], v[218:219], v[92:93], v[108:109] op_sel_hi:[0,1,1] neg_hi:[1,0,0]
	v_pk_mul_f32 v[88:89], v[92:93], v[0:1] op_sel:[1,1] op_sel_hi:[1,0] neg_lo:[1,0]
	v_pk_fma_f32 v[92:93], v[92:93], v[0:1], v[88:89] op_sel_hi:[0,1,1]
	v_pk_mul_f32 v[88:89], v[220:221], v[92:93] op_sel:[1,1] op_sel_hi:[1,0]
	v_pk_fma_f32 v[108:109], v[220:221], v[92:93], v[88:89] op_sel_hi:[0,1,1] neg_hi:[1,0,0]
	s_nop 0
	v_pk_mul_f32 v[88:89], v[92:93], v[0:1] op_sel:[1,1] op_sel_hi:[1,0] neg_lo:[1,0]
	v_pk_fma_f32 v[92:93], v[92:93], v[0:1], v[88:89] op_sel_hi:[0,1,1]
	s_waitcnt lgkmcnt(2)
	v_pk_mul_f32 v[112:113], v[222:223], v[92:93] op_sel:[1,1] op_sel_hi:[1,0]
	v_pk_fma_f32 v[110:111], v[222:223], v[92:93], v[112:113] op_sel_hi:[0,1,1] neg_hi:[1,0,0]
	v_pk_mul_f32 v[88:89], v[92:93], v[0:1] op_sel:[1,1] op_sel_hi:[1,0] neg_lo:[1,0]
	v_pk_fma_f32 v[92:93], v[92:93], v[0:1], v[88:89] op_sel_hi:[0,1,1]
	v_pk_mul_f32 v[88:89], v[224:225], v[92:93] op_sel:[1,1] op_sel_hi:[1,0]
	v_pk_fma_f32 v[112:113], v[224:225], v[92:93], v[88:89] op_sel_hi:[0,1,1] neg_hi:[1,0,0]
	s_nop 0
	v_pk_mul_f32 v[88:89], v[92:93], v[0:1] op_sel:[1,1] op_sel_hi:[1,0] neg_lo:[1,0]
	v_pk_fma_f32 v[92:93], v[92:93], v[0:1], v[88:89] op_sel_hi:[0,1,1]
	s_waitcnt lgkmcnt(1)
	v_pk_mul_f32 v[116:117], v[226:227], v[92:93] op_sel:[1,1] op_sel_hi:[1,0]
	v_pk_fma_f32 v[114:115], v[226:227], v[92:93], v[116:117] op_sel_hi:[0,1,1] neg_hi:[1,0,0]
	v_pk_mul_f32 v[88:89], v[92:93], v[0:1] op_sel:[1,1] op_sel_hi:[1,0] neg_lo:[1,0]
	v_pk_fma_f32 v[92:93], v[92:93], v[0:1], v[88:89] op_sel_hi:[0,1,1]
	v_pk_mul_f32 v[88:89], v[228:229], v[92:93] op_sel:[1,1] op_sel_hi:[1,0]
	v_pk_fma_f32 v[116:117], v[228:229], v[92:93], v[88:89] op_sel_hi:[0,1,1] neg_hi:[1,0,0]
	s_nop 0
	v_pk_mul_f32 v[88:89], v[92:93], v[0:1] op_sel:[1,1] op_sel_hi:[1,0] neg_lo:[1,0]
	v_pk_fma_f32 v[118:119], v[92:93], v[0:1], v[88:89] op_sel_hi:[0,1,1]
	s_nop 0
	v_add_u32_e32 v88, 0xc00, v86
	v_pk_mul_f32 v[120:121], v[118:119], v[0:1] op_sel:[1,1] op_sel_hi:[1,0] neg_lo:[1,0]
	v_pk_fma_f32 v[0:1], v[118:119], v[0:1], v[120:121] op_sel_hi:[0,1,1]
	s_waitcnt lgkmcnt(0)
; template <int R, bool INV> DEV void dft_regs(cf (&v)[R]) {
; #pragma unroll
;     for (int s = R; s >= 2; s >>= 1) {
;         const int h = s >> 1;
; #pragma unroll
;         for (int b = 0; b < R; b += s) {
; #pragma unroll
;             for (int k = 0; k < h; ++k) {
;                 const cf a = v[b + k], c = v[b + k + h];
;                 v[b + k] = a + c;
;                 const cf d = a - c;
;                 const int m = k * (32 / s);
;                 const float wr = tw_cos(m), wi = INV ? tw_sin(m) : -tw_sin(m);
;                 v[b + k + h] = cf{d.x * wr - d.y * wi, d.x * wi + d.y * wr};
;             }
;         }
;     }
; DEV void fft_i2(LAS cf* buf, int t8) {
;     ...
;     for (int p = 0; p < 32; ++p) { v[p] = cmulc(pb[17 * p], wp); wp = cmul(wp, w); }
;     dft_regs<32, true>(v);
	v_pk_mul_f32 v[120:121], v[236:237], v[118:119] op_sel:[1,1] op_sel_hi:[1,0]
	v_pk_fma_f32 v[90:91], v[236:237], v[118:119], v[120:121] op_sel_hi:[0,1,1] neg_hi:[1,0,0]
	v_pk_mul_f32 v[118:119], v[238:239], v[0:1] op_sel:[1,1] op_sel_hi:[1,0]
	v_pk_fma_f32 v[0:1], v[238:239], v[0:1], v[118:119] op_sel_hi:[0,1,1] neg_hi:[1,0,0]
	v_pk_add_f32 v[92:93], v[4:5], v[84:85]
	v_pk_add_f32 v[4:5], v[4:5], v[84:85] neg_lo:[0,1] neg_hi:[0,1]
	v_pk_mul_f32 v[84:85], v[4:5], 0 op_sel_hi:[1,0]
	v_pk_add_f32 v[118:119], v[4:5], v[84:85] op_sel:[0,1] op_sel_hi:[1,0]
	v_pk_add_f32 v[4:5], v[4:5], v[84:85] op_sel:[0,1] op_sel_hi:[1,0] neg_lo:[0,1] neg_hi:[0,1]
	v_mov_b32_e32 v119, v5
	v_pk_add_f32 v[4:5], v[2:3], v[82:83]
	v_pk_add_f32 v[2:3], v[2:3], v[82:83] neg_lo:[0,1] neg_hi:[0,1]
	v_pk_mul_f32 v[82:83], v[2:3], s[82:83] op_sel_hi:[1,0]
	v_pk_fma_f32 v[84:85], v[2:3], s[94:95], v[82:83] op_sel:[0,0,1] op_sel_hi:[1,0,0] neg_lo:[0,0,1] neg_hi:[0,0,1]
	v_pk_fma_f32 v[2:3], v[2:3], s[94:95], v[82:83] op_sel:[0,0,1] op_sel_hi:[1,0,0]
	v_mov_b32_e32 v85, v3
	v_pk_add_f32 v[2:3], v[10:11], v[94:95]
	v_pk_add_f32 v[10:11], v[10:11], v[94:95] neg_lo:[0,1] neg_hi:[0,1]
	v_pk_mul_f32 v[82:83], v[10:11], s[84:85] op_sel_hi:[1,0]
	v_pk_fma_f32 v[94:95], v[10:11], s[16:17], v[82:83] op_sel:[0,0,1] op_sel_hi:[1,0,0] neg_lo:[0,0,1] neg_hi:[0,0,1]
	v_pk_fma_f32 v[10:11], v[10:11], s[16:17], v[82:83] op_sel:[0,0,1] op_sel_hi:[1,0,0]
	v_mov_b32_e32 v95, v11
	v_pk_add_f32 v[10:11], v[6:7], v[96:97]
	v_pk_add_f32 v[6:7], v[6:7], v[96:97] neg_lo:[0,1] neg_hi:[0,1]
	v_pk_mul_f32 v[82:83], v[6:7], s[4:5] op_sel_hi:[1,0]
	v_pk_fma_f32 v[96:97], v[6:7], s[86:87], v[82:83] op_sel:[0,0,1] op_sel_hi:[1,0,0] neg_lo:[0,0,1] neg_hi:[0,0,1]
	v_pk_fma_f32 v[6:7], v[6:7], s[86:87], v[82:83] op_sel:[0,0,1] op_sel_hi:[1,0,0]
	v_mov_b32_e32 v97, v7
	v_pk_add_f32 v[6:7], v[12:13], v[98:99]
	v_pk_add_f32 v[12:13], v[12:13], v[98:99] neg_lo:[0,1] neg_hi:[0,1]
	v_pk_mul_f32 v[82:83], v[12:13], s[18:19] op_sel_hi:[1,0]
	v_pk_fma_f32 v[98:99], v[12:13], s[18:19], v[82:83] op_sel:[0,0,1] op_sel_hi:[1,0,0] neg_lo:[0,0,1] neg_hi:[0,0,1]
	v_pk_fma_f32 v[12:13], v[12:13], s[18:19], v[82:83] op_sel_hi:[1,0,0]
	v_mov_b32_e32 v99, v13
	v_pk_add_f32 v[12:13], v[8:9], v[100:101]
	v_pk_add_f32 v[8:9], v[8:9], v[100:101] neg_lo:[0,1] neg_hi:[0,1]
	v_pk_mul_f32 v[82:83], v[8:9], s[86:87] op_sel_hi:[1,0]
	v_pk_fma_f32 v[100:101], v[8:9], s[4:5], v[82:83] op_sel:[0,0,1] op_sel_hi:[1,0,0] neg_lo:[0,0,1] neg_hi:[0,0,1]
	v_pk_fma_f32 v[8:9], v[8:9], s[4:5], v[82:83] op_sel:[0,0,1] op_sel_hi:[1,0,0]
	v_mov_b32_e32 v101, v9
	v_pk_add_f32 v[8:9], v[16:17], v[102:103]
	v_pk_add_f32 v[16:17], v[16:17], v[102:103] neg_lo:[0,1] neg_hi:[0,1]
	v_pk_mul_f32 v[82:83], v[16:17], s[16:17] op_sel_hi:[1,0]
	v_pk_fma_f32 v[102:103], v[16:17], s[84:85], v[82:83] op_sel:[0,0,1] op_sel_hi:[1,0,0] neg_lo:[0,0,1] neg_hi:[0,0,1]
	v_pk_fma_f32 v[16:17], v[16:17], s[84:85], v[82:83] op_sel:[0,0,1] op_sel_hi:[1,0,0]
	v_mov_b32_e32 v103, v17
	v_pk_add_f32 v[16:17], v[14:15], v[104:105]
	v_pk_add_f32 v[14:15], v[14:15], v[104:105] neg_lo:[0,1] neg_hi:[0,1]
	v_pk_mul_f32 v[82:83], v[14:15], s[94:95] op_sel_hi:[1,0]
	v_pk_fma_f32 v[104:105], v[14:15], s[82:83], v[82:83] op_sel:[0,0,1] op_sel_hi:[1,0,0] neg_lo:[0,0,1] neg_hi:[0,0,1]
	v_pk_fma_f32 v[14:15], v[14:15], s[82:83], v[82:83] op_sel:[0,0,1] op_sel_hi:[1,0,0]
	v_mov_b32_e32 v105, v15
	v_pk_add_f32 v[14:15], v[68:69], v[106:107]
	v_pk_add_f32 v[68:69], v[68:69], v[106:107] neg_lo:[0,1] neg_hi:[0,1]
	v_pk_fma_f32 v[82:83], v[68:69], 0, v[68:69] op_sel:[0,0,1] op_sel_hi:[1,0,0] neg_lo:[0,0,1] neg_hi:[0,0,1]
	v_pk_fma_f32 v[68:69], v[68:69], 0, v[68:69] op_sel:[0,0,1] op_sel_hi:[1,0,0]
	v_mov_b32_e32 v83, v69
	v_pk_add_f32 v[68:69], v[18:19], v[108:109]
	v_pk_add_f32 v[18:19], v[18:19], v[108:109] neg_lo:[0,1] neg_hi:[0,1]
	v_pk_mul_f32 v[106:107], v[18:19], s[6:7] op_sel:[1,0]
	s_mov_b32 s6, s87
	v_pk_fma_f32 v[18:19], v[18:19], s[28:29], v[106:107] op_sel_hi:[0,1,1] neg_lo:[0,0,1] neg_hi:[0,0,1]
	v_pk_add_f32 v[106:107], v[72:73], v[110:111]
	v_pk_add_f32 v[72:73], v[72:73], v[110:111] neg_lo:[0,1] neg_hi:[0,1]
	s_mov_b32 s7, s86
	v_pk_mul_f32 v[108:109], v[72:73], s[24:25] op_sel:[1,0]
	v_pk_fma_f32 v[72:73], v[72:73], s[0:1], v[108:109] op_sel_hi:[0,1,1] neg_lo:[0,0,1] neg_hi:[0,0,1]
	v_pk_add_f32 v[108:109], v[70:71], v[112:113]
	v_pk_add_f32 v[70:71], v[70:71], v[112:113] neg_lo:[0,1] neg_hi:[0,1]
	v_pk_mul_f32 v[110:111], v[70:71], s[2:3] op_sel:[1,0]
	s_mov_b32 s2, s11
	v_pk_fma_f32 v[70:71], v[70:71], s[6:7], v[110:111] op_sel_hi:[0,1,1] neg_lo:[0,0,1] neg_hi:[0,0,1]
	v_pk_add_f32 v[110:111], v[76:77], v[114:115]
	v_pk_add_f32 v[76:77], v[76:77], v[114:115] neg_lo:[0,1] neg_hi:[0,1]
	v_mul_f32_e32 v112, 0x3f3504f3, v77
	v_pk_fma_f32 v[76:77], v[76:77], s[96:97], v[112:113] op_sel_hi:[0,1,0] neg_lo:[0,0,1] neg_hi:[0,0,1]
	v_pk_add_f32 v[112:113], v[74:75], v[116:117]
	v_pk_add_f32 v[74:75], v[74:75], v[116:117] neg_lo:[0,1] neg_hi:[0,1]
	v_pk_mul_f32 v[114:115], v[74:75], s[4:5] op_sel:[1,0]
	s_lshl_b32 s5, s19, 10
	v_pk_fma_f32 v[74:75], v[74:75], s[2:3], v[114:115] op_sel_hi:[0,1,1] neg_lo:[0,0,1] neg_hi:[0,0,1]
	v_pk_add_f32 v[114:115], v[80:81], v[90:91]
	v_pk_add_f32 v[80:81], v[80:81], v[90:91] neg_lo:[0,1] neg_hi:[0,1]
	s_mov_b32 s2, s9
	v_pk_mul_f32 v[90:91], v[80:81], s[84:85] op_sel:[1,0]
	s_mov_b32 s3, s82
	v_pk_fma_f32 v[80:81], v[80:81], s[88:89], v[90:91] op_sel_hi:[0,1,1] neg_lo:[0,0,1] neg_hi:[0,0,1]
	v_pk_add_f32 v[90:91], v[78:79], v[0:1]
	v_pk_add_f32 v[0:1], v[78:79], v[0:1] neg_lo:[0,1] neg_hi:[0,1]
	s_add_i32 s6, s79, s5
	v_pk_mul_f32 v[78:79], v[0:1], s[82:83] op_sel:[1,0]
; template <int R, bool INV> DEV void dft_regs(cf (&v)[R]) {
; #pragma unroll
;     for (int s = R; s >= 2; s >>= 1) {
;         const int h = s >> 1;
; #pragma unroll
;         for (int b = 0; b < R; b += s) {
; #pragma unroll
;             for (int k = 0; k < h; ++k) {
;                 const cf a = v[b + k], c = v[b + k + h];
;                 v[b + k] = a + c;
;                 const cf d = a - c;
;                 const int m = k * (32 / s);
;                 const float wr = tw_cos(m), wi = INV ? tw_sin(m) : -tw_sin(m);
;                 v[b + k + h] = cf{d.x * wr - d.y * wi, d.x * wi + d.y * wr};
;             }
;         }
;     }
; DEV void hyena_issue_rows(const bf16_t* UT, int s, int c, u32x4 (&r)[4], int tid) {
; #pragma unroll
;     for (int b = 0; b < 4; ++b) r[b] = *(const u32x4*)(UT + ((size_t)(b * 3072 + s * 1024 + c)) * 4096 + tid * 8);
	s_ashr_i32 s7, s6, 31
	v_pk_fma_f32 v[0:1], v[0:1], s[2:3], v[78:79] op_sel_hi:[0,1,1] neg_lo:[0,0,1] neg_hi:[0,0,1]
	v_pk_add_f32 v[78:79], v[92:93], v[14:15]
	v_pk_add_f32 v[14:15], v[92:93], v[14:15] neg_lo:[0,1] neg_hi:[0,1]
	s_lshl_b64 s[2:3], s[6:7], 13
	v_pk_mul_f32 v[92:93], v[14:15], 0 op_sel_hi:[1,0]
	v_pk_add_f32 v[116:117], v[14:15], v[92:93] op_sel:[0,1] op_sel_hi:[1,0]
	v_pk_add_f32 v[14:15], v[14:15], v[92:93] op_sel:[0,1] op_sel_hi:[1,0] neg_lo:[0,1] neg_hi:[0,1]
	v_mov_b32_e32 v117, v15
	v_pk_add_f32 v[14:15], v[4:5], v[68:69]
	v_pk_add_f32 v[4:5], v[4:5], v[68:69] neg_lo:[0,1] neg_hi:[0,1]
	v_pk_mul_f32 v[68:69], v[4:5], s[84:85] op_sel_hi:[1,0]
	v_pk_fma_f32 v[92:93], v[4:5], s[16:17], v[68:69] op_sel:[0,0,1] op_sel_hi:[1,0,0] neg_lo:[0,0,1] neg_hi:[0,0,1]
	v_pk_fma_f32 v[4:5], v[4:5], s[16:17], v[68:69] op_sel:[0,0,1] op_sel_hi:[1,0,0]
	v_mov_b32_e32 v93, v5
	v_pk_add_f32 v[4:5], v[2:3], v[106:107]
	v_pk_add_f32 v[2:3], v[2:3], v[106:107] neg_lo:[0,1] neg_hi:[0,1]
	v_pk_mul_f32 v[68:69], v[2:3], s[18:19] op_sel_hi:[1,0]
	v_pk_fma_f32 v[106:107], v[2:3], s[18:19], v[68:69] op_sel:[0,0,1] op_sel_hi:[1,0,0] neg_lo:[0,0,1] neg_hi:[0,0,1]
	v_pk_fma_f32 v[2:3], v[2:3], s[18:19], v[68:69] op_sel_hi:[1,0,0]
	v_mov_b32_e32 v107, v3
	v_pk_add_f32 v[2:3], v[10:11], v[108:109]
	v_pk_add_f32 v[10:11], v[10:11], v[108:109] neg_lo:[0,1] neg_hi:[0,1]
	v_pk_mul_f32 v[68:69], v[10:11], s[16:17] op_sel_hi:[1,0]
	v_pk_fma_f32 v[108:109], v[10:11], s[84:85], v[68:69] op_sel:[0,0,1] op_sel_hi:[1,0,0] neg_lo:[0,0,1] neg_hi:[0,0,1]
	v_pk_fma_f32 v[10:11], v[10:11], s[84:85], v[68:69] op_sel:[0,0,1] op_sel_hi:[1,0,0]
	v_mov_b32_e32 v109, v11
	v_pk_add_f32 v[10:11], v[6:7], v[110:111]
	v_pk_add_f32 v[6:7], v[6:7], v[110:111] neg_lo:[0,1] neg_hi:[0,1]
	v_pk_fma_f32 v[68:69], v[6:7], 0, v[6:7] op_sel:[0,0,1] op_sel_hi:[1,0,0] neg_lo:[0,0,1] neg_hi:[0,0,1]
	v_pk_fma_f32 v[6:7], v[6:7], 0, v[6:7] op_sel:[0,0,1] op_sel_hi:[1,0,0]
	v_mov_b32_e32 v69, v7
	v_pk_add_f32 v[6:7], v[12:13], v[112:113]
	v_pk_add_f32 v[12:13], v[12:13], v[112:113] neg_lo:[0,1] neg_hi:[0,1]
	v_pk_mul_f32 v[110:111], v[12:13], s[24:25] op_sel:[1,0]
	v_pk_fma_f32 v[12:13], v[12:13], s[0:1], v[110:111] op_sel_hi:[0,1,1] neg_lo:[0,0,1] neg_hi:[0,0,1]
	v_pk_add_f32 v[110:111], v[8:9], v[114:115]
	v_pk_add_f32 v[8:9], v[8:9], v[114:115] neg_lo:[0,1] neg_hi:[0,1]
	v_mul_f32_e32 v112, 0x3f3504f3, v9
	v_pk_fma_f32 v[8:9], v[8:9], s[96:97], v[112:113] op_sel_hi:[0,1,0] neg_lo:[0,0,1] neg_hi:[0,0,1]
	v_pk_add_f32 v[112:113], v[16:17], v[90:91]
	v_pk_add_f32 v[16:17], v[16:17], v[90:91] neg_lo:[0,1] neg_hi:[0,1]
	v_pk_mul_f32 v[90:91], v[16:17], s[84:85] op_sel:[1,0]
	v_pk_fma_f32 v[16:17], v[16:17], s[88:89], v[90:91] op_sel_hi:[0,1,1] neg_lo:[0,0,1] neg_hi:[0,0,1]
	v_pk_add_f32 v[90:91], v[118:119], v[82:83]
	v_pk_add_f32 v[82:83], v[118:119], v[82:83] neg_lo:[0,1] neg_hi:[0,1]
	v_pk_mul_f32 v[114:115], v[82:83], 0 op_sel_hi:[1,0]
	v_pk_add_f32 v[118:119], v[82:83], v[114:115] op_sel:[0,1] op_sel_hi:[1,0]
	v_pk_add_f32 v[82:83], v[82:83], v[114:115] op_sel:[0,1] op_sel_hi:[1,0] neg_lo:[0,1] neg_hi:[0,1]
	v_mov_b32_e32 v119, v83
	v_pk_add_f32 v[82:83], v[84:85], v[18:19]
	v_pk_add_f32 v[18:19], v[84:85], v[18:19] neg_lo:[0,1] neg_hi:[0,1]
	v_pk_mul_f32 v[84:85], v[18:19], s[84:85] op_sel_hi:[1,0]
	v_pk_fma_f32 v[114:115], v[18:19], s[16:17], v[84:85] op_sel:[0,0,1] op_sel_hi:[1,0,0] neg_lo:[0,0,1] neg_hi:[0,0,1]
	v_pk_fma_f32 v[18:19], v[18:19], s[16:17], v[84:85] op_sel:[0,0,1] op_sel_hi:[1,0,0]
	v_mov_b32_e32 v115, v19
	v_pk_add_f32 v[18:19], v[94:95], v[72:73]
	v_pk_add_f32 v[72:73], v[94:95], v[72:73] neg_lo:[0,1] neg_hi:[0,1]
	v_pk_mul_f32 v[84:85], v[72:73], s[18:19] op_sel_hi:[1,0]
	v_pk_fma_f32 v[94:95], v[72:73], s[18:19], v[84:85] op_sel:[0,0,1] op_sel_hi:[1,0,0] neg_lo:[0,0,1] neg_hi:[0,0,1]
	v_pk_fma_f32 v[72:73], v[72:73], s[18:19], v[84:85] op_sel_hi:[1,0,0]
	v_mov_b32_e32 v95, v73
	v_pk_add_f32 v[72:73], v[96:97], v[70:71]
	v_pk_add_f32 v[70:71], v[96:97], v[70:71] neg_lo:[0,1] neg_hi:[0,1]
	v_pk_mul_f32 v[84:85], v[70:71], s[16:17] op_sel_hi:[1,0]
	v_pk_fma_f32 v[96:97], v[70:71], s[84:85], v[84:85] op_sel:[0,0,1] op_sel_hi:[1,0,0] neg_lo:[0,0,1] neg_hi:[0,0,1]
	v_pk_fma_f32 v[70:71], v[70:71], s[84:85], v[84:85] op_sel:[0,0,1] op_sel_hi:[1,0,0]
	v_mov_b32_e32 v97, v71
	v_pk_add_f32 v[70:71], v[98:99], v[76:77]
	v_pk_add_f32 v[76:77], v[98:99], v[76:77] neg_lo:[0,1] neg_hi:[0,1]
	v_pk_fma_f32 v[84:85], v[76:77], 0, v[76:77] op_sel:[0,0,1] op_sel_hi:[1,0,0] neg_lo:[0,0,1] neg_hi:[0,0,1]
	v_pk_fma_f32 v[76:77], v[76:77], 0, v[76:77] op_sel:[0,0,1] op_sel_hi:[1,0,0]
	v_mov_b32_e32 v85, v77
	v_pk_add_f32 v[76:77], v[100:101], v[74:75]
	v_pk_add_f32 v[74:75], v[100:101], v[74:75] neg_lo:[0,1] neg_hi:[0,1]
	v_pk_mul_f32 v[98:99], v[74:75], s[24:25] op_sel:[1,0]
	v_pk_fma_f32 v[74:75], v[74:75], s[0:1], v[98:99] op_sel_hi:[0,1,1] neg_lo:[0,0,1] neg_hi:[0,0,1]
	v_pk_add_f32 v[98:99], v[102:103], v[80:81]
	v_pk_add_f32 v[80:81], v[102:103], v[80:81] neg_lo:[0,1] neg_hi:[0,1]
	v_mul_f32_e32 v100, 0x3f3504f3, v81
	v_pk_fma_f32 v[80:81], v[80:81], s[96:97], v[100:101] op_sel_hi:[0,1,0] neg_lo:[0,0,1] neg_hi:[0,0,1]
	v_pk_add_f32 v[100:101], v[104:105], v[0:1]
	v_pk_add_f32 v[0:1], v[104:105], v[0:1] neg_lo:[0,1] neg_hi:[0,1]
	v_pk_mul_f32 v[102:103], v[0:1], s[84:85] op_sel:[1,0]
	v_pk_fma_f32 v[0:1], v[0:1], s[88:89], v[102:103] op_sel_hi:[0,1,1] neg_lo:[0,0,1] neg_hi:[0,0,1]
	v_pk_add_f32 v[102:103], v[78:79], v[10:11]
	v_pk_add_f32 v[10:11], v[78:79], v[10:11] neg_lo:[0,1] neg_hi:[0,1]
	v_pk_mul_f32 v[78:79], v[10:11], 0 op_sel_hi:[1,0]
	v_pk_add_f32 v[104:105], v[10:11], v[78:79] op_sel:[0,1] op_sel_hi:[1,0]
; template <int R, bool INV> DEV void dft_regs(cf (&v)[R]) {
; #pragma unroll
;     for (int s = R; s >= 2; s >>= 1) {
;         const int h = s >> 1;
; #pragma unroll
;         for (int b = 0; b < R; b += s) {
; #pragma unroll
;             for (int k = 0; k < h; ++k) {
;                 const cf a = v[b + k], c = v[b + k + h];
;                 v[b + k] = a + c;
;                 const cf d = a - c;
;                 const int m = k * (32 / s);
;                 const float wr = tw_cos(m), wi = INV ? tw_sin(m) : -tw_sin(m);
;                 v[b + k + h] = cf{d.x * wr - d.y * wi, d.x * wi + d.y * wr};
;             }
;         }
;     }
	v_pk_add_f32 v[10:11], v[10:11], v[78:79] op_sel:[0,1] op_sel_hi:[1,0] neg_lo:[0,1] neg_hi:[0,1]
	v_mov_b32_e32 v105, v11
	v_pk_add_f32 v[10:11], v[14:15], v[6:7]
	v_pk_add_f32 v[6:7], v[14:15], v[6:7] neg_lo:[0,1] neg_hi:[0,1]
	v_pk_mul_f32 v[14:15], v[6:7], s[18:19] op_sel_hi:[1,0]
	v_pk_fma_f32 v[78:79], v[6:7], s[18:19], v[14:15] op_sel:[0,0,1] op_sel_hi:[1,0,0] neg_lo:[0,0,1] neg_hi:[0,0,1]
	v_pk_fma_f32 v[6:7], v[6:7], s[18:19], v[14:15] op_sel_hi:[1,0,0]
	v_mov_b32_e32 v79, v7
	v_pk_add_f32 v[6:7], v[4:5], v[110:111]
	v_pk_add_f32 v[4:5], v[4:5], v[110:111] neg_lo:[0,1] neg_hi:[0,1]
	v_pk_fma_f32 v[14:15], v[4:5], 0, v[4:5] op_sel:[0,0,1] op_sel_hi:[1,0,0] neg_lo:[0,0,1] neg_hi:[0,0,1]
	v_pk_fma_f32 v[4:5], v[4:5], 0, v[4:5] op_sel:[0,0,1] op_sel_hi:[1,0,0]
	v_mov_b32_e32 v15, v5
	v_pk_add_f32 v[4:5], v[2:3], v[112:113]
	v_pk_add_f32 v[2:3], v[2:3], v[112:113] neg_lo:[0,1] neg_hi:[0,1]
	v_mul_f32_e32 v110, 0x3f3504f3, v3
	v_pk_fma_f32 v[2:3], v[2:3], s[96:97], v[110:111] op_sel_hi:[0,1,0] neg_lo:[0,0,1] neg_hi:[0,0,1]
	v_pk_add_f32 v[110:111], v[116:117], v[68:69]
	v_pk_add_f32 v[68:69], v[116:117], v[68:69] neg_lo:[0,1] neg_hi:[0,1]
	v_pk_mul_f32 v[112:113], v[68:69], 0 op_sel_hi:[1,0]
	v_pk_add_f32 v[116:117], v[68:69], v[112:113] op_sel:[0,1] op_sel_hi:[1,0]
	v_pk_add_f32 v[68:69], v[68:69], v[112:113] op_sel:[0,1] op_sel_hi:[1,0] neg_lo:[0,1] neg_hi:[0,1]
	v_mov_b32_e32 v117, v69
	v_pk_add_f32 v[68:69], v[92:93], v[12:13]
	v_pk_add_f32 v[12:13], v[92:93], v[12:13] neg_lo:[0,1] neg_hi:[0,1]
	v_pk_mul_f32 v[92:93], v[12:13], s[18:19] op_sel_hi:[1,0]
	v_pk_fma_f32 v[112:113], v[12:13], s[18:19], v[92:93] op_sel:[0,0,1] op_sel_hi:[1,0,0] neg_lo:[0,0,1] neg_hi:[0,0,1]
	v_pk_fma_f32 v[12:13], v[12:13], s[18:19], v[92:93] op_sel_hi:[1,0,0]
	v_mov_b32_e32 v113, v13
	v_pk_add_f32 v[12:13], v[106:107], v[8:9]
	v_pk_add_f32 v[8:9], v[106:107], v[8:9] neg_lo:[0,1] neg_hi:[0,1]
	v_pk_fma_f32 v[92:93], v[8:9], 0, v[8:9] op_sel:[0,0,1] op_sel_hi:[1,0,0] neg_lo:[0,0,1] neg_hi:[0,0,1]
	v_pk_fma_f32 v[8:9], v[8:9], 0, v[8:9] op_sel:[0,0,1] op_sel_hi:[1,0,0]
	v_mov_b32_e32 v93, v9
	v_pk_add_f32 v[8:9], v[108:109], v[16:17]
	v_pk_add_f32 v[16:17], v[108:109], v[16:17] neg_lo:[0,1] neg_hi:[0,1]
	v_mul_f32_e32 v106, 0x3f3504f3, v17
	v_pk_fma_f32 v[16:17], v[16:17], s[96:97], v[106:107] op_sel_hi:[0,1,0] neg_lo:[0,0,1] neg_hi:[0,0,1]
	v_pk_add_f32 v[106:107], v[90:91], v[70:71]
	v_pk_add_f32 v[70:71], v[90:91], v[70:71] neg_lo:[0,1] neg_hi:[0,1]
	v_pk_mul_f32 v[90:91], v[70:71], 0 op_sel_hi:[1,0]
	v_pk_add_f32 v[108:109], v[70:71], v[90:91] op_sel:[0,1] op_sel_hi:[1,0]
	v_pk_add_f32 v[70:71], v[70:71], v[90:91] op_sel:[0,1] op_sel_hi:[1,0] neg_lo:[0,1] neg_hi:[0,1]
	v_mov_b32_e32 v109, v71
	v_pk_add_f32 v[70:71], v[82:83], v[76:77]
	v_pk_add_f32 v[76:77], v[82:83], v[76:77] neg_lo:[0,1] neg_hi:[0,1]
	v_pk_mul_f32 v[82:83], v[76:77], s[18:19] op_sel_hi:[1,0]
	v_pk_fma_f32 v[90:91], v[76:77], s[18:19], v[82:83] op_sel:[0,0,1] op_sel_hi:[1,0,0] neg_lo:[0,0,1] neg_hi:[0,0,1]
	v_pk_fma_f32 v[76:77], v[76:77], s[18:19], v[82:83] op_sel_hi:[1,0,0]
	v_mov_b32_e32 v91, v77
	v_pk_add_f32 v[76:77], v[18:19], v[98:99]
	v_pk_add_f32 v[18:19], v[18:19], v[98:99] neg_lo:[0,1] neg_hi:[0,1]
	v_pk_fma_f32 v[82:83], v[18:19], 0, v[18:19] op_sel:[0,0,1] op_sel_hi:[1,0,0] neg_lo:[0,0,1] neg_hi:[0,0,1]
	v_pk_fma_f32 v[18:19], v[18:19], 0, v[18:19] op_sel:[0,0,1] op_sel_hi:[1,0,0]
	v_mov_b32_e32 v83, v19
	v_pk_add_f32 v[18:19], v[72:73], v[100:101]
	v_pk_add_f32 v[72:73], v[72:73], v[100:101] neg_lo:[0,1] neg_hi:[0,1]
	v_mul_f32_e32 v98, 0x3f3504f3, v73
	v_pk_fma_f32 v[72:73], v[72:73], s[96:97], v[98:99] op_sel_hi:[0,1,0] neg_lo:[0,0,1] neg_hi:[0,0,1]
	v_pk_add_f32 v[98:99], v[118:119], v[84:85]
	v_pk_add_f32 v[84:85], v[118:119], v[84:85] neg_lo:[0,1] neg_hi:[0,1]
	v_pk_mul_f32 v[100:101], v[84:85], 0 op_sel_hi:[1,0]
	v_pk_add_f32 v[118:119], v[84:85], v[100:101] op_sel:[0,1] op_sel_hi:[1,0]
	v_pk_add_f32 v[84:85], v[84:85], v[100:101] op_sel:[0,1] op_sel_hi:[1,0] neg_lo:[0,1] neg_hi:[0,1]
	v_mov_b32_e32 v119, v85
	v_pk_add_f32 v[84:85], v[114:115], v[74:75]
	v_pk_add_f32 v[74:75], v[114:115], v[74:75] neg_lo:[0,1] neg_hi:[0,1]
	v_pk_mul_f32 v[100:101], v[74:75], s[18:19] op_sel_hi:[1,0]
	v_pk_fma_f32 v[114:115], v[74:75], s[18:19], v[100:101] op_sel:[0,0,1] op_sel_hi:[1,0,0] neg_lo:[0,0,1] neg_hi:[0,0,1]
	v_pk_fma_f32 v[74:75], v[74:75], s[18:19], v[100:101] op_sel_hi:[1,0,0]
	v_mov_b32_e32 v115, v75
	v_pk_add_f32 v[74:75], v[94:95], v[80:81]
	v_pk_add_f32 v[80:81], v[94:95], v[80:81] neg_lo:[0,1] neg_hi:[0,1]
	v_pk_fma_f32 v[94:95], v[80:81], 0, v[80:81] op_sel:[0,0,1] op_sel_hi:[1,0,0] neg_lo:[0,0,1] neg_hi:[0,0,1]
	v_pk_fma_f32 v[80:81], v[80:81], 0, v[80:81] op_sel:[0,0,1] op_sel_hi:[1,0,0]
	v_mov_b32_e32 v95, v81
	v_pk_add_f32 v[80:81], v[96:97], v[0:1]
	v_pk_add_f32 v[0:1], v[96:97], v[0:1] neg_lo:[0,1] neg_hi:[0,1]
	v_mul_f32_e32 v96, 0x3f3504f3, v1
	v_pk_fma_f32 v[0:1], v[0:1], s[96:97], v[96:97] op_sel_hi:[0,1,0] neg_lo:[0,0,1] neg_hi:[0,0,1]
	v_pk_add_f32 v[96:97], v[102:103], v[6:7]
	v_pk_add_f32 v[6:7], v[102:103], v[6:7] neg_lo:[0,1] neg_hi:[0,1]
	v_pk_mul_f32 v[100:101], v[6:7], 0 op_sel_hi:[1,0]
	v_pk_add_f32 v[102:103], v[6:7], v[100:101] op_sel:[0,1] op_sel_hi:[1,0]
	v_pk_add_f32 v[6:7], v[6:7], v[100:101] op_sel:[0,1] op_sel_hi:[1,0] neg_lo:[0,1] neg_hi:[0,1]
	v_mov_b32_e32 v103, v7
	v_pk_add_f32 v[6:7], v[10:11], v[4:5]
	v_pk_add_f32 v[4:5], v[10:11], v[4:5] neg_lo:[0,1] neg_hi:[0,1]
	v_pk_fma_f32 v[10:11], v[4:5], 0, v[4:5] op_sel:[0,0,1] op_sel_hi:[1,0,0] neg_lo:[0,0,1] neg_hi:[0,0,1]
	v_pk_fma_f32 v[4:5], v[4:5], 0, v[4:5] op_sel:[0,0,1] op_sel_hi:[1,0,0]
; template <int R, bool INV> DEV void dft_regs(cf (&v)[R]) {
; #pragma unroll
;     for (int s = R; s >= 2; s >>= 1) {
;         const int h = s >> 1;
; #pragma unroll
;         for (int b = 0; b < R; b += s) {
; #pragma unroll
;             for (int k = 0; k < h; ++k) {
;                 const cf a = v[b + k], c = v[b + k + h];
;                 v[b + k] = a + c;
;                 const cf d = a - c;
;                 const int m = k * (32 / s);
;                 const float wr = tw_cos(m), wi = INV ? tw_sin(m) : -tw_sin(m);
;                 v[b + k + h] = cf{d.x * wr - d.y * wi, d.x * wi + d.y * wr};
;             }
;         }
;     }
	v_mov_b32_e32 v11, v5
	v_pk_add_f32 v[4:5], v[104:105], v[14:15]
	v_pk_add_f32 v[14:15], v[104:105], v[14:15] neg_lo:[0,1] neg_hi:[0,1]
	v_pk_mul_f32 v[100:101], v[14:15], 0 op_sel_hi:[1,0]
	v_pk_add_f32 v[104:105], v[14:15], v[100:101] op_sel:[0,1] op_sel_hi:[1,0]
	v_pk_add_f32 v[14:15], v[14:15], v[100:101] op_sel:[0,1] op_sel_hi:[1,0] neg_lo:[0,1] neg_hi:[0,1]
	v_mov_b32_e32 v105, v15
	v_pk_add_f32 v[14:15], v[78:79], v[2:3]
	v_pk_add_f32 v[2:3], v[78:79], v[2:3] neg_lo:[0,1] neg_hi:[0,1]
	v_pk_fma_f32 v[78:79], v[2:3], 0, v[2:3] op_sel:[0,0,1] op_sel_hi:[1,0,0] neg_lo:[0,0,1] neg_hi:[0,0,1]
	v_pk_fma_f32 v[2:3], v[2:3], 0, v[2:3] op_sel:[0,0,1] op_sel_hi:[1,0,0]
	v_mov_b32_e32 v79, v3
	v_pk_add_f32 v[2:3], v[110:111], v[12:13]
	v_pk_add_f32 v[12:13], v[110:111], v[12:13] neg_lo:[0,1] neg_hi:[0,1]
	v_pk_mul_f32 v[100:101], v[12:13], 0 op_sel_hi:[1,0]
	v_pk_add_f32 v[110:111], v[12:13], v[100:101] op_sel:[0,1] op_sel_hi:[1,0]
	v_pk_add_f32 v[12:13], v[12:13], v[100:101] op_sel:[0,1] op_sel_hi:[1,0] neg_lo:[0,1] neg_hi:[0,1]
	v_mov_b32_e32 v111, v13
	v_pk_add_f32 v[12:13], v[68:69], v[8:9]
	v_pk_add_f32 v[8:9], v[68:69], v[8:9] neg_lo:[0,1] neg_hi:[0,1]
	v_pk_fma_f32 v[68:69], v[8:9], 0, v[8:9] op_sel:[0,0,1] op_sel_hi:[1,0,0] neg_lo:[0,0,1] neg_hi:[0,0,1]
	v_pk_fma_f32 v[8:9], v[8:9], 0, v[8:9] op_sel:[0,0,1] op_sel_hi:[1,0,0]
	v_mov_b32_e32 v69, v9
	v_pk_add_f32 v[8:9], v[116:117], v[92:93]
	v_pk_add_f32 v[92:93], v[116:117], v[92:93] neg_lo:[0,1] neg_hi:[0,1]
	v_pk_mul_f32 v[100:101], v[92:93], 0 op_sel_hi:[1,0]
	v_pk_add_f32 v[116:117], v[92:93], v[100:101] op_sel:[0,1] op_sel_hi:[1,0]
	v_pk_add_f32 v[92:93], v[92:93], v[100:101] op_sel:[0,1] op_sel_hi:[1,0] neg_lo:[0,1] neg_hi:[0,1]
	v_mov_b32_e32 v117, v93
	v_pk_add_f32 v[92:93], v[112:113], v[16:17]
	v_pk_add_f32 v[16:17], v[112:113], v[16:17] neg_lo:[0,1] neg_hi:[0,1]
	v_pk_fma_f32 v[100:101], v[16:17], 0, v[16:17] op_sel:[0,0,1] op_sel_hi:[1,0,0] neg_lo:[0,0,1] neg_hi:[0,0,1]
	v_pk_fma_f32 v[16:17], v[16:17], 0, v[16:17] op_sel:[0,0,1] op_sel_hi:[1,0,0]
	v_mov_b32_e32 v101, v17
	v_pk_add_f32 v[16:17], v[106:107], v[76:77]
	v_pk_add_f32 v[76:77], v[106:107], v[76:77] neg_lo:[0,1] neg_hi:[0,1]
	v_pk_mul_f32 v[106:107], v[76:77], 0 op_sel_hi:[1,0]
	v_pk_add_f32 v[112:113], v[76:77], v[106:107] op_sel:[0,1] op_sel_hi:[1,0]
	v_pk_add_f32 v[76:77], v[76:77], v[106:107] op_sel:[0,1] op_sel_hi:[1,0] neg_lo:[0,1] neg_hi:[0,1]
	v_mov_b32_e32 v113, v77
	v_pk_add_f32 v[76:77], v[70:71], v[18:19]
	v_pk_add_f32 v[18:19], v[70:71], v[18:19] neg_lo:[0,1] neg_hi:[0,1]
	v_pk_fma_f32 v[70:71], v[18:19], 0, v[18:19] op_sel:[0,0,1] op_sel_hi:[1,0,0] neg_lo:[0,0,1] neg_hi:[0,0,1]
	v_pk_fma_f32 v[18:19], v[18:19], 0, v[18:19] op_sel:[0,0,1] op_sel_hi:[1,0,0]
	v_mov_b32_e32 v71, v19
	v_pk_add_f32 v[18:19], v[108:109], v[82:83]
	v_pk_add_f32 v[82:83], v[108:109], v[82:83] neg_lo:[0,1] neg_hi:[0,1]
	v_pk_mul_f32 v[106:107], v[82:83], 0 op_sel_hi:[1,0]
	v_pk_add_f32 v[108:109], v[82:83], v[106:107] op_sel:[0,1] op_sel_hi:[1,0]
	v_pk_add_f32 v[82:83], v[82:83], v[106:107] op_sel:[0,1] op_sel_hi:[1,0] neg_lo:[0,1] neg_hi:[0,1]
	v_mov_b32_e32 v109, v83
	v_pk_add_f32 v[82:83], v[90:91], v[72:73]
	v_pk_add_f32 v[72:73], v[90:91], v[72:73] neg_lo:[0,1] neg_hi:[0,1]
	v_pk_fma_f32 v[90:91], v[72:73], 0, v[72:73] op_sel:[0,0,1] op_sel_hi:[1,0,0] neg_lo:[0,0,1] neg_hi:[0,0,1]
	v_pk_fma_f32 v[72:73], v[72:73], 0, v[72:73] op_sel:[0,0,1] op_sel_hi:[1,0,0]
	v_mov_b32_e32 v91, v73
	v_pk_add_f32 v[72:73], v[98:99], v[74:75]
	v_pk_add_f32 v[74:75], v[98:99], v[74:75] neg_lo:[0,1] neg_hi:[0,1]
	v_pk_mul_f32 v[98:99], v[74:75], 0 op_sel_hi:[1,0]
	v_pk_add_f32 v[106:107], v[74:75], v[98:99] op_sel:[0,1] op_sel_hi:[1,0]
	v_pk_add_f32 v[74:75], v[74:75], v[98:99] op_sel:[0,1] op_sel_hi:[1,0] neg_lo:[0,1] neg_hi:[0,1]
	v_mov_b32_e32 v107, v75
	v_pk_add_f32 v[74:75], v[84:85], v[80:81]
	v_pk_add_f32 v[80:81], v[84:85], v[80:81] neg_lo:[0,1] neg_hi:[0,1]
	v_pk_fma_f32 v[84:85], v[80:81], 0, v[80:81] op_sel:[0,0,1] op_sel_hi:[1,0,0] neg_lo:[0,0,1] neg_hi:[0,0,1]
	v_pk_fma_f32 v[80:81], v[80:81], 0, v[80:81] op_sel:[0,0,1] op_sel_hi:[1,0,0]
	v_mov_b32_e32 v85, v81
	v_pk_add_f32 v[80:81], v[118:119], v[94:95]
	v_pk_add_f32 v[94:95], v[118:119], v[94:95] neg_lo:[0,1] neg_hi:[0,1]
	v_pk_mul_f32 v[98:99], v[94:95], 0 op_sel_hi:[1,0]
	v_pk_add_f32 v[118:119], v[94:95], v[98:99] op_sel:[0,1] op_sel_hi:[1,0]
	v_pk_add_f32 v[94:95], v[94:95], v[98:99] op_sel:[0,1] op_sel_hi:[1,0] neg_lo:[0,1] neg_hi:[0,1]
	v_mov_b32_e32 v119, v95
	v_pk_add_f32 v[94:95], v[114:115], v[0:1]
	v_pk_add_f32 v[0:1], v[114:115], v[0:1] neg_lo:[0,1] neg_hi:[0,1]
	v_pk_fma_f32 v[98:99], v[0:1], 0, v[0:1] op_sel:[0,0,1] op_sel_hi:[1,0,0] neg_lo:[0,0,1] neg_hi:[0,0,1]
	v_pk_fma_f32 v[0:1], v[0:1], 0, v[0:1] op_sel:[0,0,1] op_sel_hi:[1,0,0]
	v_mov_b32_e32 v99, v1
	v_pk_add_f32 v[0:1], v[96:97], v[6:7]
	v_pk_add_f32 v[6:7], v[96:97], v[6:7] neg_lo:[0,1] neg_hi:[0,1]
	v_pk_mul_f32 v[96:97], v[6:7], 0 op_sel_hi:[1,0]
	v_pk_add_f32 v[114:115], v[6:7], v[96:97] op_sel:[0,1] op_sel_hi:[1,0]
	v_pk_add_f32 v[6:7], v[6:7], v[96:97] op_sel:[0,1] op_sel_hi:[1,0] neg_lo:[0,1] neg_hi:[0,1]
	v_mov_b32_e32 v115, v7
	v_pk_add_f32 v[6:7], v[102:103], v[10:11]
	v_pk_add_f32 v[10:11], v[102:103], v[10:11] neg_lo:[0,1] neg_hi:[0,1]
	v_pk_mul_f32 v[96:97], v[10:11], 0 op_sel_hi:[1,0]
	v_pk_add_f32 v[102:103], v[10:11], v[96:97] op_sel:[0,1] op_sel_hi:[1,0]
	v_pk_add_f32 v[10:11], v[10:11], v[96:97] op_sel:[0,1] op_sel_hi:[1,0] neg_lo:[0,1] neg_hi:[0,1]
	v_mov_b32_e32 v103, v11
	v_pk_add_f32 v[10:11], v[4:5], v[14:15]
	v_pk_add_f32 v[4:5], v[4:5], v[14:15] neg_lo:[0,1] neg_hi:[0,1]
; template <int R, bool INV> DEV void dft_regs(cf (&v)[R]) {
; #pragma unroll
;     for (int s = R; s >= 2; s >>= 1) {
;         const int h = s >> 1;
; #pragma unroll
;         for (int b = 0; b < R; b += s) {
; #pragma unroll
;             for (int k = 0; k < h; ++k) {
;                 const cf a = v[b + k], c = v[b + k + h];
;                 v[b + k] = a + c;
;                 const cf d = a - c;
;                 const int m = k * (32 / s);
;                 const float wr = tw_cos(m), wi = INV ? tw_sin(m) : -tw_sin(m);
;                 v[b + k + h] = cf{d.x * wr - d.y * wi, d.x * wi + d.y * wr};
;             }
;         }
;     }
; DEV void fft_i2(LAS cf* buf, int t8) {
;     ...
;     for (int q = 0; q < 32; ++q) pb[17 * q] = v[BR32[q]];
; }
	v_pk_mul_f32 v[14:15], v[4:5], 0 op_sel_hi:[1,0]
	v_pk_add_f32 v[96:97], v[4:5], v[14:15] op_sel:[0,1] op_sel_hi:[1,0]
	v_pk_add_f32 v[4:5], v[4:5], v[14:15] op_sel:[0,1] op_sel_hi:[1,0] neg_lo:[0,1] neg_hi:[0,1]
	v_pk_add_f32 v[14:15], v[104:105], v[78:79] neg_lo:[0,1] neg_hi:[0,1]
	v_mov_b32_e32 v97, v5
	v_pk_add_f32 v[4:5], v[104:105], v[78:79]
	v_pk_mul_f32 v[78:79], v[14:15], 0 op_sel_hi:[1,0]
	v_pk_add_f32 v[104:105], v[14:15], v[78:79] op_sel:[0,1] op_sel_hi:[1,0]
	v_pk_add_f32 v[14:15], v[14:15], v[78:79] op_sel:[0,1] op_sel_hi:[1,0] neg_lo:[0,1] neg_hi:[0,1]
	v_mov_b32_e32 v105, v15
	v_pk_add_f32 v[14:15], v[2:3], v[12:13]
	v_pk_add_f32 v[2:3], v[2:3], v[12:13] neg_lo:[0,1] neg_hi:[0,1]
	v_pk_mul_f32 v[12:13], v[2:3], 0 op_sel_hi:[1,0]
	v_pk_add_f32 v[78:79], v[2:3], v[12:13] op_sel:[0,1] op_sel_hi:[1,0]
	v_pk_add_f32 v[2:3], v[2:3], v[12:13] op_sel:[0,1] op_sel_hi:[1,0] neg_lo:[0,1] neg_hi:[0,1]
	v_pk_add_f32 v[12:13], v[110:111], v[68:69] neg_lo:[0,1] neg_hi:[0,1]
	v_mov_b32_e32 v79, v3
	v_pk_add_f32 v[2:3], v[110:111], v[68:69]
	v_pk_mul_f32 v[68:69], v[12:13], 0 op_sel_hi:[1,0]
	v_pk_add_f32 v[110:111], v[12:13], v[68:69] op_sel:[0,1] op_sel_hi:[1,0]
	v_pk_add_f32 v[12:13], v[12:13], v[68:69] op_sel:[0,1] op_sel_hi:[1,0] neg_lo:[0,1] neg_hi:[0,1]
	v_mov_b32_e32 v111, v13
	v_pk_add_f32 v[12:13], v[8:9], v[92:93]
	v_pk_add_f32 v[8:9], v[8:9], v[92:93] neg_lo:[0,1] neg_hi:[0,1]
	v_pk_mul_f32 v[68:69], v[8:9], 0 op_sel_hi:[1,0]
	v_pk_add_f32 v[92:93], v[8:9], v[68:69] op_sel:[0,1] op_sel_hi:[1,0]
	v_pk_add_f32 v[8:9], v[8:9], v[68:69] op_sel:[0,1] op_sel_hi:[1,0] neg_lo:[0,1] neg_hi:[0,1]
	v_pk_add_f32 v[68:69], v[116:117], v[100:101] neg_lo:[0,1] neg_hi:[0,1]
	v_mov_b32_e32 v93, v9
	v_pk_add_f32 v[8:9], v[116:117], v[100:101]
	v_pk_mul_f32 v[100:101], v[68:69], 0 op_sel_hi:[1,0]
	v_pk_add_f32 v[116:117], v[68:69], v[100:101] op_sel:[0,1] op_sel_hi:[1,0]
	v_pk_add_f32 v[68:69], v[68:69], v[100:101] op_sel:[0,1] op_sel_hi:[1,0] neg_lo:[0,1] neg_hi:[0,1]
	v_mov_b32_e32 v117, v69
	v_pk_add_f32 v[68:69], v[16:17], v[76:77]
	v_pk_add_f32 v[16:17], v[16:17], v[76:77] neg_lo:[0,1] neg_hi:[0,1]
	v_pk_mul_f32 v[76:77], v[16:17], 0 op_sel_hi:[1,0]
	v_pk_add_f32 v[100:101], v[16:17], v[76:77] op_sel:[0,1] op_sel_hi:[1,0]
	v_pk_add_f32 v[16:17], v[16:17], v[76:77] op_sel:[0,1] op_sel_hi:[1,0] neg_lo:[0,1] neg_hi:[0,1]
	v_mov_b32_e32 v101, v17
	v_pk_add_f32 v[16:17], v[112:113], v[70:71]
	v_pk_add_f32 v[70:71], v[112:113], v[70:71] neg_lo:[0,1] neg_hi:[0,1]
	v_pk_mul_f32 v[76:77], v[70:71], 0 op_sel_hi:[1,0]
	v_pk_add_f32 v[112:113], v[70:71], v[76:77] op_sel:[0,1] op_sel_hi:[1,0]
	v_pk_add_f32 v[70:71], v[70:71], v[76:77] op_sel:[0,1] op_sel_hi:[1,0] neg_lo:[0,1] neg_hi:[0,1]
	v_mov_b32_e32 v113, v71
	v_pk_add_f32 v[70:71], v[18:19], v[82:83]
	v_pk_add_f32 v[18:19], v[18:19], v[82:83] neg_lo:[0,1] neg_hi:[0,1]
	v_pk_mul_f32 v[76:77], v[18:19], 0 op_sel_hi:[1,0]
	v_pk_add_f32 v[82:83], v[18:19], v[76:77] op_sel:[0,1] op_sel_hi:[1,0]
	v_pk_add_f32 v[18:19], v[18:19], v[76:77] op_sel:[0,1] op_sel_hi:[1,0] neg_lo:[0,1] neg_hi:[0,1]
	v_pk_add_f32 v[76:77], v[108:109], v[90:91] neg_lo:[0,1] neg_hi:[0,1]
	v_mov_b32_e32 v83, v19
	v_pk_add_f32 v[18:19], v[108:109], v[90:91]
	v_pk_mul_f32 v[90:91], v[76:77], 0 op_sel_hi:[1,0]
	v_pk_add_f32 v[108:109], v[76:77], v[90:91] op_sel:[0,1] op_sel_hi:[1,0]
	v_pk_add_f32 v[76:77], v[76:77], v[90:91] op_sel:[0,1] op_sel_hi:[1,0] neg_lo:[0,1] neg_hi:[0,1]
	v_mov_b32_e32 v109, v77
	v_pk_add_f32 v[76:77], v[72:73], v[74:75]
	v_pk_add_f32 v[72:73], v[72:73], v[74:75] neg_lo:[0,1] neg_hi:[0,1]
	v_pk_mul_f32 v[74:75], v[72:73], 0 op_sel_hi:[1,0]
	v_pk_add_f32 v[90:91], v[72:73], v[74:75] op_sel:[0,1] op_sel_hi:[1,0]
	v_pk_add_f32 v[72:73], v[72:73], v[74:75] op_sel:[0,1] op_sel_hi:[1,0] neg_lo:[0,1] neg_hi:[0,1]
	v_pk_add_f32 v[74:75], v[106:107], v[84:85] neg_lo:[0,1] neg_hi:[0,1]
	v_mov_b32_e32 v91, v73
	v_pk_add_f32 v[72:73], v[106:107], v[84:85]
	v_pk_mul_f32 v[84:85], v[74:75], 0 op_sel_hi:[1,0]
	v_pk_add_f32 v[106:107], v[74:75], v[84:85] op_sel:[0,1] op_sel_hi:[1,0]
	v_pk_add_f32 v[74:75], v[74:75], v[84:85] op_sel:[0,1] op_sel_hi:[1,0] neg_lo:[0,1] neg_hi:[0,1]
	v_mov_b32_e32 v107, v75
	v_pk_add_f32 v[74:75], v[80:81], v[94:95]
	v_pk_add_f32 v[80:81], v[80:81], v[94:95] neg_lo:[0,1] neg_hi:[0,1]
	v_pk_mul_f32 v[84:85], v[80:81], 0 op_sel_hi:[1,0]
	v_pk_add_f32 v[94:95], v[80:81], v[84:85] op_sel:[0,1] op_sel_hi:[1,0]
	v_pk_add_f32 v[80:81], v[80:81], v[84:85] op_sel:[0,1] op_sel_hi:[1,0] neg_lo:[0,1] neg_hi:[0,1]
	v_pk_add_f32 v[84:85], v[118:119], v[98:99] neg_lo:[0,1] neg_hi:[0,1]
	v_mov_b32_e32 v95, v81
	v_pk_add_f32 v[80:81], v[118:119], v[98:99]
	v_pk_mul_f32 v[98:99], v[84:85], 0 op_sel_hi:[1,0]
	v_pk_add_f32 v[118:119], v[84:85], v[98:99] op_sel:[0,1] op_sel_hi:[1,0]
	v_pk_add_f32 v[84:85], v[84:85], v[98:99] op_sel:[0,1] op_sel_hi:[1,0] neg_lo:[0,1] neg_hi:[0,1]
	v_mov_b32_e32 v119, v85
	ds_write2_b64 v86, v[0:1], v[68:69] offset1:17
	ds_write2_b64 v86, v[14:15], v[76:77] offset0:34 offset1:51
	ds_write2_b64 v86, v[10:11], v[70:71] offset0:68 offset1:85
	ds_write2_b64 v86, v[12:13], v[74:75] offset0:102 offset1:119
	ds_write2_b64 v86, v[6:7], v[16:17] offset0:136 offset1:153
	ds_write2_b64 v86, v[2:3], v[72:73] offset0:170 offset1:187
	ds_write2_b64 v86, v[4:5], v[18:19] offset0:204 offset1:221
	ds_write2_b64 v86, v[8:9], v[80:81] offset0:238 offset1:255
	ds_write2_b64 v87, v[114:115], v[100:101] offset0:16 offset1:33
	ds_write2_b64 v87, v[78:79], v[90:91] offset0:50 offset1:67
	ds_write2_b64 v87, v[96:97], v[82:83] offset0:84 offset1:101
	ds_write2_b64 v87, v[92:93], v[94:95] offset0:118 offset1:135
	ds_write2_b64 v87, v[102:103], v[112:113] offset0:152 offset1:169
	ds_write2_b64 v87, v[110:111], v[106:107] offset0:186 offset1:203
	ds_write2_b64 v87, v[104:105], v[108:109] offset0:220 offset1:237
	ds_write2_b64 v88, v[116:117], v[118:119] offset0:126 offset1:143
	v_lshl_add_u64 v[12:13], v[56:57], 0, s[2:3]
	s_mov_b32 s2, 0x1800000
	v_add_co_u32_e32 v4, vcc, s2, v12
	s_mov_b32 s2, 0x3000000
	s_nop 0
	v_addc_co_u32_e32 v5, vcc, 0, v13, vcc
	v_add_co_u32_e32 v8, vcc, s2, v12
	s_mov_b32 s2, 0x4800000
	s_nop 0
	v_addc_co_u32_e32 v9, vcc, 0, v13, vcc
	s_waitcnt lgkmcnt(0)
	s_barrier
; #define LAS __attribute__((address_space(3)))
; #define SINCOSPI(x, s, c) do { const float hx_ = 0.5f * (x); *(s) = __builtin_amdgcn_sinf(hx_); *(c) = __builtin_amdgcn_cosf(hx_); } while (0)
; #define OPAQUE_I(x) asm volatile("" : "+v"(x))
; DEV void fft_i1x2(LAS cf* buf0, LAS cf* buf1, cf (&y0)[8], cf (&y1)[8], int tid) {
;     OPAQUE_I(tid);
;     float sn, cs; SINCOSPI(-(float)tid * (2.0f / 8192.0f), &sn, &cs);
;     const cf w = cf{cs, sn}; cf wp = cf{1.f, 0.f};
;     cf v[16], u[16];
;     const LAS cf* p0 = buf0 + PADI(tid); const LAS cf* p1 = buf1 + PADI(tid);
; #pragma unroll
;     for (int p = 0; p < 16; ++p) { v[p] = cmulc(p0[544 * p], wp); u[p] = cmulc(p1[544 * p], wp); wp = cmul(wp, w); }
; DEV void hyena_issue_rows(const bf16_t* UT, int s, int c, u32x4 (&r)[4], int tid) {
; #pragma unroll
;     for (int b = 0; b < 4; ++b) r[b] = *(const u32x4*)(UT + ((size_t)(b * 3072 + s * 1024 + c)) * 4096 + tid * 8);
; }
	global_load_dwordx4 v[0:3], v[12:13], off
	v_add_co_u32_e32 v12, vcc, s2, v12
	global_load_dwordx4 v[4:7], v[4:5], off
	s_nop 0
	v_addc_co_u32_e32 v13, vcc, 0, v13, vcc
	global_load_dwordx4 v[8:11], v[8:9], off
	v_mov_b32_e32 v16, v21
	global_load_dwordx4 v[12:15], v[12:13], off
	s_andn2_b64 vcc, exec, s[26:27]
	v_cvt_f32_i32_e32 v17, v16
	v_mul_f32_e32 v17, 0xb9800000, v17
	v_mul_f32_e32 v17, 0.5, v17
	v_sin_f32_e32 v93, v17
	v_cos_f32_e32 v92, v17
	v_ashrrev_i32_e32 v17, 4, v16
	v_add_lshl_u32 v16, v17, v16, 3
	v_add_u32_e32 v163, 0, v16
	v_add_u32_e32 v164, s33, v16
	ds_read_b64 v[166:167], v163
	ds_read_b64 v[168:169], v164
	ds_read_b64 v[170:171], v163 offset:4352
	ds_read_b64 v[172:173], v164 offset:4352
	ds_read_b64 v[174:175], v163 offset:8704
	ds_read_b64 v[176:177], v164 offset:8704
	ds_read_b64 v[178:179], v163 offset:13056
	ds_read_b64 v[180:181], v164 offset:13056
	ds_read_b64 v[182:183], v163 offset:17408
	ds_read_b64 v[184:185], v164 offset:17408
	ds_read_b64 v[186:187], v163 offset:21760
	ds_read_b64 v[188:189], v164 offset:21760
	ds_read_b64 v[190:191], v163 offset:26112
	s_waitcnt lgkmcnt(12)
	v_pk_mul_f32 v[18:19], v[166:167], v[66:67] op_sel:[1,1] op_sel_hi:[1,0]
	v_pk_fma_f32 v[76:77], v[166:167], v[66:67], v[18:19] op_sel_hi:[0,1,1] neg_hi:[1,0,0]
	ds_read_b64 v[192:193], v164 offset:26112
	s_waitcnt lgkmcnt(12)
	v_pk_mul_f32 v[18:19], v[168:169], v[66:67] op_sel:[1,1] op_sel_hi:[1,0]
	v_pk_fma_f32 v[16:17], v[168:169], v[66:67], v[18:19] op_sel_hi:[0,1,1] neg_hi:[1,0,0]
	s_nop 0
	v_pk_mul_f32 v[18:19], v[66:67], v[92:93] op_sel:[1,1] op_sel_hi:[1,0] neg_lo:[1,0]
	v_pk_fma_f32 v[66:67], v[66:67], v[92:93], v[18:19] op_sel_hi:[0,1,1]
	ds_read_b64 v[194:195], v163 offset:30464
	s_waitcnt lgkmcnt(12)
	v_pk_mul_f32 v[68:69], v[170:171], v[66:67] op_sel:[1,1] op_sel_hi:[1,0]
	v_pk_fma_f32 v[78:79], v[170:171], v[66:67], v[68:69] op_sel_hi:[0,1,1] neg_hi:[1,0,0]
	ds_read_b64 v[196:197], v164 offset:30464
	s_waitcnt lgkmcnt(12)
	v_pk_mul_f32 v[68:69], v[172:173], v[66:67] op_sel:[1,1] op_sel_hi:[1,0]
	v_pk_fma_f32 v[18:19], v[172:173], v[66:67], v[68:69] op_sel_hi:[0,1,1] neg_hi:[1,0,0]
	s_nop 0
	v_pk_mul_f32 v[68:69], v[66:67], v[92:93] op_sel:[1,1] op_sel_hi:[1,0] neg_lo:[1,0]
	v_pk_fma_f32 v[70:71], v[66:67], v[92:93], v[68:69] op_sel_hi:[0,1,1]
	ds_read_b64 v[198:199], v163 offset:34816
	s_waitcnt lgkmcnt(12)
	v_pk_mul_f32 v[68:69], v[174:175], v[70:71] op_sel:[1,1] op_sel_hi:[1,0]
	v_pk_fma_f32 v[82:83], v[174:175], v[70:71], v[68:69] op_sel_hi:[0,1,1] neg_hi:[1,0,0]
	ds_read_b64 v[200:201], v164 offset:34816
	s_waitcnt lgkmcnt(12)
	v_pk_mul_f32 v[68:69], v[176:177], v[70:71] op_sel:[1,1] op_sel_hi:[1,0]
	v_pk_fma_f32 v[66:67], v[176:177], v[70:71], v[68:69] op_sel_hi:[0,1,1] neg_hi:[1,0,0]
	s_nop 0
	v_pk_mul_f32 v[68:69], v[70:71], v[92:93] op_sel:[1,1] op_sel_hi:[1,0] neg_lo:[1,0]
	v_pk_fma_f32 v[70:71], v[70:71], v[92:93], v[68:69] op_sel_hi:[0,1,1]
	ds_read_b64 v[202:203], v163 offset:39168
	s_waitcnt lgkmcnt(12)
	v_pk_mul_f32 v[72:73], v[178:179], v[70:71] op_sel:[1,1] op_sel_hi:[1,0]
	v_pk_fma_f32 v[84:85], v[178:179], v[70:71], v[72:73] op_sel_hi:[0,1,1] neg_hi:[1,0,0]
	ds_read_b64 v[204:205], v164 offset:39168
	s_waitcnt lgkmcnt(12)
	v_pk_mul_f32 v[72:73], v[180:181], v[70:71] op_sel:[1,1] op_sel_hi:[1,0]
	v_pk_fma_f32 v[68:69], v[180:181], v[70:71], v[72:73] op_sel_hi:[0,1,1] neg_hi:[1,0,0]
	s_nop 0
	v_pk_mul_f32 v[72:73], v[70:71], v[92:93] op_sel:[1,1] op_sel_hi:[1,0] neg_lo:[1,0]
	v_pk_fma_f32 v[74:75], v[70:71], v[92:93], v[72:73] op_sel_hi:[0,1,1]
	ds_read_b64 v[208:209], v163 offset:43520
	s_waitcnt lgkmcnt(12)
	v_pk_mul_f32 v[72:73], v[182:183], v[74:75] op_sel:[1,1] op_sel_hi:[1,0]
	v_pk_fma_f32 v[86:87], v[182:183], v[74:75], v[72:73] op_sel_hi:[0,1,1] neg_hi:[1,0,0]
	ds_read_b64 v[210:211], v164 offset:43520
	s_waitcnt lgkmcnt(12)
	v_pk_mul_f32 v[72:73], v[184:185], v[74:75] op_sel:[1,1] op_sel_hi:[1,0]
	v_pk_fma_f32 v[70:71], v[184:185], v[74:75], v[72:73] op_sel_hi:[0,1,1] neg_hi:[1,0,0]
	s_nop 0
	v_pk_mul_f32 v[72:73], v[74:75], v[92:93] op_sel:[1,1] op_sel_hi:[1,0] neg_lo:[1,0]
	v_pk_fma_f32 v[74:75], v[74:75], v[92:93], v[72:73] op_sel_hi:[0,1,1]
	ds_read_b64 v[214:215], v163 offset:47872
	s_waitcnt lgkmcnt(12)
	v_pk_mul_f32 v[80:81], v[186:187], v[74:75] op_sel:[1,1] op_sel_hi:[1,0]
	v_pk_fma_f32 v[90:91], v[186:187], v[74:75], v[80:81] op_sel_hi:[0,1,1] neg_hi:[1,0,0]
	ds_read_b64 v[216:217], v164 offset:47872
	s_waitcnt lgkmcnt(12)
	v_pk_mul_f32 v[80:81], v[188:189], v[74:75] op_sel:[1,1] op_sel_hi:[1,0]
	v_pk_fma_f32 v[72:73], v[188:189], v[74:75], v[80:81] op_sel_hi:[0,1,1] neg_hi:[1,0,0]
	s_nop 0
	v_pk_mul_f32 v[80:81], v[74:75], v[92:93] op_sel:[1,1] op_sel_hi:[1,0] neg_lo:[1,0]
	v_pk_fma_f32 v[88:89], v[74:75], v[92:93], v[80:81] op_sel_hi:[0,1,1]
	ds_read_b64 v[218:219], v163 offset:52224
	s_waitcnt lgkmcnt(12)
	v_pk_mul_f32 v[80:81], v[190:191], v[88:89] op_sel:[1,1] op_sel_hi:[1,0]
	v_pk_fma_f32 v[94:95], v[190:191], v[88:89], v[80:81] op_sel_hi:[0,1,1] neg_hi:[1,0,0]
	ds_read_b64 v[220:221], v164 offset:52224
	s_waitcnt lgkmcnt(12)
	v_pk_mul_f32 v[80:81], v[192:193], v[88:89] op_sel:[1,1] op_sel_hi:[1,0]
	v_pk_fma_f32 v[74:75], v[192:193], v[88:89], v[80:81] op_sel_hi:[0,1,1] neg_hi:[1,0,0]
	s_nop 0
	v_pk_mul_f32 v[80:81], v[88:89], v[92:93] op_sel:[1,1] op_sel_hi:[1,0] neg_lo:[1,0]
	v_pk_fma_f32 v[88:89], v[88:89], v[92:93], v[80:81] op_sel_hi:[0,1,1]
	ds_read_b64 v[222:223], v163 offset:56576
	s_waitcnt lgkmcnt(12)
; #define LAS __attribute__((address_space(3)))
; #define SYNC() __syncthreads()
; #define SINCOSPI(x, s, c) do { const float hx_ = 0.5f * (x); *(s) = __builtin_amdgcn_sinf(hx_); *(c) = __builtin_amdgcn_cosf(hx_); } while (0)
; #define OPAQUE_I(x) asm volatile("" : "+v"(x))
; DEV void fft_i1x2(LAS cf* buf0, LAS cf* buf1, cf (&y0)[8], cf (&y1)[8], int tid) {
;     OPAQUE_I(tid);
;     float sn, cs; SINCOSPI(-(float)tid * (2.0f / 8192.0f), &sn, &cs);
;     const cf w = cf{cs, sn}; cf wp = cf{1.f, 0.f};
;     cf v[16], u[16];
;     const LAS cf* p0 = buf0 + PADI(tid); const LAS cf* p1 = buf1 + PADI(tid);
; #pragma unroll
;     for (int p = 0; p < 16; ++p) { v[p] = cmulc(p0[544 * p], wp); u[p] = cmulc(p1[544 * p], wp); wp = cmul(wp, w); }
; DEV void hyena_units(int c0, int cstride, const bf16_t* UT, bf16_t* YHT, const unsigned* KF, const float* convw  , const float* convb  , const float* hyb  , LAS unsigned char* lds, int tid, bool abl = false) {
;     ...
;             hyena_issue_rows(UT, 1 + o, c, r, tid);
;             if (abl && (HY_ABL == 1 || HY_ABL == 4)) {
; #pragma unroll
;                 for (int i = 0; i < 8; ++i) { y[0][i] = z[0][i]; y[1][i] = z[1][i]; }
;             } else fft_i1x2(buf0, buf1, y[0], y[1], tid);
;             SYNC();
;             hyena_commit_rows(lds, r, tid);
;             if (o == 1 && c + cstride < 1024) hyena_issue_rows(UT, 0, c + cstride, r, tid);
	v_pk_mul_f32 v[96:97], v[194:195], v[88:89] op_sel:[1,1] op_sel_hi:[1,0]
	v_pk_fma_f32 v[98:99], v[194:195], v[88:89], v[96:97] op_sel_hi:[0,1,1] neg_hi:[1,0,0]
	ds_read_b64 v[224:225], v164 offset:56576
	s_waitcnt lgkmcnt(12)
	v_pk_mul_f32 v[96:97], v[196:197], v[88:89] op_sel:[1,1] op_sel_hi:[1,0]
	v_pk_fma_f32 v[80:81], v[196:197], v[88:89], v[96:97] op_sel_hi:[0,1,1] neg_hi:[1,0,0]
	s_nop 0
	v_pk_mul_f32 v[96:97], v[88:89], v[92:93] op_sel:[1,1] op_sel_hi:[1,0] neg_lo:[1,0]
	v_pk_fma_f32 v[102:103], v[88:89], v[92:93], v[96:97] op_sel_hi:[0,1,1]
	ds_read_b64 v[226:227], v163 offset:60928
	s_waitcnt lgkmcnt(12)
	v_pk_mul_f32 v[96:97], v[198:199], v[102:103] op_sel:[1,1] op_sel_hi:[1,0]
	v_pk_fma_f32 v[100:101], v[198:199], v[102:103], v[96:97] op_sel_hi:[0,1,1] neg_hi:[1,0,0]
	ds_read_b64 v[228:229], v164 offset:60928
	s_waitcnt lgkmcnt(12)
	v_pk_mul_f32 v[96:97], v[200:201], v[102:103] op_sel:[1,1] op_sel_hi:[1,0]
	v_pk_fma_f32 v[88:89], v[200:201], v[102:103], v[96:97] op_sel_hi:[0,1,1] neg_hi:[1,0,0]
	s_nop 0
	v_pk_mul_f32 v[96:97], v[102:103], v[92:93] op_sel:[1,1] op_sel_hi:[1,0] neg_lo:[1,0]
	v_pk_fma_f32 v[102:103], v[102:103], v[92:93], v[96:97] op_sel_hi:[0,1,1]
	ds_read_b64 v[232:233], v163 offset:65280
	s_waitcnt lgkmcnt(12)
	v_pk_mul_f32 v[104:105], v[202:203], v[102:103] op_sel:[1,1] op_sel_hi:[1,0]
	v_pk_fma_f32 v[112:113], v[202:203], v[102:103], v[104:105] op_sel_hi:[0,1,1] neg_hi:[1,0,0]
	ds_read_b64 v[236:237], v164 offset:65280
	s_waitcnt lgkmcnt(12)
	v_pk_mul_f32 v[104:105], v[204:205], v[102:103] op_sel:[1,1] op_sel_hi:[1,0]
	v_pk_fma_f32 v[96:97], v[204:205], v[102:103], v[104:105] op_sel_hi:[0,1,1] neg_hi:[1,0,0]
	s_nop 0
	v_pk_mul_f32 v[104:105], v[102:103], v[92:93] op_sel:[1,1] op_sel_hi:[1,0] neg_lo:[1,0]
	v_pk_fma_f32 v[106:107], v[102:103], v[92:93], v[104:105] op_sel_hi:[0,1,1]
	s_waitcnt lgkmcnt(11)
	v_pk_mul_f32 v[104:105], v[208:209], v[106:107] op_sel:[1,1] op_sel_hi:[1,0]
	v_pk_fma_f32 v[116:117], v[208:209], v[106:107], v[104:105] op_sel_hi:[0,1,1] neg_hi:[1,0,0]
	s_waitcnt lgkmcnt(10)
	v_pk_mul_f32 v[104:105], v[210:211], v[106:107] op_sel:[1,1] op_sel_hi:[1,0]
	v_pk_fma_f32 v[102:103], v[210:211], v[106:107], v[104:105] op_sel_hi:[0,1,1] neg_hi:[1,0,0]
	s_nop 0
	v_pk_mul_f32 v[104:105], v[106:107], v[92:93] op_sel:[1,1] op_sel_hi:[1,0] neg_lo:[1,0]
	v_pk_fma_f32 v[106:107], v[106:107], v[92:93], v[104:105] op_sel_hi:[0,1,1]
	s_waitcnt lgkmcnt(9)
	v_pk_mul_f32 v[108:109], v[214:215], v[106:107] op_sel:[1,1] op_sel_hi:[1,0]
	v_pk_fma_f32 v[118:119], v[214:215], v[106:107], v[108:109] op_sel_hi:[0,1,1] neg_hi:[1,0,0]
	s_waitcnt lgkmcnt(8)
	v_pk_mul_f32 v[108:109], v[216:217], v[106:107] op_sel:[1,1] op_sel_hi:[1,0]
	v_pk_fma_f32 v[104:105], v[216:217], v[106:107], v[108:109] op_sel_hi:[0,1,1] neg_hi:[1,0,0]
	s_nop 0
	v_pk_mul_f32 v[108:109], v[106:107], v[92:93] op_sel:[1,1] op_sel_hi:[1,0] neg_lo:[1,0]
	v_pk_fma_f32 v[110:111], v[106:107], v[92:93], v[108:109] op_sel_hi:[0,1,1]
	s_waitcnt lgkmcnt(7)
	v_pk_mul_f32 v[108:109], v[218:219], v[110:111] op_sel:[1,1] op_sel_hi:[1,0]
	v_pk_fma_f32 v[120:121], v[218:219], v[110:111], v[108:109] op_sel_hi:[0,1,1] neg_hi:[1,0,0]
	s_waitcnt lgkmcnt(6)
	v_pk_mul_f32 v[108:109], v[220:221], v[110:111] op_sel:[1,1] op_sel_hi:[1,0]
	v_pk_fma_f32 v[106:107], v[220:221], v[110:111], v[108:109] op_sel_hi:[0,1,1] neg_hi:[1,0,0]
	s_nop 0
	v_pk_mul_f32 v[108:109], v[110:111], v[92:93] op_sel:[1,1] op_sel_hi:[1,0] neg_lo:[1,0]
	v_pk_fma_f32 v[110:111], v[110:111], v[92:93], v[108:109] op_sel_hi:[0,1,1]
	s_waitcnt lgkmcnt(5)
	v_pk_mul_f32 v[114:115], v[222:223], v[110:111] op_sel:[1,1] op_sel_hi:[1,0]
	v_pk_fma_f32 v[122:123], v[222:223], v[110:111], v[114:115] op_sel_hi:[0,1,1] neg_hi:[1,0,0]
	s_waitcnt lgkmcnt(4)
	v_pk_mul_f32 v[114:115], v[224:225], v[110:111] op_sel:[1,1] op_sel_hi:[1,0]
	v_pk_fma_f32 v[108:109], v[224:225], v[110:111], v[114:115] op_sel_hi:[0,1,1] neg_hi:[1,0,0]
	s_nop 0
	v_pk_mul_f32 v[114:115], v[110:111], v[92:93] op_sel:[1,1] op_sel_hi:[1,0] neg_lo:[1,0]
	v_pk_fma_f32 v[126:127], v[110:111], v[92:93], v[114:115] op_sel_hi:[0,1,1]
	s_waitcnt lgkmcnt(3)
	v_pk_mul_f32 v[114:115], v[226:227], v[126:127] op_sel:[1,1] op_sel_hi:[1,0]
	v_pk_fma_f32 v[124:125], v[226:227], v[126:127], v[114:115] op_sel_hi:[0,1,1] neg_hi:[1,0,0]
	s_waitcnt lgkmcnt(2)
	v_pk_mul_f32 v[114:115], v[228:229], v[126:127] op_sel:[1,1] op_sel_hi:[1,0]
	v_pk_fma_f32 v[110:111], v[228:229], v[126:127], v[114:115] op_sel_hi:[0,1,1] neg_hi:[1,0,0]
	s_nop 0
	v_pk_mul_f32 v[114:115], v[126:127], v[92:93] op_sel:[1,1] op_sel_hi:[1,0] neg_lo:[1,0]
	v_pk_fma_f32 v[126:127], v[126:127], v[92:93], v[114:115] op_sel_hi:[0,1,1]
	s_waitcnt lgkmcnt(1)
	v_pk_mul_f32 v[114:115], v[232:233], v[126:127] op_sel:[1,1] op_sel_hi:[1,0]
	v_pk_fma_f32 v[92:93], v[232:233], v[126:127], v[114:115] op_sel_hi:[0,1,1] neg_hi:[1,0,0]
	s_waitcnt lgkmcnt(0)
	v_pk_mul_f32 v[164:165], v[236:237], v[126:127] op_sel:[1,1] op_sel_hi:[1,0]
	v_pk_fma_f32 v[114:115], v[236:237], v[126:127], v[164:165] op_sel_hi:[0,1,1] neg_hi:[1,0,0]
	s_barrier
	s_waitcnt vmcnt(3)
	ds_write_b128 v128, v[0:3]
	s_waitcnt vmcnt(2)
	ds_write_b128 v128, v[4:7] offset:8192
	s_waitcnt vmcnt(1)
	ds_write_b128 v128, v[8:11] offset:16384
	s_waitcnt vmcnt(0)
	ds_write_b128 v128, v[12:15] offset:24576
	s_cbranch_vccnz .LBB0_518
	s_andn2_b64 vcc, exec, s[20:21]
	s_cbranch_vccnz .LBB0_518
	global_load_dwordx4 v[0:3], v[58:59], off
	global_load_dwordx4 v[4:7], v[60:61], off
	global_load_dwordx4 v[8:11], v[62:63], off
	global_load_dwordx4 v[12:15], v[64:65], off
	s_branch .LBB0_518
